# k=8 cross-chunk scans (HGRN2, retention, RG-LRU) rewritten as straight-line software pipelines: loads of chunk n+16 issued after chunk n is consumed, counted vmcnt, same f32 math
# baseline (speedup 1.0000x reference)
.LBB0_530:
	v_lshl_add_u64 v[8:9], v[2:3], 0, v[140:141]
	v_lshl_add_u64 v[10:11], v[4:5], 0, v[140:141]
	v_lshl_add_u64 v[12:13], v[0:1], 0, v[140:141]
	s_mov_b64 s[10:11], 0x1d790000
	v_lshl_add_u64 v[8:9], v[8:9], 0, s[10:11]
	s_mov_b64 s[10:11], 0x1d810000
	v_lshl_add_u64 v[10:11], v[10:11], 0, s[10:11]
	s_mov_b64 s[10:11], 0x1d890000
	v_lshl_add_u64 v[12:13], v[12:13], 0, s[10:11]
	s_nop 0
	s_mov_b64 s[10:11], 0x400
	global_load_dword v72, v[8:9], off
	global_load_dword v88, v[10:11], off
	v_lshl_add_u64 v[8:9], v[8:9], 0, s[10:11]
	v_lshl_add_u64 v[10:11], v[10:11], 0, s[10:11]
	global_load_dword v73, v[8:9], off
	global_load_dword v89, v[10:11], off
	v_lshl_add_u64 v[8:9], v[8:9], 0, s[10:11]
	v_lshl_add_u64 v[10:11], v[10:11], 0, s[10:11]
	global_load_dword v74, v[8:9], off
	global_load_dword v90, v[10:11], off
	v_lshl_add_u64 v[8:9], v[8:9], 0, s[10:11]
	v_lshl_add_u64 v[10:11], v[10:11], 0, s[10:11]
	global_load_dword v75, v[8:9], off
	global_load_dword v91, v[10:11], off
	v_lshl_add_u64 v[8:9], v[8:9], 0, s[10:11]
	v_lshl_add_u64 v[10:11], v[10:11], 0, s[10:11]
	global_load_dword v76, v[8:9], off
	global_load_dword v92, v[10:11], off
	v_lshl_add_u64 v[8:9], v[8:9], 0, s[10:11]
	v_lshl_add_u64 v[10:11], v[10:11], 0, s[10:11]
	global_load_dword v77, v[8:9], off
	global_load_dword v93, v[10:11], off
	v_lshl_add_u64 v[8:9], v[8:9], 0, s[10:11]
	v_lshl_add_u64 v[10:11], v[10:11], 0, s[10:11]
	global_load_dword v78, v[8:9], off
	global_load_dword v94, v[10:11], off
	v_lshl_add_u64 v[8:9], v[8:9], 0, s[10:11]
	v_lshl_add_u64 v[10:11], v[10:11], 0, s[10:11]
	global_load_dword v79, v[8:9], off
	global_load_dword v95, v[10:11], off
	v_lshl_add_u64 v[8:9], v[8:9], 0, s[10:11]
	v_lshl_add_u64 v[10:11], v[10:11], 0, s[10:11]
	global_load_dword v80, v[8:9], off
	global_load_dword v96, v[10:11], off
	v_lshl_add_u64 v[8:9], v[8:9], 0, s[10:11]
	v_lshl_add_u64 v[10:11], v[10:11], 0, s[10:11]
	global_load_dword v81, v[8:9], off
	global_load_dword v97, v[10:11], off
	v_lshl_add_u64 v[8:9], v[8:9], 0, s[10:11]
	v_lshl_add_u64 v[10:11], v[10:11], 0, s[10:11]
	global_load_dword v82, v[8:9], off
	global_load_dword v98, v[10:11], off
	v_lshl_add_u64 v[8:9], v[8:9], 0, s[10:11]
	v_lshl_add_u64 v[10:11], v[10:11], 0, s[10:11]
	global_load_dword v83, v[8:9], off
	global_load_dword v99, v[10:11], off
	v_lshl_add_u64 v[8:9], v[8:9], 0, s[10:11]
	v_lshl_add_u64 v[10:11], v[10:11], 0, s[10:11]
	global_load_dword v84, v[8:9], off
	global_load_dword v100, v[10:11], off
	v_lshl_add_u64 v[8:9], v[8:9], 0, s[10:11]
	v_lshl_add_u64 v[10:11], v[10:11], 0, s[10:11]
	global_load_dword v85, v[8:9], off
	global_load_dword v101, v[10:11], off
	v_lshl_add_u64 v[8:9], v[8:9], 0, s[10:11]
	v_lshl_add_u64 v[10:11], v[10:11], 0, s[10:11]
	global_load_dword v86, v[8:9], off
	global_load_dword v102, v[10:11], off
	v_lshl_add_u64 v[8:9], v[8:9], 0, s[10:11]
	v_lshl_add_u64 v[10:11], v[10:11], 0, s[10:11]
	global_load_dword v87, v[8:9], off
	global_load_dword v103, v[10:11], off
	v_lshl_add_u64 v[8:9], v[8:9], 0, s[10:11]
	v_lshl_add_u64 v[10:11], v[10:11], 0, s[10:11]
	s_waitcnt vmcnt(30)
	global_store_dword v[12:13], v6, off
	v_lshl_add_u64 v[12:13], v[12:13], 0, s[10:11]
	v_fma_f32 v6, v6, v72, v88
	global_load_dword v72, v[8:9], off
	global_load_dword v88, v[10:11], off
	v_lshl_add_u64 v[8:9], v[8:9], 0, s[10:11]
	v_lshl_add_u64 v[10:11], v[10:11], 0, s[10:11]
	s_waitcnt vmcnt(31)
	global_store_dword v[12:13], v6, off
	v_lshl_add_u64 v[12:13], v[12:13], 0, s[10:11]
	v_fma_f32 v6, v6, v73, v89
	global_load_dword v73, v[8:9], off
	global_load_dword v89, v[10:11], off
	v_lshl_add_u64 v[8:9], v[8:9], 0, s[10:11]
	v_lshl_add_u64 v[10:11], v[10:11], 0, s[10:11]
	s_waitcnt vmcnt(32)
	global_store_dword v[12:13], v6, off
	v_lshl_add_u64 v[12:13], v[12:13], 0, s[10:11]
	v_fma_f32 v6, v6, v74, v90
	global_load_dword v74, v[8:9], off
	global_load_dword v90, v[10:11], off
	v_lshl_add_u64 v[8:9], v[8:9], 0, s[10:11]
	v_lshl_add_u64 v[10:11], v[10:11], 0, s[10:11]
	s_waitcnt vmcnt(33)
	global_store_dword v[12:13], v6, off
	v_lshl_add_u64 v[12:13], v[12:13], 0, s[10:11]
	v_fma_f32 v6, v6, v75, v91
	global_load_dword v75, v[8:9], off
	global_load_dword v91, v[10:11], off
	v_lshl_add_u64 v[8:9], v[8:9], 0, s[10:11]
	v_lshl_add_u64 v[10:11], v[10:11], 0, s[10:11]
	s_waitcnt vmcnt(34)
	global_store_dword v[12:13], v6, off
	v_lshl_add_u64 v[12:13], v[12:13], 0, s[10:11]
	v_fma_f32 v6, v6, v76, v92
	global_load_dword v76, v[8:9], off
	global_load_dword v92, v[10:11], off
	v_lshl_add_u64 v[8:9], v[8:9], 0, s[10:11]
	v_lshl_add_u64 v[10:11], v[10:11], 0, s[10:11]
	s_waitcnt vmcnt(35)
	global_store_dword v[12:13], v6, off
	v_lshl_add_u64 v[12:13], v[12:13], 0, s[10:11]
	v_fma_f32 v6, v6, v77, v93
	global_load_dword v77, v[8:9], off
	global_load_dword v93, v[10:11], off
	v_lshl_add_u64 v[8:9], v[8:9], 0, s[10:11]
	v_lshl_add_u64 v[10:11], v[10:11], 0, s[10:11]
	s_waitcnt vmcnt(36)
	global_store_dword v[12:13], v6, off
	v_lshl_add_u64 v[12:13], v[12:13], 0, s[10:11]
	v_fma_f32 v6, v6, v78, v94
	global_load_dword v78, v[8:9], off
	global_load_dword v94, v[10:11], off
	v_lshl_add_u64 v[8:9], v[8:9], 0, s[10:11]
	v_lshl_add_u64 v[10:11], v[10:11], 0, s[10:11]
	s_waitcnt vmcnt(37)
	global_store_dword v[12:13], v6, off
	v_lshl_add_u64 v[12:13], v[12:13], 0, s[10:11]
	v_fma_f32 v6, v6, v79, v95
	global_load_dword v79, v[8:9], off
	global_load_dword v95, v[10:11], off
	v_lshl_add_u64 v[8:9], v[8:9], 0, s[10:11]
	v_lshl_add_u64 v[10:11], v[10:11], 0, s[10:11]
	s_waitcnt vmcnt(38)
	global_store_dword v[12:13], v6, off
	v_lshl_add_u64 v[12:13], v[12:13], 0, s[10:11]
	v_fma_f32 v6, v6, v80, v96
	global_load_dword v80, v[8:9], off
	global_load_dword v96, v[10:11], off
	v_lshl_add_u64 v[8:9], v[8:9], 0, s[10:11]
	v_lshl_add_u64 v[10:11], v[10:11], 0, s[10:11]
	s_waitcnt vmcnt(39)
	global_store_dword v[12:13], v6, off
	v_lshl_add_u64 v[12:13], v[12:13], 0, s[10:11]
	v_fma_f32 v6, v6, v81, v97
	global_load_dword v81, v[8:9], off
	global_load_dword v97, v[10:11], off
	v_lshl_add_u64 v[8:9], v[8:9], 0, s[10:11]
	v_lshl_add_u64 v[10:11], v[10:11], 0, s[10:11]
	s_waitcnt vmcnt(40)
	global_store_dword v[12:13], v6, off
	v_lshl_add_u64 v[12:13], v[12:13], 0, s[10:11]
	v_fma_f32 v6, v6, v82, v98
	global_load_dword v82, v[8:9], off
	global_load_dword v98, v[10:11], off
	v_lshl_add_u64 v[8:9], v[8:9], 0, s[10:11]
	v_lshl_add_u64 v[10:11], v[10:11], 0, s[10:11]
	s_waitcnt vmcnt(41)
	global_store_dword v[12:13], v6, off
	v_lshl_add_u64 v[12:13], v[12:13], 0, s[10:11]
	v_fma_f32 v6, v6, v83, v99
	global_load_dword v83, v[8:9], off
	global_load_dword v99, v[10:11], off
	v_lshl_add_u64 v[8:9], v[8:9], 0, s[10:11]
	v_lshl_add_u64 v[10:11], v[10:11], 0, s[10:11]
	s_waitcnt vmcnt(42)
	global_store_dword v[12:13], v6, off
	v_lshl_add_u64 v[12:13], v[12:13], 0, s[10:11]
	v_fma_f32 v6, v6, v84, v100
	global_load_dword v84, v[8:9], off
	global_load_dword v100, v[10:11], off
	v_lshl_add_u64 v[8:9], v[8:9], 0, s[10:11]
	v_lshl_add_u64 v[10:11], v[10:11], 0, s[10:11]
	s_waitcnt vmcnt(43)
	global_store_dword v[12:13], v6, off
	v_lshl_add_u64 v[12:13], v[12:13], 0, s[10:11]
	v_fma_f32 v6, v6, v85, v101
	global_load_dword v85, v[8:9], off
	global_load_dword v101, v[10:11], off
	v_lshl_add_u64 v[8:9], v[8:9], 0, s[10:11]
	v_lshl_add_u64 v[10:11], v[10:11], 0, s[10:11]
	s_waitcnt vmcnt(44)
	global_store_dword v[12:13], v6, off
	v_lshl_add_u64 v[12:13], v[12:13], 0, s[10:11]
	v_fma_f32 v6, v6, v86, v102
	global_load_dword v86, v[8:9], off
	global_load_dword v102, v[10:11], off
	v_lshl_add_u64 v[8:9], v[8:9], 0, s[10:11]
	v_lshl_add_u64 v[10:11], v[10:11], 0, s[10:11]
	s_waitcnt vmcnt(45)
	global_store_dword v[12:13], v6, off
	v_lshl_add_u64 v[12:13], v[12:13], 0, s[10:11]
	v_fma_f32 v6, v6, v87, v103
	global_load_dword v87, v[8:9], off
	global_load_dword v103, v[10:11], off
	v_lshl_add_u64 v[8:9], v[8:9], 0, s[10:11]
	v_lshl_add_u64 v[10:11], v[10:11], 0, s[10:11]
	s_waitcnt vmcnt(45)
	global_store_dword v[12:13], v6, off
	v_lshl_add_u64 v[12:13], v[12:13], 0, s[10:11]
	v_fma_f32 v6, v6, v72, v88
	global_load_dword v72, v[8:9], off
	global_load_dword v88, v[10:11], off
	v_lshl_add_u64 v[8:9], v[8:9], 0, s[10:11]
	v_lshl_add_u64 v[10:11], v[10:11], 0, s[10:11]
	s_waitcnt vmcnt(45)
	global_store_dword v[12:13], v6, off
	v_lshl_add_u64 v[12:13], v[12:13], 0, s[10:11]
	v_fma_f32 v6, v6, v73, v89
	global_load_dword v73, v[8:9], off
	global_load_dword v89, v[10:11], off
	v_lshl_add_u64 v[8:9], v[8:9], 0, s[10:11]
	v_lshl_add_u64 v[10:11], v[10:11], 0, s[10:11]
	s_waitcnt vmcnt(45)
	global_store_dword v[12:13], v6, off
	v_lshl_add_u64 v[12:13], v[12:13], 0, s[10:11]
	v_fma_f32 v6, v6, v74, v90
	global_load_dword v74, v[8:9], off
	global_load_dword v90, v[10:11], off
	v_lshl_add_u64 v[8:9], v[8:9], 0, s[10:11]
	v_lshl_add_u64 v[10:11], v[10:11], 0, s[10:11]
	s_waitcnt vmcnt(45)
	global_store_dword v[12:13], v6, off
	v_lshl_add_u64 v[12:13], v[12:13], 0, s[10:11]
	v_fma_f32 v6, v6, v75, v91
	global_load_dword v75, v[8:9], off
	global_load_dword v91, v[10:11], off
	v_lshl_add_u64 v[8:9], v[8:9], 0, s[10:11]
	v_lshl_add_u64 v[10:11], v[10:11], 0, s[10:11]
	s_waitcnt vmcnt(45)
	global_store_dword v[12:13], v6, off
	v_lshl_add_u64 v[12:13], v[12:13], 0, s[10:11]
	v_fma_f32 v6, v6, v76, v92
	global_load_dword v76, v[8:9], off
	global_load_dword v92, v[10:11], off
	v_lshl_add_u64 v[8:9], v[8:9], 0, s[10:11]
	v_lshl_add_u64 v[10:11], v[10:11], 0, s[10:11]
	s_waitcnt vmcnt(45)
	global_store_dword v[12:13], v6, off
	v_lshl_add_u64 v[12:13], v[12:13], 0, s[10:11]
	v_fma_f32 v6, v6, v77, v93
	global_load_dword v77, v[8:9], off
	global_load_dword v93, v[10:11], off
	v_lshl_add_u64 v[8:9], v[8:9], 0, s[10:11]
	v_lshl_add_u64 v[10:11], v[10:11], 0, s[10:11]
	s_waitcnt vmcnt(45)
	global_store_dword v[12:13], v6, off
	v_lshl_add_u64 v[12:13], v[12:13], 0, s[10:11]
	v_fma_f32 v6, v6, v78, v94
	global_load_dword v78, v[8:9], off
	global_load_dword v94, v[10:11], off
	v_lshl_add_u64 v[8:9], v[8:9], 0, s[10:11]
	v_lshl_add_u64 v[10:11], v[10:11], 0, s[10:11]
	s_waitcnt vmcnt(45)
	global_store_dword v[12:13], v6, off
	v_lshl_add_u64 v[12:13], v[12:13], 0, s[10:11]
	v_fma_f32 v6, v6, v79, v95
	global_load_dword v79, v[8:9], off
	global_load_dword v95, v[10:11], off
	v_lshl_add_u64 v[8:9], v[8:9], 0, s[10:11]
	v_lshl_add_u64 v[10:11], v[10:11], 0, s[10:11]
	s_waitcnt vmcnt(45)
	global_store_dword v[12:13], v6, off
	v_lshl_add_u64 v[12:13], v[12:13], 0, s[10:11]
	v_fma_f32 v6, v6, v80, v96
	global_load_dword v80, v[8:9], off
	global_load_dword v96, v[10:11], off
	v_lshl_add_u64 v[8:9], v[8:9], 0, s[10:11]
	v_lshl_add_u64 v[10:11], v[10:11], 0, s[10:11]
	s_waitcnt vmcnt(45)
	global_store_dword v[12:13], v6, off
	v_lshl_add_u64 v[12:13], v[12:13], 0, s[10:11]
	v_fma_f32 v6, v6, v81, v97
	global_load_dword v81, v[8:9], off
	global_load_dword v97, v[10:11], off
	v_lshl_add_u64 v[8:9], v[8:9], 0, s[10:11]
	v_lshl_add_u64 v[10:11], v[10:11], 0, s[10:11]
	s_waitcnt vmcnt(45)
	global_store_dword v[12:13], v6, off
	v_lshl_add_u64 v[12:13], v[12:13], 0, s[10:11]
	v_fma_f32 v6, v6, v82, v98
	global_load_dword v82, v[8:9], off
	global_load_dword v98, v[10:11], off
	v_lshl_add_u64 v[8:9], v[8:9], 0, s[10:11]
	v_lshl_add_u64 v[10:11], v[10:11], 0, s[10:11]
	s_waitcnt vmcnt(45)
	global_store_dword v[12:13], v6, off
	v_lshl_add_u64 v[12:13], v[12:13], 0, s[10:11]
	v_fma_f32 v6, v6, v83, v99
	global_load_dword v83, v[8:9], off
	global_load_dword v99, v[10:11], off
	v_lshl_add_u64 v[8:9], v[8:9], 0, s[10:11]
	v_lshl_add_u64 v[10:11], v[10:11], 0, s[10:11]
	s_waitcnt vmcnt(45)
	global_store_dword v[12:13], v6, off
	v_lshl_add_u64 v[12:13], v[12:13], 0, s[10:11]
	v_fma_f32 v6, v6, v84, v100
	global_load_dword v84, v[8:9], off
	global_load_dword v100, v[10:11], off
	v_lshl_add_u64 v[8:9], v[8:9], 0, s[10:11]
	v_lshl_add_u64 v[10:11], v[10:11], 0, s[10:11]
	s_waitcnt vmcnt(45)
	global_store_dword v[12:13], v6, off
	v_lshl_add_u64 v[12:13], v[12:13], 0, s[10:11]
	v_fma_f32 v6, v6, v85, v101
	global_load_dword v85, v[8:9], off
	global_load_dword v101, v[10:11], off
	v_lshl_add_u64 v[8:9], v[8:9], 0, s[10:11]
	v_lshl_add_u64 v[10:11], v[10:11], 0, s[10:11]
	s_waitcnt vmcnt(45)
	global_store_dword v[12:13], v6, off
	v_lshl_add_u64 v[12:13], v[12:13], 0, s[10:11]
	v_fma_f32 v6, v6, v86, v102
	global_load_dword v86, v[8:9], off
	global_load_dword v102, v[10:11], off
	v_lshl_add_u64 v[8:9], v[8:9], 0, s[10:11]
	v_lshl_add_u64 v[10:11], v[10:11], 0, s[10:11]
	s_waitcnt vmcnt(45)
	global_store_dword v[12:13], v6, off
	v_lshl_add_u64 v[12:13], v[12:13], 0, s[10:11]
	v_fma_f32 v6, v6, v87, v103
	global_load_dword v87, v[8:9], off
	global_load_dword v103, v[10:11], off
	v_lshl_add_u64 v[8:9], v[8:9], 0, s[10:11]
	v_lshl_add_u64 v[10:11], v[10:11], 0, s[10:11]
	s_waitcnt vmcnt(45)
	global_store_dword v[12:13], v6, off
	v_lshl_add_u64 v[12:13], v[12:13], 0, s[10:11]
	v_fma_f32 v6, v6, v72, v88
	global_load_dword v72, v[8:9], off
	global_load_dword v88, v[10:11], off
	v_lshl_add_u64 v[8:9], v[8:9], 0, s[10:11]
	v_lshl_add_u64 v[10:11], v[10:11], 0, s[10:11]
	s_waitcnt vmcnt(45)
	global_store_dword v[12:13], v6, off
	v_lshl_add_u64 v[12:13], v[12:13], 0, s[10:11]
	v_fma_f32 v6, v6, v73, v89
	global_load_dword v73, v[8:9], off
	global_load_dword v89, v[10:11], off
	v_lshl_add_u64 v[8:9], v[8:9], 0, s[10:11]
	v_lshl_add_u64 v[10:11], v[10:11], 0, s[10:11]
	s_waitcnt vmcnt(45)
	global_store_dword v[12:13], v6, off
	v_lshl_add_u64 v[12:13], v[12:13], 0, s[10:11]
	v_fma_f32 v6, v6, v74, v90
	global_load_dword v74, v[8:9], off
	global_load_dword v90, v[10:11], off
	v_lshl_add_u64 v[8:9], v[8:9], 0, s[10:11]
	v_lshl_add_u64 v[10:11], v[10:11], 0, s[10:11]
	s_waitcnt vmcnt(45)
	global_store_dword v[12:13], v6, off
	v_lshl_add_u64 v[12:13], v[12:13], 0, s[10:11]
	v_fma_f32 v6, v6, v75, v91
	global_load_dword v75, v[8:9], off
	global_load_dword v91, v[10:11], off
	v_lshl_add_u64 v[8:9], v[8:9], 0, s[10:11]
	v_lshl_add_u64 v[10:11], v[10:11], 0, s[10:11]
	s_waitcnt vmcnt(45)
	global_store_dword v[12:13], v6, off
	v_lshl_add_u64 v[12:13], v[12:13], 0, s[10:11]
	v_fma_f32 v6, v6, v76, v92
	global_load_dword v76, v[8:9], off
	global_load_dword v92, v[10:11], off
	v_lshl_add_u64 v[8:9], v[8:9], 0, s[10:11]
	v_lshl_add_u64 v[10:11], v[10:11], 0, s[10:11]
	s_waitcnt vmcnt(45)
	global_store_dword v[12:13], v6, off
	v_lshl_add_u64 v[12:13], v[12:13], 0, s[10:11]
	v_fma_f32 v6, v6, v77, v93
	global_load_dword v77, v[8:9], off
	global_load_dword v93, v[10:11], off
	v_lshl_add_u64 v[8:9], v[8:9], 0, s[10:11]
	v_lshl_add_u64 v[10:11], v[10:11], 0, s[10:11]
	s_waitcnt vmcnt(45)
	global_store_dword v[12:13], v6, off
	v_lshl_add_u64 v[12:13], v[12:13], 0, s[10:11]
	v_fma_f32 v6, v6, v78, v94
	global_load_dword v78, v[8:9], off
	global_load_dword v94, v[10:11], off
	v_lshl_add_u64 v[8:9], v[8:9], 0, s[10:11]
	v_lshl_add_u64 v[10:11], v[10:11], 0, s[10:11]
	s_waitcnt vmcnt(45)
	global_store_dword v[12:13], v6, off
	v_lshl_add_u64 v[12:13], v[12:13], 0, s[10:11]
	v_fma_f32 v6, v6, v79, v95
	global_load_dword v79, v[8:9], off
	global_load_dword v95, v[10:11], off
	v_lshl_add_u64 v[8:9], v[8:9], 0, s[10:11]
	v_lshl_add_u64 v[10:11], v[10:11], 0, s[10:11]
	s_waitcnt vmcnt(45)
	global_store_dword v[12:13], v6, off
	v_lshl_add_u64 v[12:13], v[12:13], 0, s[10:11]
	v_fma_f32 v6, v6, v80, v96
	global_load_dword v80, v[8:9], off
	global_load_dword v96, v[10:11], off
	v_lshl_add_u64 v[8:9], v[8:9], 0, s[10:11]
	v_lshl_add_u64 v[10:11], v[10:11], 0, s[10:11]
	s_waitcnt vmcnt(45)
	global_store_dword v[12:13], v6, off
	v_lshl_add_u64 v[12:13], v[12:13], 0, s[10:11]
	v_fma_f32 v6, v6, v81, v97
	global_load_dword v81, v[8:9], off
	global_load_dword v97, v[10:11], off
	v_lshl_add_u64 v[8:9], v[8:9], 0, s[10:11]
	v_lshl_add_u64 v[10:11], v[10:11], 0, s[10:11]
	s_waitcnt vmcnt(45)
	global_store_dword v[12:13], v6, off
	v_lshl_add_u64 v[12:13], v[12:13], 0, s[10:11]
	v_fma_f32 v6, v6, v82, v98
	global_load_dword v82, v[8:9], off
	global_load_dword v98, v[10:11], off
	v_lshl_add_u64 v[8:9], v[8:9], 0, s[10:11]
	v_lshl_add_u64 v[10:11], v[10:11], 0, s[10:11]
	s_waitcnt vmcnt(45)
	global_store_dword v[12:13], v6, off
	v_lshl_add_u64 v[12:13], v[12:13], 0, s[10:11]
	v_fma_f32 v6, v6, v83, v99
	global_load_dword v83, v[8:9], off
	global_load_dword v99, v[10:11], off
	v_lshl_add_u64 v[8:9], v[8:9], 0, s[10:11]
	v_lshl_add_u64 v[10:11], v[10:11], 0, s[10:11]
	s_waitcnt vmcnt(45)
	global_store_dword v[12:13], v6, off
	v_lshl_add_u64 v[12:13], v[12:13], 0, s[10:11]
	v_fma_f32 v6, v6, v84, v100
	global_load_dword v84, v[8:9], off
	global_load_dword v100, v[10:11], off
	v_lshl_add_u64 v[8:9], v[8:9], 0, s[10:11]
	v_lshl_add_u64 v[10:11], v[10:11], 0, s[10:11]
	s_waitcnt vmcnt(45)
	global_store_dword v[12:13], v6, off
	v_lshl_add_u64 v[12:13], v[12:13], 0, s[10:11]
	v_fma_f32 v6, v6, v85, v101
	global_load_dword v85, v[8:9], off
	global_load_dword v101, v[10:11], off
	v_lshl_add_u64 v[8:9], v[8:9], 0, s[10:11]
	v_lshl_add_u64 v[10:11], v[10:11], 0, s[10:11]
	s_waitcnt vmcnt(45)
	global_store_dword v[12:13], v6, off
	v_lshl_add_u64 v[12:13], v[12:13], 0, s[10:11]
	v_fma_f32 v6, v6, v86, v102
	global_load_dword v86, v[8:9], off
	global_load_dword v102, v[10:11], off
	v_lshl_add_u64 v[8:9], v[8:9], 0, s[10:11]
	v_lshl_add_u64 v[10:11], v[10:11], 0, s[10:11]
	s_waitcnt vmcnt(45)
	global_store_dword v[12:13], v6, off
	v_lshl_add_u64 v[12:13], v[12:13], 0, s[10:11]
	v_fma_f32 v6, v6, v87, v103
	global_load_dword v87, v[8:9], off
	global_load_dword v103, v[10:11], off
	v_lshl_add_u64 v[8:9], v[8:9], 0, s[10:11]
	v_lshl_add_u64 v[10:11], v[10:11], 0, s[10:11]
	s_waitcnt vmcnt(45)
	global_store_dword v[12:13], v6, off
	v_lshl_add_u64 v[12:13], v[12:13], 0, s[10:11]
	v_fma_f32 v6, v6, v72, v88
	global_load_dword v72, v[8:9], off
	global_load_dword v88, v[10:11], off
	v_lshl_add_u64 v[8:9], v[8:9], 0, s[10:11]
	v_lshl_add_u64 v[10:11], v[10:11], 0, s[10:11]
	s_waitcnt vmcnt(45)
	global_store_dword v[12:13], v6, off
	v_lshl_add_u64 v[12:13], v[12:13], 0, s[10:11]
	v_fma_f32 v6, v6, v73, v89
	global_load_dword v73, v[8:9], off
	global_load_dword v89, v[10:11], off
	v_lshl_add_u64 v[8:9], v[8:9], 0, s[10:11]
	v_lshl_add_u64 v[10:11], v[10:11], 0, s[10:11]
	s_waitcnt vmcnt(45)
	global_store_dword v[12:13], v6, off
	v_lshl_add_u64 v[12:13], v[12:13], 0, s[10:11]
	v_fma_f32 v6, v6, v74, v90
	global_load_dword v74, v[8:9], off
	global_load_dword v90, v[10:11], off
	v_lshl_add_u64 v[8:9], v[8:9], 0, s[10:11]
	v_lshl_add_u64 v[10:11], v[10:11], 0, s[10:11]
	s_waitcnt vmcnt(45)
	global_store_dword v[12:13], v6, off
	v_lshl_add_u64 v[12:13], v[12:13], 0, s[10:11]
	v_fma_f32 v6, v6, v75, v91
	global_load_dword v75, v[8:9], off
	global_load_dword v91, v[10:11], off
	v_lshl_add_u64 v[8:9], v[8:9], 0, s[10:11]
	v_lshl_add_u64 v[10:11], v[10:11], 0, s[10:11]
	s_waitcnt vmcnt(45)
	global_store_dword v[12:13], v6, off
	v_lshl_add_u64 v[12:13], v[12:13], 0, s[10:11]
	v_fma_f32 v6, v6, v76, v92
	global_load_dword v76, v[8:9], off
	global_load_dword v92, v[10:11], off
	v_lshl_add_u64 v[8:9], v[8:9], 0, s[10:11]
	v_lshl_add_u64 v[10:11], v[10:11], 0, s[10:11]
	s_waitcnt vmcnt(45)
	global_store_dword v[12:13], v6, off
	v_lshl_add_u64 v[12:13], v[12:13], 0, s[10:11]
	v_fma_f32 v6, v6, v77, v93
	global_load_dword v77, v[8:9], off
	global_load_dword v93, v[10:11], off
	v_lshl_add_u64 v[8:9], v[8:9], 0, s[10:11]
	v_lshl_add_u64 v[10:11], v[10:11], 0, s[10:11]
	s_waitcnt vmcnt(45)
	global_store_dword v[12:13], v6, off
	v_lshl_add_u64 v[12:13], v[12:13], 0, s[10:11]
	v_fma_f32 v6, v6, v78, v94
	global_load_dword v78, v[8:9], off
	global_load_dword v94, v[10:11], off
	v_lshl_add_u64 v[8:9], v[8:9], 0, s[10:11]
	v_lshl_add_u64 v[10:11], v[10:11], 0, s[10:11]
	s_waitcnt vmcnt(45)
	global_store_dword v[12:13], v6, off
	v_lshl_add_u64 v[12:13], v[12:13], 0, s[10:11]
	v_fma_f32 v6, v6, v79, v95
	global_load_dword v79, v[8:9], off
	global_load_dword v95, v[10:11], off
	v_lshl_add_u64 v[8:9], v[8:9], 0, s[10:11]
	v_lshl_add_u64 v[10:11], v[10:11], 0, s[10:11]
	s_waitcnt vmcnt(45)
	global_store_dword v[12:13], v6, off
	v_lshl_add_u64 v[12:13], v[12:13], 0, s[10:11]
	v_fma_f32 v6, v6, v80, v96
	global_load_dword v80, v[8:9], off
	global_load_dword v96, v[10:11], off
	v_lshl_add_u64 v[8:9], v[8:9], 0, s[10:11]
	v_lshl_add_u64 v[10:11], v[10:11], 0, s[10:11]
	s_waitcnt vmcnt(45)
	global_store_dword v[12:13], v6, off
	v_lshl_add_u64 v[12:13], v[12:13], 0, s[10:11]
	v_fma_f32 v6, v6, v81, v97
	global_load_dword v81, v[8:9], off
	global_load_dword v97, v[10:11], off
	v_lshl_add_u64 v[8:9], v[8:9], 0, s[10:11]
	v_lshl_add_u64 v[10:11], v[10:11], 0, s[10:11]
	s_waitcnt vmcnt(45)
	global_store_dword v[12:13], v6, off
	v_lshl_add_u64 v[12:13], v[12:13], 0, s[10:11]
	v_fma_f32 v6, v6, v82, v98
	global_load_dword v82, v[8:9], off
	global_load_dword v98, v[10:11], off
	v_lshl_add_u64 v[8:9], v[8:9], 0, s[10:11]
	v_lshl_add_u64 v[10:11], v[10:11], 0, s[10:11]
	s_waitcnt vmcnt(45)
	global_store_dword v[12:13], v6, off
	v_lshl_add_u64 v[12:13], v[12:13], 0, s[10:11]
	v_fma_f32 v6, v6, v83, v99
	global_load_dword v83, v[8:9], off
	global_load_dword v99, v[10:11], off
	v_lshl_add_u64 v[8:9], v[8:9], 0, s[10:11]
	v_lshl_add_u64 v[10:11], v[10:11], 0, s[10:11]
	s_waitcnt vmcnt(45)
	global_store_dword v[12:13], v6, off
	v_lshl_add_u64 v[12:13], v[12:13], 0, s[10:11]
	v_fma_f32 v6, v6, v84, v100
	global_load_dword v84, v[8:9], off
	global_load_dword v100, v[10:11], off
	v_lshl_add_u64 v[8:9], v[8:9], 0, s[10:11]
	v_lshl_add_u64 v[10:11], v[10:11], 0, s[10:11]
	s_waitcnt vmcnt(45)
	global_store_dword v[12:13], v6, off
	v_lshl_add_u64 v[12:13], v[12:13], 0, s[10:11]
	v_fma_f32 v6, v6, v85, v101
	global_load_dword v85, v[8:9], off
	global_load_dword v101, v[10:11], off
	v_lshl_add_u64 v[8:9], v[8:9], 0, s[10:11]
	v_lshl_add_u64 v[10:11], v[10:11], 0, s[10:11]
	s_waitcnt vmcnt(45)
	global_store_dword v[12:13], v6, off
	v_lshl_add_u64 v[12:13], v[12:13], 0, s[10:11]
	v_fma_f32 v6, v6, v86, v102
	global_load_dword v86, v[8:9], off
	global_load_dword v102, v[10:11], off
	v_lshl_add_u64 v[8:9], v[8:9], 0, s[10:11]
	v_lshl_add_u64 v[10:11], v[10:11], 0, s[10:11]
	s_waitcnt vmcnt(45)
	global_store_dword v[12:13], v6, off
	v_lshl_add_u64 v[12:13], v[12:13], 0, s[10:11]
	v_fma_f32 v6, v6, v87, v103
	global_load_dword v87, v[8:9], off
	global_load_dword v103, v[10:11], off
	v_lshl_add_u64 v[8:9], v[8:9], 0, s[10:11]
	v_lshl_add_u64 v[10:11], v[10:11], 0, s[10:11]
	s_waitcnt vmcnt(45)
	global_store_dword v[12:13], v6, off
	v_lshl_add_u64 v[12:13], v[12:13], 0, s[10:11]
	v_fma_f32 v6, v6, v72, v88
	global_load_dword v72, v[8:9], off
	global_load_dword v88, v[10:11], off
	v_lshl_add_u64 v[8:9], v[8:9], 0, s[10:11]
	v_lshl_add_u64 v[10:11], v[10:11], 0, s[10:11]
	s_waitcnt vmcnt(45)
	global_store_dword v[12:13], v6, off
	v_lshl_add_u64 v[12:13], v[12:13], 0, s[10:11]
	v_fma_f32 v6, v6, v73, v89
	global_load_dword v73, v[8:9], off
	global_load_dword v89, v[10:11], off
	v_lshl_add_u64 v[8:9], v[8:9], 0, s[10:11]
	v_lshl_add_u64 v[10:11], v[10:11], 0, s[10:11]
	s_waitcnt vmcnt(45)
	global_store_dword v[12:13], v6, off
	v_lshl_add_u64 v[12:13], v[12:13], 0, s[10:11]
	v_fma_f32 v6, v6, v74, v90
	global_load_dword v74, v[8:9], off
	global_load_dword v90, v[10:11], off
	v_lshl_add_u64 v[8:9], v[8:9], 0, s[10:11]
	v_lshl_add_u64 v[10:11], v[10:11], 0, s[10:11]
	s_waitcnt vmcnt(45)
	global_store_dword v[12:13], v6, off
	v_lshl_add_u64 v[12:13], v[12:13], 0, s[10:11]
	v_fma_f32 v6, v6, v75, v91
	global_load_dword v75, v[8:9], off
	global_load_dword v91, v[10:11], off
	v_lshl_add_u64 v[8:9], v[8:9], 0, s[10:11]
	v_lshl_add_u64 v[10:11], v[10:11], 0, s[10:11]
	s_waitcnt vmcnt(45)
	global_store_dword v[12:13], v6, off
	v_lshl_add_u64 v[12:13], v[12:13], 0, s[10:11]
	v_fma_f32 v6, v6, v76, v92
	global_load_dword v76, v[8:9], off
	global_load_dword v92, v[10:11], off
	v_lshl_add_u64 v[8:9], v[8:9], 0, s[10:11]
	v_lshl_add_u64 v[10:11], v[10:11], 0, s[10:11]
	s_waitcnt vmcnt(45)
	global_store_dword v[12:13], v6, off
	v_lshl_add_u64 v[12:13], v[12:13], 0, s[10:11]
	v_fma_f32 v6, v6, v77, v93
	global_load_dword v77, v[8:9], off
	global_load_dword v93, v[10:11], off
	v_lshl_add_u64 v[8:9], v[8:9], 0, s[10:11]
	v_lshl_add_u64 v[10:11], v[10:11], 0, s[10:11]
	s_waitcnt vmcnt(45)
	global_store_dword v[12:13], v6, off
	v_lshl_add_u64 v[12:13], v[12:13], 0, s[10:11]
	v_fma_f32 v6, v6, v78, v94
	global_load_dword v78, v[8:9], off
	global_load_dword v94, v[10:11], off
	v_lshl_add_u64 v[8:9], v[8:9], 0, s[10:11]
	v_lshl_add_u64 v[10:11], v[10:11], 0, s[10:11]
	s_waitcnt vmcnt(45)
	global_store_dword v[12:13], v6, off
	v_lshl_add_u64 v[12:13], v[12:13], 0, s[10:11]
	v_fma_f32 v6, v6, v79, v95
	global_load_dword v79, v[8:9], off
	global_load_dword v95, v[10:11], off
	v_lshl_add_u64 v[8:9], v[8:9], 0, s[10:11]
	v_lshl_add_u64 v[10:11], v[10:11], 0, s[10:11]
	s_waitcnt vmcnt(45)
	global_store_dword v[12:13], v6, off
	v_lshl_add_u64 v[12:13], v[12:13], 0, s[10:11]
	v_fma_f32 v6, v6, v80, v96
	global_load_dword v80, v[8:9], off
	global_load_dword v96, v[10:11], off
	v_lshl_add_u64 v[8:9], v[8:9], 0, s[10:11]
	v_lshl_add_u64 v[10:11], v[10:11], 0, s[10:11]
	s_waitcnt vmcnt(45)
	global_store_dword v[12:13], v6, off
	v_lshl_add_u64 v[12:13], v[12:13], 0, s[10:11]
	v_fma_f32 v6, v6, v81, v97
	global_load_dword v81, v[8:9], off
	global_load_dword v97, v[10:11], off
	v_lshl_add_u64 v[8:9], v[8:9], 0, s[10:11]
	v_lshl_add_u64 v[10:11], v[10:11], 0, s[10:11]
	s_waitcnt vmcnt(45)
	global_store_dword v[12:13], v6, off
	v_lshl_add_u64 v[12:13], v[12:13], 0, s[10:11]
	v_fma_f32 v6, v6, v82, v98
	global_load_dword v82, v[8:9], off
	global_load_dword v98, v[10:11], off
	v_lshl_add_u64 v[8:9], v[8:9], 0, s[10:11]
	v_lshl_add_u64 v[10:11], v[10:11], 0, s[10:11]
	s_waitcnt vmcnt(45)
	global_store_dword v[12:13], v6, off
	v_lshl_add_u64 v[12:13], v[12:13], 0, s[10:11]
	v_fma_f32 v6, v6, v83, v99
	global_load_dword v83, v[8:9], off
	global_load_dword v99, v[10:11], off
	v_lshl_add_u64 v[8:9], v[8:9], 0, s[10:11]
	v_lshl_add_u64 v[10:11], v[10:11], 0, s[10:11]
	s_waitcnt vmcnt(45)
	global_store_dword v[12:13], v6, off
	v_lshl_add_u64 v[12:13], v[12:13], 0, s[10:11]
	v_fma_f32 v6, v6, v84, v100
	global_load_dword v84, v[8:9], off
	global_load_dword v100, v[10:11], off
	v_lshl_add_u64 v[8:9], v[8:9], 0, s[10:11]
	v_lshl_add_u64 v[10:11], v[10:11], 0, s[10:11]
	s_waitcnt vmcnt(45)
	global_store_dword v[12:13], v6, off
	v_lshl_add_u64 v[12:13], v[12:13], 0, s[10:11]
	v_fma_f32 v6, v6, v85, v101
	global_load_dword v85, v[8:9], off
	global_load_dword v101, v[10:11], off
	v_lshl_add_u64 v[8:9], v[8:9], 0, s[10:11]
	v_lshl_add_u64 v[10:11], v[10:11], 0, s[10:11]
	s_waitcnt vmcnt(45)
	global_store_dword v[12:13], v6, off
	v_lshl_add_u64 v[12:13], v[12:13], 0, s[10:11]
	v_fma_f32 v6, v6, v86, v102
	global_load_dword v86, v[8:9], off
	global_load_dword v102, v[10:11], off
	v_lshl_add_u64 v[8:9], v[8:9], 0, s[10:11]
	v_lshl_add_u64 v[10:11], v[10:11], 0, s[10:11]
	s_waitcnt vmcnt(45)
	global_store_dword v[12:13], v6, off
	v_lshl_add_u64 v[12:13], v[12:13], 0, s[10:11]
	v_fma_f32 v6, v6, v87, v103
	global_load_dword v87, v[8:9], off
	global_load_dword v103, v[10:11], off
	v_lshl_add_u64 v[8:9], v[8:9], 0, s[10:11]
	v_lshl_add_u64 v[10:11], v[10:11], 0, s[10:11]
	s_waitcnt vmcnt(45)
	global_store_dword v[12:13], v6, off
	v_lshl_add_u64 v[12:13], v[12:13], 0, s[10:11]
	v_fma_f32 v6, v6, v72, v88
	global_load_dword v72, v[8:9], off
	global_load_dword v88, v[10:11], off
	v_lshl_add_u64 v[8:9], v[8:9], 0, s[10:11]
	v_lshl_add_u64 v[10:11], v[10:11], 0, s[10:11]
	s_waitcnt vmcnt(45)
	global_store_dword v[12:13], v6, off
	v_lshl_add_u64 v[12:13], v[12:13], 0, s[10:11]
	v_fma_f32 v6, v6, v73, v89
	global_load_dword v73, v[8:9], off
	global_load_dword v89, v[10:11], off
	v_lshl_add_u64 v[8:9], v[8:9], 0, s[10:11]
	v_lshl_add_u64 v[10:11], v[10:11], 0, s[10:11]
	s_waitcnt vmcnt(45)
	global_store_dword v[12:13], v6, off
	v_lshl_add_u64 v[12:13], v[12:13], 0, s[10:11]
	v_fma_f32 v6, v6, v74, v90
	global_load_dword v74, v[8:9], off
	global_load_dword v90, v[10:11], off
	v_lshl_add_u64 v[8:9], v[8:9], 0, s[10:11]
	v_lshl_add_u64 v[10:11], v[10:11], 0, s[10:11]
	s_waitcnt vmcnt(45)
	global_store_dword v[12:13], v6, off
	v_lshl_add_u64 v[12:13], v[12:13], 0, s[10:11]
	v_fma_f32 v6, v6, v75, v91
	global_load_dword v75, v[8:9], off
	global_load_dword v91, v[10:11], off
	v_lshl_add_u64 v[8:9], v[8:9], 0, s[10:11]
	v_lshl_add_u64 v[10:11], v[10:11], 0, s[10:11]
	s_waitcnt vmcnt(45)
	global_store_dword v[12:13], v6, off
	v_lshl_add_u64 v[12:13], v[12:13], 0, s[10:11]
	v_fma_f32 v6, v6, v76, v92
	global_load_dword v76, v[8:9], off
	global_load_dword v92, v[10:11], off
	v_lshl_add_u64 v[8:9], v[8:9], 0, s[10:11]
	v_lshl_add_u64 v[10:11], v[10:11], 0, s[10:11]
	s_waitcnt vmcnt(45)
	global_store_dword v[12:13], v6, off
	v_lshl_add_u64 v[12:13], v[12:13], 0, s[10:11]
	v_fma_f32 v6, v6, v77, v93
	global_load_dword v77, v[8:9], off
	global_load_dword v93, v[10:11], off
	v_lshl_add_u64 v[8:9], v[8:9], 0, s[10:11]
	v_lshl_add_u64 v[10:11], v[10:11], 0, s[10:11]
	s_waitcnt vmcnt(45)
	global_store_dword v[12:13], v6, off
	v_lshl_add_u64 v[12:13], v[12:13], 0, s[10:11]
	v_fma_f32 v6, v6, v78, v94
	global_load_dword v78, v[8:9], off
	global_load_dword v94, v[10:11], off
	v_lshl_add_u64 v[8:9], v[8:9], 0, s[10:11]
	v_lshl_add_u64 v[10:11], v[10:11], 0, s[10:11]
	s_waitcnt vmcnt(45)
	global_store_dword v[12:13], v6, off
	v_lshl_add_u64 v[12:13], v[12:13], 0, s[10:11]
	v_fma_f32 v6, v6, v79, v95
	global_load_dword v79, v[8:9], off
	global_load_dword v95, v[10:11], off
	v_lshl_add_u64 v[8:9], v[8:9], 0, s[10:11]
	v_lshl_add_u64 v[10:11], v[10:11], 0, s[10:11]
	s_waitcnt vmcnt(45)
	global_store_dword v[12:13], v6, off
	v_lshl_add_u64 v[12:13], v[12:13], 0, s[10:11]
	v_fma_f32 v6, v6, v80, v96
	global_load_dword v80, v[8:9], off
	global_load_dword v96, v[10:11], off
	v_lshl_add_u64 v[8:9], v[8:9], 0, s[10:11]
	v_lshl_add_u64 v[10:11], v[10:11], 0, s[10:11]
	s_waitcnt vmcnt(45)
	global_store_dword v[12:13], v6, off
	v_lshl_add_u64 v[12:13], v[12:13], 0, s[10:11]
	v_fma_f32 v6, v6, v81, v97
	global_load_dword v81, v[8:9], off
	global_load_dword v97, v[10:11], off
	v_lshl_add_u64 v[8:9], v[8:9], 0, s[10:11]
	v_lshl_add_u64 v[10:11], v[10:11], 0, s[10:11]
	s_waitcnt vmcnt(45)
	global_store_dword v[12:13], v6, off
	v_lshl_add_u64 v[12:13], v[12:13], 0, s[10:11]
	v_fma_f32 v6, v6, v82, v98
	global_load_dword v82, v[8:9], off
	global_load_dword v98, v[10:11], off
	v_lshl_add_u64 v[8:9], v[8:9], 0, s[10:11]
	v_lshl_add_u64 v[10:11], v[10:11], 0, s[10:11]
	s_waitcnt vmcnt(45)
	global_store_dword v[12:13], v6, off
	v_lshl_add_u64 v[12:13], v[12:13], 0, s[10:11]
	v_fma_f32 v6, v6, v83, v99
	global_load_dword v83, v[8:9], off
	global_load_dword v99, v[10:11], off
	v_lshl_add_u64 v[8:9], v[8:9], 0, s[10:11]
	v_lshl_add_u64 v[10:11], v[10:11], 0, s[10:11]
	s_waitcnt vmcnt(45)
	global_store_dword v[12:13], v6, off
	v_lshl_add_u64 v[12:13], v[12:13], 0, s[10:11]
	v_fma_f32 v6, v6, v84, v100
	global_load_dword v84, v[8:9], off
	global_load_dword v100, v[10:11], off
	v_lshl_add_u64 v[8:9], v[8:9], 0, s[10:11]
	v_lshl_add_u64 v[10:11], v[10:11], 0, s[10:11]
	s_waitcnt vmcnt(45)
	global_store_dword v[12:13], v6, off
	v_lshl_add_u64 v[12:13], v[12:13], 0, s[10:11]
	v_fma_f32 v6, v6, v85, v101
	global_load_dword v85, v[8:9], off
	global_load_dword v101, v[10:11], off
	v_lshl_add_u64 v[8:9], v[8:9], 0, s[10:11]
	v_lshl_add_u64 v[10:11], v[10:11], 0, s[10:11]
	s_waitcnt vmcnt(45)
	global_store_dword v[12:13], v6, off
	v_lshl_add_u64 v[12:13], v[12:13], 0, s[10:11]
	v_fma_f32 v6, v6, v86, v102
	global_load_dword v86, v[8:9], off
	global_load_dword v102, v[10:11], off
	v_lshl_add_u64 v[8:9], v[8:9], 0, s[10:11]
	v_lshl_add_u64 v[10:11], v[10:11], 0, s[10:11]
	s_waitcnt vmcnt(45)
	global_store_dword v[12:13], v6, off
	v_lshl_add_u64 v[12:13], v[12:13], 0, s[10:11]
	v_fma_f32 v6, v6, v87, v103
	global_load_dword v87, v[8:9], off
	global_load_dword v103, v[10:11], off
	v_lshl_add_u64 v[8:9], v[8:9], 0, s[10:11]
	v_lshl_add_u64 v[10:11], v[10:11], 0, s[10:11]
	s_waitcnt vmcnt(45)
	global_store_dword v[12:13], v6, off
	v_lshl_add_u64 v[12:13], v[12:13], 0, s[10:11]
	v_fma_f32 v6, v6, v72, v88
	global_load_dword v72, v[8:9], off
	global_load_dword v88, v[10:11], off
	v_lshl_add_u64 v[8:9], v[8:9], 0, s[10:11]
	v_lshl_add_u64 v[10:11], v[10:11], 0, s[10:11]
	s_waitcnt vmcnt(45)
	global_store_dword v[12:13], v6, off
	v_lshl_add_u64 v[12:13], v[12:13], 0, s[10:11]
	v_fma_f32 v6, v6, v73, v89
	global_load_dword v73, v[8:9], off
	global_load_dword v89, v[10:11], off
	v_lshl_add_u64 v[8:9], v[8:9], 0, s[10:11]
	v_lshl_add_u64 v[10:11], v[10:11], 0, s[10:11]
	s_waitcnt vmcnt(45)
	global_store_dword v[12:13], v6, off
	v_lshl_add_u64 v[12:13], v[12:13], 0, s[10:11]
	v_fma_f32 v6, v6, v74, v90
	global_load_dword v74, v[8:9], off
	global_load_dword v90, v[10:11], off
	v_lshl_add_u64 v[8:9], v[8:9], 0, s[10:11]
	v_lshl_add_u64 v[10:11], v[10:11], 0, s[10:11]
	s_waitcnt vmcnt(45)
	global_store_dword v[12:13], v6, off
	v_lshl_add_u64 v[12:13], v[12:13], 0, s[10:11]
	v_fma_f32 v6, v6, v75, v91
	global_load_dword v75, v[8:9], off
	global_load_dword v91, v[10:11], off
	v_lshl_add_u64 v[8:9], v[8:9], 0, s[10:11]
	v_lshl_add_u64 v[10:11], v[10:11], 0, s[10:11]
	s_waitcnt vmcnt(45)
	global_store_dword v[12:13], v6, off
	v_lshl_add_u64 v[12:13], v[12:13], 0, s[10:11]
	v_fma_f32 v6, v6, v76, v92
	global_load_dword v76, v[8:9], off
	global_load_dword v92, v[10:11], off
	v_lshl_add_u64 v[8:9], v[8:9], 0, s[10:11]
	v_lshl_add_u64 v[10:11], v[10:11], 0, s[10:11]
	s_waitcnt vmcnt(45)
	global_store_dword v[12:13], v6, off
	v_lshl_add_u64 v[12:13], v[12:13], 0, s[10:11]
	v_fma_f32 v6, v6, v77, v93
	global_load_dword v77, v[8:9], off
	global_load_dword v93, v[10:11], off
	v_lshl_add_u64 v[8:9], v[8:9], 0, s[10:11]
	v_lshl_add_u64 v[10:11], v[10:11], 0, s[10:11]
	s_waitcnt vmcnt(45)
	global_store_dword v[12:13], v6, off
	v_lshl_add_u64 v[12:13], v[12:13], 0, s[10:11]
	v_fma_f32 v6, v6, v78, v94
	global_load_dword v78, v[8:9], off
	global_load_dword v94, v[10:11], off
	v_lshl_add_u64 v[8:9], v[8:9], 0, s[10:11]
	v_lshl_add_u64 v[10:11], v[10:11], 0, s[10:11]
	s_waitcnt vmcnt(45)
	global_store_dword v[12:13], v6, off
	v_lshl_add_u64 v[12:13], v[12:13], 0, s[10:11]
	v_fma_f32 v6, v6, v79, v95
	global_load_dword v79, v[8:9], off
	global_load_dword v95, v[10:11], off
	v_lshl_add_u64 v[8:9], v[8:9], 0, s[10:11]
	v_lshl_add_u64 v[10:11], v[10:11], 0, s[10:11]
	s_waitcnt vmcnt(45)
	global_store_dword v[12:13], v6, off
	v_lshl_add_u64 v[12:13], v[12:13], 0, s[10:11]
	v_fma_f32 v6, v6, v80, v96
	global_load_dword v80, v[8:9], off
	global_load_dword v96, v[10:11], off
	v_lshl_add_u64 v[8:9], v[8:9], 0, s[10:11]
	v_lshl_add_u64 v[10:11], v[10:11], 0, s[10:11]
	s_waitcnt vmcnt(45)
	global_store_dword v[12:13], v6, off
	v_lshl_add_u64 v[12:13], v[12:13], 0, s[10:11]
	v_fma_f32 v6, v6, v81, v97
	global_load_dword v81, v[8:9], off
	global_load_dword v97, v[10:11], off
	v_lshl_add_u64 v[8:9], v[8:9], 0, s[10:11]
	v_lshl_add_u64 v[10:11], v[10:11], 0, s[10:11]
	s_waitcnt vmcnt(45)
	global_store_dword v[12:13], v6, off
	v_lshl_add_u64 v[12:13], v[12:13], 0, s[10:11]
	v_fma_f32 v6, v6, v82, v98
	global_load_dword v82, v[8:9], off
	global_load_dword v98, v[10:11], off
	v_lshl_add_u64 v[8:9], v[8:9], 0, s[10:11]
	v_lshl_add_u64 v[10:11], v[10:11], 0, s[10:11]
	s_waitcnt vmcnt(45)
	global_store_dword v[12:13], v6, off
	v_lshl_add_u64 v[12:13], v[12:13], 0, s[10:11]
	v_fma_f32 v6, v6, v83, v99
	global_load_dword v83, v[8:9], off
	global_load_dword v99, v[10:11], off
	v_lshl_add_u64 v[8:9], v[8:9], 0, s[10:11]
	v_lshl_add_u64 v[10:11], v[10:11], 0, s[10:11]
	s_waitcnt vmcnt(45)
	global_store_dword v[12:13], v6, off
	v_lshl_add_u64 v[12:13], v[12:13], 0, s[10:11]
	v_fma_f32 v6, v6, v84, v100
	global_load_dword v84, v[8:9], off
	global_load_dword v100, v[10:11], off
	v_lshl_add_u64 v[8:9], v[8:9], 0, s[10:11]
	v_lshl_add_u64 v[10:11], v[10:11], 0, s[10:11]
	s_waitcnt vmcnt(45)
	global_store_dword v[12:13], v6, off
	v_lshl_add_u64 v[12:13], v[12:13], 0, s[10:11]
	v_fma_f32 v6, v6, v85, v101
	global_load_dword v85, v[8:9], off
	global_load_dword v101, v[10:11], off
	v_lshl_add_u64 v[8:9], v[8:9], 0, s[10:11]
	v_lshl_add_u64 v[10:11], v[10:11], 0, s[10:11]
	s_waitcnt vmcnt(45)
	global_store_dword v[12:13], v6, off
	v_lshl_add_u64 v[12:13], v[12:13], 0, s[10:11]
	v_fma_f32 v6, v6, v86, v102
	global_load_dword v86, v[8:9], off
	global_load_dword v102, v[10:11], off
	v_lshl_add_u64 v[8:9], v[8:9], 0, s[10:11]
	v_lshl_add_u64 v[10:11], v[10:11], 0, s[10:11]
	s_waitcnt vmcnt(45)
	global_store_dword v[12:13], v6, off
	v_lshl_add_u64 v[12:13], v[12:13], 0, s[10:11]
	v_fma_f32 v6, v6, v87, v103
	global_load_dword v87, v[8:9], off
	global_load_dword v103, v[10:11], off
	v_lshl_add_u64 v[8:9], v[8:9], 0, s[10:11]
	v_lshl_add_u64 v[10:11], v[10:11], 0, s[10:11]
	s_waitcnt vmcnt(45)
	global_store_dword v[12:13], v6, off
	v_lshl_add_u64 v[12:13], v[12:13], 0, s[10:11]
	v_fma_f32 v6, v6, v72, v88
	s_waitcnt vmcnt(43)
	global_store_dword v[12:13], v6, off
	v_lshl_add_u64 v[12:13], v[12:13], 0, s[10:11]
	v_fma_f32 v6, v6, v73, v89
	s_waitcnt vmcnt(41)
	global_store_dword v[12:13], v6, off
	v_lshl_add_u64 v[12:13], v[12:13], 0, s[10:11]
	v_fma_f32 v6, v6, v74, v90
	s_waitcnt vmcnt(39)
	global_store_dword v[12:13], v6, off
	v_lshl_add_u64 v[12:13], v[12:13], 0, s[10:11]
	v_fma_f32 v6, v6, v75, v91
	s_waitcnt vmcnt(37)
	global_store_dword v[12:13], v6, off
	v_lshl_add_u64 v[12:13], v[12:13], 0, s[10:11]
	v_fma_f32 v6, v6, v76, v92
	s_waitcnt vmcnt(35)
	global_store_dword v[12:13], v6, off
	v_lshl_add_u64 v[12:13], v[12:13], 0, s[10:11]
	v_fma_f32 v6, v6, v77, v93
	s_waitcnt vmcnt(33)
	global_store_dword v[12:13], v6, off
	v_lshl_add_u64 v[12:13], v[12:13], 0, s[10:11]
	v_fma_f32 v6, v6, v78, v94
	s_waitcnt vmcnt(31)
	global_store_dword v[12:13], v6, off
	v_lshl_add_u64 v[12:13], v[12:13], 0, s[10:11]
	v_fma_f32 v6, v6, v79, v95
	s_waitcnt vmcnt(29)
	global_store_dword v[12:13], v6, off
	v_lshl_add_u64 v[12:13], v[12:13], 0, s[10:11]
	v_fma_f32 v6, v6, v80, v96
	s_waitcnt vmcnt(27)
	global_store_dword v[12:13], v6, off
	v_lshl_add_u64 v[12:13], v[12:13], 0, s[10:11]
	v_fma_f32 v6, v6, v81, v97
	s_waitcnt vmcnt(25)
	global_store_dword v[12:13], v6, off
	v_lshl_add_u64 v[12:13], v[12:13], 0, s[10:11]
	v_fma_f32 v6, v6, v82, v98
	s_waitcnt vmcnt(23)
	global_store_dword v[12:13], v6, off
	v_lshl_add_u64 v[12:13], v[12:13], 0, s[10:11]
	v_fma_f32 v6, v6, v83, v99
	s_waitcnt vmcnt(21)
	global_store_dword v[12:13], v6, off
	v_lshl_add_u64 v[12:13], v[12:13], 0, s[10:11]
	v_fma_f32 v6, v6, v84, v100
	s_waitcnt vmcnt(19)
	global_store_dword v[12:13], v6, off
	v_lshl_add_u64 v[12:13], v[12:13], 0, s[10:11]
	v_fma_f32 v6, v6, v85, v101
	s_waitcnt vmcnt(17)
	global_store_dword v[12:13], v6, off
	v_lshl_add_u64 v[12:13], v[12:13], 0, s[10:11]
	v_fma_f32 v6, v6, v86, v102
	s_waitcnt vmcnt(15)
	global_store_dword v[12:13], v6, off
	v_lshl_add_u64 v[12:13], v[12:13], 0, s[10:11]
	v_fma_f32 v6, v6, v87, v103

.LBB0_534:
	s_mov_b32 s10, 0xfff82000
	s_mov_b32 s11, -1
	v_lshl_add_u64 v[32:33], v[2:3], 0, s[10:11]
	v_lshl_add_u64 v[34:35], v[2:3], 0, s[10:11]
	s_nop 0
	s_mov_b64 s[10:11], 0x12000
	global_load_dwordx2 v[72:73], v[32:33], off
	v_lshl_add_u64 v[32:33], v[32:33], 0, s[10:11]
	global_load_dwordx2 v[74:75], v[32:33], off
	v_lshl_add_u64 v[32:33], v[32:33], 0, s[10:11]
	global_load_dwordx2 v[76:77], v[32:33], off
	v_lshl_add_u64 v[32:33], v[32:33], 0, s[10:11]
	global_load_dwordx2 v[78:79], v[32:33], off
	v_lshl_add_u64 v[32:33], v[32:33], 0, s[10:11]
	global_load_dwordx2 v[80:81], v[32:33], off
	v_lshl_add_u64 v[32:33], v[32:33], 0, s[10:11]
	global_load_dwordx2 v[82:83], v[32:33], off
	v_lshl_add_u64 v[32:33], v[32:33], 0, s[10:11]
	global_load_dwordx2 v[84:85], v[32:33], off
	v_lshl_add_u64 v[32:33], v[32:33], 0, s[10:11]
	global_load_dwordx2 v[86:87], v[32:33], off
	v_lshl_add_u64 v[32:33], v[32:33], 0, s[10:11]
	global_load_dwordx2 v[88:89], v[32:33], off
	v_lshl_add_u64 v[32:33], v[32:33], 0, s[10:11]
	global_load_dwordx2 v[90:91], v[32:33], off
	v_lshl_add_u64 v[32:33], v[32:33], 0, s[10:11]
	global_load_dwordx2 v[92:93], v[32:33], off
	v_lshl_add_u64 v[32:33], v[32:33], 0, s[10:11]
	global_load_dwordx2 v[94:95], v[32:33], off
	v_lshl_add_u64 v[32:33], v[32:33], 0, s[10:11]
	global_load_dwordx2 v[96:97], v[32:33], off
	v_lshl_add_u64 v[32:33], v[32:33], 0, s[10:11]
	global_load_dwordx2 v[98:99], v[32:33], off
	v_lshl_add_u64 v[32:33], v[32:33], 0, s[10:11]
	global_load_dwordx2 v[100:101], v[32:33], off
	v_lshl_add_u64 v[32:33], v[32:33], 0, s[10:11]
	global_load_dwordx2 v[102:103], v[32:33], off
	v_lshl_add_u64 v[32:33], v[32:33], 0, s[10:11]
	v_cvt_pk_bf16_f32 v28, v22, v23
	v_cvt_pk_bf16_f32 v29, v4, v5
	s_waitcnt vmcnt(15)
	global_store_dwordx2 v[34:35], v[28:29], off
	v_lshl_add_u64 v[34:35], v[34:35], 0, s[10:11]
	v_lshlrev_b32_e32 v24, 16, v72
	v_and_b32_e32 v25, 0xffff0000, v72
	v_lshlrev_b32_e32 v26, 16, v73
	v_and_b32_e32 v27, 0xffff0000, v73
	v_pk_fma_f32 v[22:23], v[0:1], v[22:23], v[24:25]
	v_pk_fma_f32 v[4:5], v[0:1], v[4:5], v[26:27]
	global_load_dwordx2 v[72:73], v[32:33], off
	v_lshl_add_u64 v[32:33], v[32:33], 0, s[10:11]
	v_cvt_pk_bf16_f32 v30, v22, v23
	v_cvt_pk_bf16_f32 v31, v4, v5
	s_waitcnt vmcnt(16)
	global_store_dwordx2 v[34:35], v[30:31], off
	v_lshl_add_u64 v[34:35], v[34:35], 0, s[10:11]
	v_lshlrev_b32_e32 v24, 16, v74
	v_and_b32_e32 v25, 0xffff0000, v74
	v_lshlrev_b32_e32 v26, 16, v75
	v_and_b32_e32 v27, 0xffff0000, v75
	v_pk_fma_f32 v[22:23], v[0:1], v[22:23], v[24:25]
	v_pk_fma_f32 v[4:5], v[0:1], v[4:5], v[26:27]
	global_load_dwordx2 v[74:75], v[32:33], off
	v_lshl_add_u64 v[32:33], v[32:33], 0, s[10:11]
	v_cvt_pk_bf16_f32 v28, v22, v23
	v_cvt_pk_bf16_f32 v29, v4, v5
	s_waitcnt vmcnt(17)
	global_store_dwordx2 v[34:35], v[28:29], off
	v_lshl_add_u64 v[34:35], v[34:35], 0, s[10:11]
	v_lshlrev_b32_e32 v24, 16, v76
	v_and_b32_e32 v25, 0xffff0000, v76
	v_lshlrev_b32_e32 v26, 16, v77
	v_and_b32_e32 v27, 0xffff0000, v77
	v_pk_fma_f32 v[22:23], v[0:1], v[22:23], v[24:25]
	v_pk_fma_f32 v[4:5], v[0:1], v[4:5], v[26:27]
	global_load_dwordx2 v[76:77], v[32:33], off
	v_lshl_add_u64 v[32:33], v[32:33], 0, s[10:11]
	v_cvt_pk_bf16_f32 v30, v22, v23
	v_cvt_pk_bf16_f32 v31, v4, v5
	s_waitcnt vmcnt(18)
	global_store_dwordx2 v[34:35], v[30:31], off
	v_lshl_add_u64 v[34:35], v[34:35], 0, s[10:11]
	v_lshlrev_b32_e32 v24, 16, v78
	v_and_b32_e32 v25, 0xffff0000, v78
	v_lshlrev_b32_e32 v26, 16, v79
	v_and_b32_e32 v27, 0xffff0000, v79
	v_pk_fma_f32 v[22:23], v[0:1], v[22:23], v[24:25]
	v_pk_fma_f32 v[4:5], v[0:1], v[4:5], v[26:27]
	global_load_dwordx2 v[78:79], v[32:33], off
	v_lshl_add_u64 v[32:33], v[32:33], 0, s[10:11]
	v_cvt_pk_bf16_f32 v28, v22, v23
	v_cvt_pk_bf16_f32 v29, v4, v5
	s_waitcnt vmcnt(19)
	global_store_dwordx2 v[34:35], v[28:29], off
	v_lshl_add_u64 v[34:35], v[34:35], 0, s[10:11]
	v_lshlrev_b32_e32 v24, 16, v80
	v_and_b32_e32 v25, 0xffff0000, v80
	v_lshlrev_b32_e32 v26, 16, v81
	v_and_b32_e32 v27, 0xffff0000, v81
	v_pk_fma_f32 v[22:23], v[0:1], v[22:23], v[24:25]
	v_pk_fma_f32 v[4:5], v[0:1], v[4:5], v[26:27]
	global_load_dwordx2 v[80:81], v[32:33], off
	v_lshl_add_u64 v[32:33], v[32:33], 0, s[10:11]
	v_cvt_pk_bf16_f32 v30, v22, v23
	v_cvt_pk_bf16_f32 v31, v4, v5
	s_waitcnt vmcnt(20)
	global_store_dwordx2 v[34:35], v[30:31], off
	v_lshl_add_u64 v[34:35], v[34:35], 0, s[10:11]
	v_lshlrev_b32_e32 v24, 16, v82
	v_and_b32_e32 v25, 0xffff0000, v82
	v_lshlrev_b32_e32 v26, 16, v83
	v_and_b32_e32 v27, 0xffff0000, v83
	v_pk_fma_f32 v[22:23], v[0:1], v[22:23], v[24:25]
	v_pk_fma_f32 v[4:5], v[0:1], v[4:5], v[26:27]
	global_load_dwordx2 v[82:83], v[32:33], off
	v_lshl_add_u64 v[32:33], v[32:33], 0, s[10:11]
	v_cvt_pk_bf16_f32 v28, v22, v23
	v_cvt_pk_bf16_f32 v29, v4, v5
	s_waitcnt vmcnt(21)
	global_store_dwordx2 v[34:35], v[28:29], off
	v_lshl_add_u64 v[34:35], v[34:35], 0, s[10:11]
	v_lshlrev_b32_e32 v24, 16, v84
	v_and_b32_e32 v25, 0xffff0000, v84
	v_lshlrev_b32_e32 v26, 16, v85
	v_and_b32_e32 v27, 0xffff0000, v85
	v_pk_fma_f32 v[22:23], v[0:1], v[22:23], v[24:25]
	v_pk_fma_f32 v[4:5], v[0:1], v[4:5], v[26:27]
	global_load_dwordx2 v[84:85], v[32:33], off
	v_lshl_add_u64 v[32:33], v[32:33], 0, s[10:11]
	v_cvt_pk_bf16_f32 v30, v22, v23
	v_cvt_pk_bf16_f32 v31, v4, v5
	s_waitcnt vmcnt(22)
	global_store_dwordx2 v[34:35], v[30:31], off
	v_lshl_add_u64 v[34:35], v[34:35], 0, s[10:11]
	v_lshlrev_b32_e32 v24, 16, v86
	v_and_b32_e32 v25, 0xffff0000, v86
	v_lshlrev_b32_e32 v26, 16, v87
	v_and_b32_e32 v27, 0xffff0000, v87
	v_pk_fma_f32 v[22:23], v[0:1], v[22:23], v[24:25]
	v_pk_fma_f32 v[4:5], v[0:1], v[4:5], v[26:27]
	global_load_dwordx2 v[86:87], v[32:33], off
	v_lshl_add_u64 v[32:33], v[32:33], 0, s[10:11]
	v_cvt_pk_bf16_f32 v28, v22, v23
	v_cvt_pk_bf16_f32 v29, v4, v5
	s_waitcnt vmcnt(23)
	global_store_dwordx2 v[34:35], v[28:29], off
	v_lshl_add_u64 v[34:35], v[34:35], 0, s[10:11]
	v_lshlrev_b32_e32 v24, 16, v88
	v_and_b32_e32 v25, 0xffff0000, v88
	v_lshlrev_b32_e32 v26, 16, v89
	v_and_b32_e32 v27, 0xffff0000, v89
	v_pk_fma_f32 v[22:23], v[0:1], v[22:23], v[24:25]
	v_pk_fma_f32 v[4:5], v[0:1], v[4:5], v[26:27]
	global_load_dwordx2 v[88:89], v[32:33], off
	v_lshl_add_u64 v[32:33], v[32:33], 0, s[10:11]
	v_cvt_pk_bf16_f32 v30, v22, v23
	v_cvt_pk_bf16_f32 v31, v4, v5
	s_waitcnt vmcnt(24)
	global_store_dwordx2 v[34:35], v[30:31], off
	v_lshl_add_u64 v[34:35], v[34:35], 0, s[10:11]
	v_lshlrev_b32_e32 v24, 16, v90
	v_and_b32_e32 v25, 0xffff0000, v90
	v_lshlrev_b32_e32 v26, 16, v91
	v_and_b32_e32 v27, 0xffff0000, v91
	v_pk_fma_f32 v[22:23], v[0:1], v[22:23], v[24:25]
	v_pk_fma_f32 v[4:5], v[0:1], v[4:5], v[26:27]
	global_load_dwordx2 v[90:91], v[32:33], off
	v_lshl_add_u64 v[32:33], v[32:33], 0, s[10:11]
	v_cvt_pk_bf16_f32 v28, v22, v23
	v_cvt_pk_bf16_f32 v29, v4, v5
	s_waitcnt vmcnt(25)
	global_store_dwordx2 v[34:35], v[28:29], off
	v_lshl_add_u64 v[34:35], v[34:35], 0, s[10:11]
	v_lshlrev_b32_e32 v24, 16, v92
	v_and_b32_e32 v25, 0xffff0000, v92
	v_lshlrev_b32_e32 v26, 16, v93
	v_and_b32_e32 v27, 0xffff0000, v93
	v_pk_fma_f32 v[22:23], v[0:1], v[22:23], v[24:25]
	v_pk_fma_f32 v[4:5], v[0:1], v[4:5], v[26:27]
	global_load_dwordx2 v[92:93], v[32:33], off
	v_lshl_add_u64 v[32:33], v[32:33], 0, s[10:11]
	v_cvt_pk_bf16_f32 v30, v22, v23
	v_cvt_pk_bf16_f32 v31, v4, v5
	s_waitcnt vmcnt(26)
	global_store_dwordx2 v[34:35], v[30:31], off
	v_lshl_add_u64 v[34:35], v[34:35], 0, s[10:11]
	v_lshlrev_b32_e32 v24, 16, v94
	v_and_b32_e32 v25, 0xffff0000, v94
	v_lshlrev_b32_e32 v26, 16, v95
	v_and_b32_e32 v27, 0xffff0000, v95
	v_pk_fma_f32 v[22:23], v[0:1], v[22:23], v[24:25]
	v_pk_fma_f32 v[4:5], v[0:1], v[4:5], v[26:27]
	global_load_dwordx2 v[94:95], v[32:33], off
	v_lshl_add_u64 v[32:33], v[32:33], 0, s[10:11]
	v_cvt_pk_bf16_f32 v28, v22, v23
	v_cvt_pk_bf16_f32 v29, v4, v5
	s_waitcnt vmcnt(27)
	global_store_dwordx2 v[34:35], v[28:29], off
	v_lshl_add_u64 v[34:35], v[34:35], 0, s[10:11]
	v_lshlrev_b32_e32 v24, 16, v96
	v_and_b32_e32 v25, 0xffff0000, v96
	v_lshlrev_b32_e32 v26, 16, v97
	v_and_b32_e32 v27, 0xffff0000, v97
	v_pk_fma_f32 v[22:23], v[0:1], v[22:23], v[24:25]
	v_pk_fma_f32 v[4:5], v[0:1], v[4:5], v[26:27]
	global_load_dwordx2 v[96:97], v[32:33], off
	v_lshl_add_u64 v[32:33], v[32:33], 0, s[10:11]
	v_cvt_pk_bf16_f32 v30, v22, v23
	v_cvt_pk_bf16_f32 v31, v4, v5
	s_waitcnt vmcnt(28)
	global_store_dwordx2 v[34:35], v[30:31], off
	v_lshl_add_u64 v[34:35], v[34:35], 0, s[10:11]
	v_lshlrev_b32_e32 v24, 16, v98
	v_and_b32_e32 v25, 0xffff0000, v98
	v_lshlrev_b32_e32 v26, 16, v99
	v_and_b32_e32 v27, 0xffff0000, v99
	v_pk_fma_f32 v[22:23], v[0:1], v[22:23], v[24:25]
	v_pk_fma_f32 v[4:5], v[0:1], v[4:5], v[26:27]
	global_load_dwordx2 v[98:99], v[32:33], off
	v_lshl_add_u64 v[32:33], v[32:33], 0, s[10:11]
	v_cvt_pk_bf16_f32 v28, v22, v23
	v_cvt_pk_bf16_f32 v29, v4, v5
	s_waitcnt vmcnt(29)
	global_store_dwordx2 v[34:35], v[28:29], off
	v_lshl_add_u64 v[34:35], v[34:35], 0, s[10:11]
	v_lshlrev_b32_e32 v24, 16, v100
	v_and_b32_e32 v25, 0xffff0000, v100
	v_lshlrev_b32_e32 v26, 16, v101
	v_and_b32_e32 v27, 0xffff0000, v101
	v_pk_fma_f32 v[22:23], v[0:1], v[22:23], v[24:25]
	v_pk_fma_f32 v[4:5], v[0:1], v[4:5], v[26:27]
	global_load_dwordx2 v[100:101], v[32:33], off
	v_lshl_add_u64 v[32:33], v[32:33], 0, s[10:11]
	v_cvt_pk_bf16_f32 v30, v22, v23
	v_cvt_pk_bf16_f32 v31, v4, v5
	s_waitcnt vmcnt(30)
	global_store_dwordx2 v[34:35], v[30:31], off
	v_lshl_add_u64 v[34:35], v[34:35], 0, s[10:11]
	v_lshlrev_b32_e32 v24, 16, v102
	v_and_b32_e32 v25, 0xffff0000, v102
	v_lshlrev_b32_e32 v26, 16, v103
	v_and_b32_e32 v27, 0xffff0000, v103
	v_pk_fma_f32 v[22:23], v[0:1], v[22:23], v[24:25]
	v_pk_fma_f32 v[4:5], v[0:1], v[4:5], v[26:27]
	global_load_dwordx2 v[102:103], v[32:33], off
	v_lshl_add_u64 v[32:33], v[32:33], 0, s[10:11]
	v_cvt_pk_bf16_f32 v28, v22, v23
	v_cvt_pk_bf16_f32 v29, v4, v5
	s_waitcnt vmcnt(30)
	global_store_dwordx2 v[34:35], v[28:29], off
	v_lshl_add_u64 v[34:35], v[34:35], 0, s[10:11]
	v_lshlrev_b32_e32 v24, 16, v72
	v_and_b32_e32 v25, 0xffff0000, v72
	v_lshlrev_b32_e32 v26, 16, v73
	v_and_b32_e32 v27, 0xffff0000, v73
	v_pk_fma_f32 v[22:23], v[0:1], v[22:23], v[24:25]
	v_pk_fma_f32 v[4:5], v[0:1], v[4:5], v[26:27]
	global_load_dwordx2 v[72:73], v[32:33], off
	v_lshl_add_u64 v[32:33], v[32:33], 0, s[10:11]
	v_cvt_pk_bf16_f32 v30, v22, v23
	v_cvt_pk_bf16_f32 v31, v4, v5
	s_waitcnt vmcnt(30)
	global_store_dwordx2 v[34:35], v[30:31], off
	v_lshl_add_u64 v[34:35], v[34:35], 0, s[10:11]
	v_lshlrev_b32_e32 v24, 16, v74
	v_and_b32_e32 v25, 0xffff0000, v74
	v_lshlrev_b32_e32 v26, 16, v75
	v_and_b32_e32 v27, 0xffff0000, v75
	v_pk_fma_f32 v[22:23], v[0:1], v[22:23], v[24:25]
	v_pk_fma_f32 v[4:5], v[0:1], v[4:5], v[26:27]
	global_load_dwordx2 v[74:75], v[32:33], off
	v_lshl_add_u64 v[32:33], v[32:33], 0, s[10:11]
	v_cvt_pk_bf16_f32 v28, v22, v23
	v_cvt_pk_bf16_f32 v29, v4, v5
	s_waitcnt vmcnt(30)
	global_store_dwordx2 v[34:35], v[28:29], off
	v_lshl_add_u64 v[34:35], v[34:35], 0, s[10:11]
	v_lshlrev_b32_e32 v24, 16, v76
	v_and_b32_e32 v25, 0xffff0000, v76
	v_lshlrev_b32_e32 v26, 16, v77
	v_and_b32_e32 v27, 0xffff0000, v77
	v_pk_fma_f32 v[22:23], v[0:1], v[22:23], v[24:25]
	v_pk_fma_f32 v[4:5], v[0:1], v[4:5], v[26:27]
	global_load_dwordx2 v[76:77], v[32:33], off
	v_lshl_add_u64 v[32:33], v[32:33], 0, s[10:11]
	v_cvt_pk_bf16_f32 v30, v22, v23
	v_cvt_pk_bf16_f32 v31, v4, v5
	s_waitcnt vmcnt(30)
	global_store_dwordx2 v[34:35], v[30:31], off
	v_lshl_add_u64 v[34:35], v[34:35], 0, s[10:11]
	v_lshlrev_b32_e32 v24, 16, v78
	v_and_b32_e32 v25, 0xffff0000, v78
	v_lshlrev_b32_e32 v26, 16, v79
	v_and_b32_e32 v27, 0xffff0000, v79
	v_pk_fma_f32 v[22:23], v[0:1], v[22:23], v[24:25]
	v_pk_fma_f32 v[4:5], v[0:1], v[4:5], v[26:27]
	global_load_dwordx2 v[78:79], v[32:33], off
	v_lshl_add_u64 v[32:33], v[32:33], 0, s[10:11]
	v_cvt_pk_bf16_f32 v28, v22, v23
	v_cvt_pk_bf16_f32 v29, v4, v5
	s_waitcnt vmcnt(30)
	global_store_dwordx2 v[34:35], v[28:29], off
	v_lshl_add_u64 v[34:35], v[34:35], 0, s[10:11]
	v_lshlrev_b32_e32 v24, 16, v80
	v_and_b32_e32 v25, 0xffff0000, v80
	v_lshlrev_b32_e32 v26, 16, v81
	v_and_b32_e32 v27, 0xffff0000, v81
	v_pk_fma_f32 v[22:23], v[0:1], v[22:23], v[24:25]
	v_pk_fma_f32 v[4:5], v[0:1], v[4:5], v[26:27]
	global_load_dwordx2 v[80:81], v[32:33], off
	v_lshl_add_u64 v[32:33], v[32:33], 0, s[10:11]
	v_cvt_pk_bf16_f32 v30, v22, v23
	v_cvt_pk_bf16_f32 v31, v4, v5
	s_waitcnt vmcnt(30)
	global_store_dwordx2 v[34:35], v[30:31], off
	v_lshl_add_u64 v[34:35], v[34:35], 0, s[10:11]
	v_lshlrev_b32_e32 v24, 16, v82
	v_and_b32_e32 v25, 0xffff0000, v82
	v_lshlrev_b32_e32 v26, 16, v83
	v_and_b32_e32 v27, 0xffff0000, v83
	v_pk_fma_f32 v[22:23], v[0:1], v[22:23], v[24:25]
	v_pk_fma_f32 v[4:5], v[0:1], v[4:5], v[26:27]
	global_load_dwordx2 v[82:83], v[32:33], off
	v_lshl_add_u64 v[32:33], v[32:33], 0, s[10:11]
	v_cvt_pk_bf16_f32 v28, v22, v23
	v_cvt_pk_bf16_f32 v29, v4, v5
	s_waitcnt vmcnt(30)
	global_store_dwordx2 v[34:35], v[28:29], off
	v_lshl_add_u64 v[34:35], v[34:35], 0, s[10:11]
	v_lshlrev_b32_e32 v24, 16, v84
	v_and_b32_e32 v25, 0xffff0000, v84
	v_lshlrev_b32_e32 v26, 16, v85
	v_and_b32_e32 v27, 0xffff0000, v85
	v_pk_fma_f32 v[22:23], v[0:1], v[22:23], v[24:25]
	v_pk_fma_f32 v[4:5], v[0:1], v[4:5], v[26:27]
	global_load_dwordx2 v[84:85], v[32:33], off
	v_lshl_add_u64 v[32:33], v[32:33], 0, s[10:11]
	v_cvt_pk_bf16_f32 v30, v22, v23
	v_cvt_pk_bf16_f32 v31, v4, v5
	s_waitcnt vmcnt(30)
	global_store_dwordx2 v[34:35], v[30:31], off
	v_lshl_add_u64 v[34:35], v[34:35], 0, s[10:11]
	v_lshlrev_b32_e32 v24, 16, v86
	v_and_b32_e32 v25, 0xffff0000, v86
	v_lshlrev_b32_e32 v26, 16, v87
	v_and_b32_e32 v27, 0xffff0000, v87
	v_pk_fma_f32 v[22:23], v[0:1], v[22:23], v[24:25]
	v_pk_fma_f32 v[4:5], v[0:1], v[4:5], v[26:27]
	global_load_dwordx2 v[86:87], v[32:33], off
	v_lshl_add_u64 v[32:33], v[32:33], 0, s[10:11]
	v_cvt_pk_bf16_f32 v28, v22, v23
	v_cvt_pk_bf16_f32 v29, v4, v5
	s_waitcnt vmcnt(30)
	global_store_dwordx2 v[34:35], v[28:29], off
	v_lshl_add_u64 v[34:35], v[34:35], 0, s[10:11]
	v_lshlrev_b32_e32 v24, 16, v88
	v_and_b32_e32 v25, 0xffff0000, v88
	v_lshlrev_b32_e32 v26, 16, v89
	v_and_b32_e32 v27, 0xffff0000, v89
	v_pk_fma_f32 v[22:23], v[0:1], v[22:23], v[24:25]
	v_pk_fma_f32 v[4:5], v[0:1], v[4:5], v[26:27]
	global_load_dwordx2 v[88:89], v[32:33], off
	v_lshl_add_u64 v[32:33], v[32:33], 0, s[10:11]
	v_cvt_pk_bf16_f32 v30, v22, v23
	v_cvt_pk_bf16_f32 v31, v4, v5
	s_waitcnt vmcnt(30)
	global_store_dwordx2 v[34:35], v[30:31], off
	v_lshl_add_u64 v[34:35], v[34:35], 0, s[10:11]
	v_lshlrev_b32_e32 v24, 16, v90
	v_and_b32_e32 v25, 0xffff0000, v90
	v_lshlrev_b32_e32 v26, 16, v91
	v_and_b32_e32 v27, 0xffff0000, v91
	v_pk_fma_f32 v[22:23], v[0:1], v[22:23], v[24:25]
	v_pk_fma_f32 v[4:5], v[0:1], v[4:5], v[26:27]
	global_load_dwordx2 v[90:91], v[32:33], off
	v_lshl_add_u64 v[32:33], v[32:33], 0, s[10:11]
	v_cvt_pk_bf16_f32 v28, v22, v23
	v_cvt_pk_bf16_f32 v29, v4, v5
	s_waitcnt vmcnt(30)
	global_store_dwordx2 v[34:35], v[28:29], off
	v_lshl_add_u64 v[34:35], v[34:35], 0, s[10:11]
	v_lshlrev_b32_e32 v24, 16, v92
	v_and_b32_e32 v25, 0xffff0000, v92
	v_lshlrev_b32_e32 v26, 16, v93
	v_and_b32_e32 v27, 0xffff0000, v93
	v_pk_fma_f32 v[22:23], v[0:1], v[22:23], v[24:25]
	v_pk_fma_f32 v[4:5], v[0:1], v[4:5], v[26:27]
	global_load_dwordx2 v[92:93], v[32:33], off
	v_lshl_add_u64 v[32:33], v[32:33], 0, s[10:11]
	v_cvt_pk_bf16_f32 v30, v22, v23
	v_cvt_pk_bf16_f32 v31, v4, v5
	s_waitcnt vmcnt(30)
	global_store_dwordx2 v[34:35], v[30:31], off
	v_lshl_add_u64 v[34:35], v[34:35], 0, s[10:11]
	v_lshlrev_b32_e32 v24, 16, v94
	v_and_b32_e32 v25, 0xffff0000, v94
	v_lshlrev_b32_e32 v26, 16, v95
	v_and_b32_e32 v27, 0xffff0000, v95
	v_pk_fma_f32 v[22:23], v[0:1], v[22:23], v[24:25]
	v_pk_fma_f32 v[4:5], v[0:1], v[4:5], v[26:27]
	global_load_dwordx2 v[94:95], v[32:33], off
	v_lshl_add_u64 v[32:33], v[32:33], 0, s[10:11]
	v_cvt_pk_bf16_f32 v28, v22, v23
	v_cvt_pk_bf16_f32 v29, v4, v5
	s_waitcnt vmcnt(30)
	global_store_dwordx2 v[34:35], v[28:29], off
	v_lshl_add_u64 v[34:35], v[34:35], 0, s[10:11]
	v_lshlrev_b32_e32 v24, 16, v96
	v_and_b32_e32 v25, 0xffff0000, v96
	v_lshlrev_b32_e32 v26, 16, v97
	v_and_b32_e32 v27, 0xffff0000, v97
	v_pk_fma_f32 v[22:23], v[0:1], v[22:23], v[24:25]
	v_pk_fma_f32 v[4:5], v[0:1], v[4:5], v[26:27]
	global_load_dwordx2 v[96:97], v[32:33], off
	v_lshl_add_u64 v[32:33], v[32:33], 0, s[10:11]
	v_cvt_pk_bf16_f32 v30, v22, v23
	v_cvt_pk_bf16_f32 v31, v4, v5
	s_waitcnt vmcnt(30)
	global_store_dwordx2 v[34:35], v[30:31], off
	v_lshl_add_u64 v[34:35], v[34:35], 0, s[10:11]
	v_lshlrev_b32_e32 v24, 16, v98
	v_and_b32_e32 v25, 0xffff0000, v98
	v_lshlrev_b32_e32 v26, 16, v99
	v_and_b32_e32 v27, 0xffff0000, v99
	v_pk_fma_f32 v[22:23], v[0:1], v[22:23], v[24:25]
	v_pk_fma_f32 v[4:5], v[0:1], v[4:5], v[26:27]
	global_load_dwordx2 v[98:99], v[32:33], off
	v_lshl_add_u64 v[32:33], v[32:33], 0, s[10:11]
	v_cvt_pk_bf16_f32 v28, v22, v23
	v_cvt_pk_bf16_f32 v29, v4, v5
	s_waitcnt vmcnt(30)
	global_store_dwordx2 v[34:35], v[28:29], off
	v_lshl_add_u64 v[34:35], v[34:35], 0, s[10:11]
	v_lshlrev_b32_e32 v24, 16, v100
	v_and_b32_e32 v25, 0xffff0000, v100
	v_lshlrev_b32_e32 v26, 16, v101
	v_and_b32_e32 v27, 0xffff0000, v101
	v_pk_fma_f32 v[22:23], v[0:1], v[22:23], v[24:25]
	v_pk_fma_f32 v[4:5], v[0:1], v[4:5], v[26:27]
	global_load_dwordx2 v[100:101], v[32:33], off
	v_lshl_add_u64 v[32:33], v[32:33], 0, s[10:11]
	v_cvt_pk_bf16_f32 v30, v22, v23
	v_cvt_pk_bf16_f32 v31, v4, v5
	s_waitcnt vmcnt(30)
	global_store_dwordx2 v[34:35], v[30:31], off
	v_lshl_add_u64 v[34:35], v[34:35], 0, s[10:11]
	v_lshlrev_b32_e32 v24, 16, v102
	v_and_b32_e32 v25, 0xffff0000, v102
	v_lshlrev_b32_e32 v26, 16, v103
	v_and_b32_e32 v27, 0xffff0000, v103
	v_pk_fma_f32 v[22:23], v[0:1], v[22:23], v[24:25]
	v_pk_fma_f32 v[4:5], v[0:1], v[4:5], v[26:27]
	global_load_dwordx2 v[102:103], v[32:33], off
	v_lshl_add_u64 v[32:33], v[32:33], 0, s[10:11]
	v_cvt_pk_bf16_f32 v28, v22, v23
	v_cvt_pk_bf16_f32 v29, v4, v5
	s_waitcnt vmcnt(30)
	global_store_dwordx2 v[34:35], v[28:29], off
	v_lshl_add_u64 v[34:35], v[34:35], 0, s[10:11]
	v_lshlrev_b32_e32 v24, 16, v72
	v_and_b32_e32 v25, 0xffff0000, v72
	v_lshlrev_b32_e32 v26, 16, v73
	v_and_b32_e32 v27, 0xffff0000, v73
	v_pk_fma_f32 v[22:23], v[0:1], v[22:23], v[24:25]
	v_pk_fma_f32 v[4:5], v[0:1], v[4:5], v[26:27]
	global_load_dwordx2 v[72:73], v[32:33], off
	v_lshl_add_u64 v[32:33], v[32:33], 0, s[10:11]
	v_cvt_pk_bf16_f32 v30, v22, v23
	v_cvt_pk_bf16_f32 v31, v4, v5
	s_waitcnt vmcnt(30)
	global_store_dwordx2 v[34:35], v[30:31], off
	v_lshl_add_u64 v[34:35], v[34:35], 0, s[10:11]
	v_lshlrev_b32_e32 v24, 16, v74
	v_and_b32_e32 v25, 0xffff0000, v74
	v_lshlrev_b32_e32 v26, 16, v75
	v_and_b32_e32 v27, 0xffff0000, v75
	v_pk_fma_f32 v[22:23], v[0:1], v[22:23], v[24:25]
	v_pk_fma_f32 v[4:5], v[0:1], v[4:5], v[26:27]
	global_load_dwordx2 v[74:75], v[32:33], off
	v_lshl_add_u64 v[32:33], v[32:33], 0, s[10:11]
	v_cvt_pk_bf16_f32 v28, v22, v23
	v_cvt_pk_bf16_f32 v29, v4, v5
	s_waitcnt vmcnt(30)
	global_store_dwordx2 v[34:35], v[28:29], off
	v_lshl_add_u64 v[34:35], v[34:35], 0, s[10:11]
	v_lshlrev_b32_e32 v24, 16, v76
	v_and_b32_e32 v25, 0xffff0000, v76
	v_lshlrev_b32_e32 v26, 16, v77
	v_and_b32_e32 v27, 0xffff0000, v77
	v_pk_fma_f32 v[22:23], v[0:1], v[22:23], v[24:25]
	v_pk_fma_f32 v[4:5], v[0:1], v[4:5], v[26:27]
	global_load_dwordx2 v[76:77], v[32:33], off
	v_lshl_add_u64 v[32:33], v[32:33], 0, s[10:11]
	v_cvt_pk_bf16_f32 v30, v22, v23
	v_cvt_pk_bf16_f32 v31, v4, v5
	s_waitcnt vmcnt(30)
	global_store_dwordx2 v[34:35], v[30:31], off
	v_lshl_add_u64 v[34:35], v[34:35], 0, s[10:11]
	v_lshlrev_b32_e32 v24, 16, v78
	v_and_b32_e32 v25, 0xffff0000, v78
	v_lshlrev_b32_e32 v26, 16, v79
	v_and_b32_e32 v27, 0xffff0000, v79
	v_pk_fma_f32 v[22:23], v[0:1], v[22:23], v[24:25]
	v_pk_fma_f32 v[4:5], v[0:1], v[4:5], v[26:27]
	global_load_dwordx2 v[78:79], v[32:33], off
	v_lshl_add_u64 v[32:33], v[32:33], 0, s[10:11]
	v_cvt_pk_bf16_f32 v28, v22, v23
	v_cvt_pk_bf16_f32 v29, v4, v5
	s_waitcnt vmcnt(30)
	global_store_dwordx2 v[34:35], v[28:29], off
	v_lshl_add_u64 v[34:35], v[34:35], 0, s[10:11]
	v_lshlrev_b32_e32 v24, 16, v80
	v_and_b32_e32 v25, 0xffff0000, v80
	v_lshlrev_b32_e32 v26, 16, v81
	v_and_b32_e32 v27, 0xffff0000, v81
	v_pk_fma_f32 v[22:23], v[0:1], v[22:23], v[24:25]
	v_pk_fma_f32 v[4:5], v[0:1], v[4:5], v[26:27]
	global_load_dwordx2 v[80:81], v[32:33], off
	v_lshl_add_u64 v[32:33], v[32:33], 0, s[10:11]
	v_cvt_pk_bf16_f32 v30, v22, v23
	v_cvt_pk_bf16_f32 v31, v4, v5
	s_waitcnt vmcnt(30)
	global_store_dwordx2 v[34:35], v[30:31], off
	v_lshl_add_u64 v[34:35], v[34:35], 0, s[10:11]
	v_lshlrev_b32_e32 v24, 16, v82
	v_and_b32_e32 v25, 0xffff0000, v82
	v_lshlrev_b32_e32 v26, 16, v83
	v_and_b32_e32 v27, 0xffff0000, v83
	v_pk_fma_f32 v[22:23], v[0:1], v[22:23], v[24:25]
	v_pk_fma_f32 v[4:5], v[0:1], v[4:5], v[26:27]
	global_load_dwordx2 v[82:83], v[32:33], off
	v_lshl_add_u64 v[32:33], v[32:33], 0, s[10:11]
	v_cvt_pk_bf16_f32 v28, v22, v23
	v_cvt_pk_bf16_f32 v29, v4, v5
	s_waitcnt vmcnt(30)
	global_store_dwordx2 v[34:35], v[28:29], off
	v_lshl_add_u64 v[34:35], v[34:35], 0, s[10:11]
	v_lshlrev_b32_e32 v24, 16, v84
	v_and_b32_e32 v25, 0xffff0000, v84
	v_lshlrev_b32_e32 v26, 16, v85
	v_and_b32_e32 v27, 0xffff0000, v85
	v_pk_fma_f32 v[22:23], v[0:1], v[22:23], v[24:25]
	v_pk_fma_f32 v[4:5], v[0:1], v[4:5], v[26:27]
	global_load_dwordx2 v[84:85], v[32:33], off
	v_lshl_add_u64 v[32:33], v[32:33], 0, s[10:11]
	v_cvt_pk_bf16_f32 v30, v22, v23
	v_cvt_pk_bf16_f32 v31, v4, v5
	s_waitcnt vmcnt(30)
	global_store_dwordx2 v[34:35], v[30:31], off
	v_lshl_add_u64 v[34:35], v[34:35], 0, s[10:11]
	v_lshlrev_b32_e32 v24, 16, v86
	v_and_b32_e32 v25, 0xffff0000, v86
	v_lshlrev_b32_e32 v26, 16, v87
	v_and_b32_e32 v27, 0xffff0000, v87
	v_pk_fma_f32 v[22:23], v[0:1], v[22:23], v[24:25]
	v_pk_fma_f32 v[4:5], v[0:1], v[4:5], v[26:27]
	global_load_dwordx2 v[86:87], v[32:33], off
	v_lshl_add_u64 v[32:33], v[32:33], 0, s[10:11]
	v_cvt_pk_bf16_f32 v28, v22, v23
	v_cvt_pk_bf16_f32 v29, v4, v5
	s_waitcnt vmcnt(30)
	global_store_dwordx2 v[34:35], v[28:29], off
	v_lshl_add_u64 v[34:35], v[34:35], 0, s[10:11]
	v_lshlrev_b32_e32 v24, 16, v88
	v_and_b32_e32 v25, 0xffff0000, v88
	v_lshlrev_b32_e32 v26, 16, v89
	v_and_b32_e32 v27, 0xffff0000, v89
	v_pk_fma_f32 v[22:23], v[0:1], v[22:23], v[24:25]
	v_pk_fma_f32 v[4:5], v[0:1], v[4:5], v[26:27]
	global_load_dwordx2 v[88:89], v[32:33], off
	v_lshl_add_u64 v[32:33], v[32:33], 0, s[10:11]
	v_cvt_pk_bf16_f32 v30, v22, v23
	v_cvt_pk_bf16_f32 v31, v4, v5
	s_waitcnt vmcnt(30)
	global_store_dwordx2 v[34:35], v[30:31], off
	v_lshl_add_u64 v[34:35], v[34:35], 0, s[10:11]
	v_lshlrev_b32_e32 v24, 16, v90
	v_and_b32_e32 v25, 0xffff0000, v90
	v_lshlrev_b32_e32 v26, 16, v91
	v_and_b32_e32 v27, 0xffff0000, v91
	v_pk_fma_f32 v[22:23], v[0:1], v[22:23], v[24:25]
	v_pk_fma_f32 v[4:5], v[0:1], v[4:5], v[26:27]
	global_load_dwordx2 v[90:91], v[32:33], off
	v_lshl_add_u64 v[32:33], v[32:33], 0, s[10:11]
	v_cvt_pk_bf16_f32 v28, v22, v23
	v_cvt_pk_bf16_f32 v29, v4, v5
	s_waitcnt vmcnt(30)
	global_store_dwordx2 v[34:35], v[28:29], off
	v_lshl_add_u64 v[34:35], v[34:35], 0, s[10:11]
	v_lshlrev_b32_e32 v24, 16, v92
	v_and_b32_e32 v25, 0xffff0000, v92
	v_lshlrev_b32_e32 v26, 16, v93
	v_and_b32_e32 v27, 0xffff0000, v93
	v_pk_fma_f32 v[22:23], v[0:1], v[22:23], v[24:25]
	v_pk_fma_f32 v[4:5], v[0:1], v[4:5], v[26:27]
	global_load_dwordx2 v[92:93], v[32:33], off
	v_lshl_add_u64 v[32:33], v[32:33], 0, s[10:11]
	v_cvt_pk_bf16_f32 v30, v22, v23
	v_cvt_pk_bf16_f32 v31, v4, v5
	s_waitcnt vmcnt(30)
	global_store_dwordx2 v[34:35], v[30:31], off
	v_lshl_add_u64 v[34:35], v[34:35], 0, s[10:11]
	v_lshlrev_b32_e32 v24, 16, v94
	v_and_b32_e32 v25, 0xffff0000, v94
	v_lshlrev_b32_e32 v26, 16, v95
	v_and_b32_e32 v27, 0xffff0000, v95
	v_pk_fma_f32 v[22:23], v[0:1], v[22:23], v[24:25]
	v_pk_fma_f32 v[4:5], v[0:1], v[4:5], v[26:27]
	global_load_dwordx2 v[94:95], v[32:33], off
	v_lshl_add_u64 v[32:33], v[32:33], 0, s[10:11]
	v_cvt_pk_bf16_f32 v28, v22, v23
	v_cvt_pk_bf16_f32 v29, v4, v5
	s_waitcnt vmcnt(30)
	global_store_dwordx2 v[34:35], v[28:29], off
	v_lshl_add_u64 v[34:35], v[34:35], 0, s[10:11]
	v_lshlrev_b32_e32 v24, 16, v96
	v_and_b32_e32 v25, 0xffff0000, v96
	v_lshlrev_b32_e32 v26, 16, v97
	v_and_b32_e32 v27, 0xffff0000, v97
	v_pk_fma_f32 v[22:23], v[0:1], v[22:23], v[24:25]
	v_pk_fma_f32 v[4:5], v[0:1], v[4:5], v[26:27]
	global_load_dwordx2 v[96:97], v[32:33], off
	v_lshl_add_u64 v[32:33], v[32:33], 0, s[10:11]
	v_cvt_pk_bf16_f32 v30, v22, v23
	v_cvt_pk_bf16_f32 v31, v4, v5
	s_waitcnt vmcnt(30)
	global_store_dwordx2 v[34:35], v[30:31], off
	v_lshl_add_u64 v[34:35], v[34:35], 0, s[10:11]
	v_lshlrev_b32_e32 v24, 16, v98
	v_and_b32_e32 v25, 0xffff0000, v98
	v_lshlrev_b32_e32 v26, 16, v99
	v_and_b32_e32 v27, 0xffff0000, v99
	v_pk_fma_f32 v[22:23], v[0:1], v[22:23], v[24:25]
	v_pk_fma_f32 v[4:5], v[0:1], v[4:5], v[26:27]
	global_load_dwordx2 v[98:99], v[32:33], off
	v_lshl_add_u64 v[32:33], v[32:33], 0, s[10:11]
	v_cvt_pk_bf16_f32 v28, v22, v23
	v_cvt_pk_bf16_f32 v29, v4, v5
	s_waitcnt vmcnt(30)
	global_store_dwordx2 v[34:35], v[28:29], off
	v_lshl_add_u64 v[34:35], v[34:35], 0, s[10:11]
	v_lshlrev_b32_e32 v24, 16, v100
	v_and_b32_e32 v25, 0xffff0000, v100
	v_lshlrev_b32_e32 v26, 16, v101
	v_and_b32_e32 v27, 0xffff0000, v101
	v_pk_fma_f32 v[22:23], v[0:1], v[22:23], v[24:25]
	v_pk_fma_f32 v[4:5], v[0:1], v[4:5], v[26:27]
	global_load_dwordx2 v[100:101], v[32:33], off
	v_lshl_add_u64 v[32:33], v[32:33], 0, s[10:11]
	v_cvt_pk_bf16_f32 v30, v22, v23
	v_cvt_pk_bf16_f32 v31, v4, v5
	s_waitcnt vmcnt(30)
	global_store_dwordx2 v[34:35], v[30:31], off
	v_lshl_add_u64 v[34:35], v[34:35], 0, s[10:11]
	v_lshlrev_b32_e32 v24, 16, v102
	v_and_b32_e32 v25, 0xffff0000, v102
	v_lshlrev_b32_e32 v26, 16, v103
	v_and_b32_e32 v27, 0xffff0000, v103
	v_pk_fma_f32 v[22:23], v[0:1], v[22:23], v[24:25]
	v_pk_fma_f32 v[4:5], v[0:1], v[4:5], v[26:27]
	global_load_dwordx2 v[102:103], v[32:33], off
	v_lshl_add_u64 v[32:33], v[32:33], 0, s[10:11]
	v_cvt_pk_bf16_f32 v28, v22, v23
	v_cvt_pk_bf16_f32 v29, v4, v5
	s_waitcnt vmcnt(30)
	global_store_dwordx2 v[34:35], v[28:29], off
	v_lshl_add_u64 v[34:35], v[34:35], 0, s[10:11]
	v_lshlrev_b32_e32 v24, 16, v72
	v_and_b32_e32 v25, 0xffff0000, v72
	v_lshlrev_b32_e32 v26, 16, v73
	v_and_b32_e32 v27, 0xffff0000, v73
	v_pk_fma_f32 v[22:23], v[0:1], v[22:23], v[24:25]
	v_pk_fma_f32 v[4:5], v[0:1], v[4:5], v[26:27]
	global_load_dwordx2 v[72:73], v[32:33], off
	v_lshl_add_u64 v[32:33], v[32:33], 0, s[10:11]
	v_cvt_pk_bf16_f32 v30, v22, v23
	v_cvt_pk_bf16_f32 v31, v4, v5
	s_waitcnt vmcnt(30)
	global_store_dwordx2 v[34:35], v[30:31], off
	v_lshl_add_u64 v[34:35], v[34:35], 0, s[10:11]
	v_lshlrev_b32_e32 v24, 16, v74
	v_and_b32_e32 v25, 0xffff0000, v74
	v_lshlrev_b32_e32 v26, 16, v75
	v_and_b32_e32 v27, 0xffff0000, v75
	v_pk_fma_f32 v[22:23], v[0:1], v[22:23], v[24:25]
	v_pk_fma_f32 v[4:5], v[0:1], v[4:5], v[26:27]
	global_load_dwordx2 v[74:75], v[32:33], off
	v_lshl_add_u64 v[32:33], v[32:33], 0, s[10:11]
	v_cvt_pk_bf16_f32 v28, v22, v23
	v_cvt_pk_bf16_f32 v29, v4, v5
	s_waitcnt vmcnt(30)
	global_store_dwordx2 v[34:35], v[28:29], off
	v_lshl_add_u64 v[34:35], v[34:35], 0, s[10:11]
	v_lshlrev_b32_e32 v24, 16, v76
	v_and_b32_e32 v25, 0xffff0000, v76
	v_lshlrev_b32_e32 v26, 16, v77
	v_and_b32_e32 v27, 0xffff0000, v77
	v_pk_fma_f32 v[22:23], v[0:1], v[22:23], v[24:25]
	v_pk_fma_f32 v[4:5], v[0:1], v[4:5], v[26:27]
	global_load_dwordx2 v[76:77], v[32:33], off
	v_lshl_add_u64 v[32:33], v[32:33], 0, s[10:11]
	v_cvt_pk_bf16_f32 v30, v22, v23
	v_cvt_pk_bf16_f32 v31, v4, v5
	s_waitcnt vmcnt(30)
	global_store_dwordx2 v[34:35], v[30:31], off
	v_lshl_add_u64 v[34:35], v[34:35], 0, s[10:11]
	v_lshlrev_b32_e32 v24, 16, v78
	v_and_b32_e32 v25, 0xffff0000, v78
	v_lshlrev_b32_e32 v26, 16, v79
	v_and_b32_e32 v27, 0xffff0000, v79
	v_pk_fma_f32 v[22:23], v[0:1], v[22:23], v[24:25]
	v_pk_fma_f32 v[4:5], v[0:1], v[4:5], v[26:27]
	global_load_dwordx2 v[78:79], v[32:33], off
	v_lshl_add_u64 v[32:33], v[32:33], 0, s[10:11]
	v_cvt_pk_bf16_f32 v28, v22, v23
	v_cvt_pk_bf16_f32 v29, v4, v5
	s_waitcnt vmcnt(30)
	global_store_dwordx2 v[34:35], v[28:29], off
	v_lshl_add_u64 v[34:35], v[34:35], 0, s[10:11]
	v_lshlrev_b32_e32 v24, 16, v80
	v_and_b32_e32 v25, 0xffff0000, v80
	v_lshlrev_b32_e32 v26, 16, v81
	v_and_b32_e32 v27, 0xffff0000, v81
	v_pk_fma_f32 v[22:23], v[0:1], v[22:23], v[24:25]
	v_pk_fma_f32 v[4:5], v[0:1], v[4:5], v[26:27]
	global_load_dwordx2 v[80:81], v[32:33], off
	v_lshl_add_u64 v[32:33], v[32:33], 0, s[10:11]
	v_cvt_pk_bf16_f32 v30, v22, v23
	v_cvt_pk_bf16_f32 v31, v4, v5
	s_waitcnt vmcnt(30)
	global_store_dwordx2 v[34:35], v[30:31], off
	v_lshl_add_u64 v[34:35], v[34:35], 0, s[10:11]
	v_lshlrev_b32_e32 v24, 16, v82
	v_and_b32_e32 v25, 0xffff0000, v82
	v_lshlrev_b32_e32 v26, 16, v83
	v_and_b32_e32 v27, 0xffff0000, v83
	v_pk_fma_f32 v[22:23], v[0:1], v[22:23], v[24:25]
	v_pk_fma_f32 v[4:5], v[0:1], v[4:5], v[26:27]
	global_load_dwordx2 v[82:83], v[32:33], off
	v_lshl_add_u64 v[32:33], v[32:33], 0, s[10:11]
	v_cvt_pk_bf16_f32 v28, v22, v23
	v_cvt_pk_bf16_f32 v29, v4, v5
	s_waitcnt vmcnt(30)
	global_store_dwordx2 v[34:35], v[28:29], off
	v_lshl_add_u64 v[34:35], v[34:35], 0, s[10:11]
	v_lshlrev_b32_e32 v24, 16, v84
	v_and_b32_e32 v25, 0xffff0000, v84
	v_lshlrev_b32_e32 v26, 16, v85
	v_and_b32_e32 v27, 0xffff0000, v85
	v_pk_fma_f32 v[22:23], v[0:1], v[22:23], v[24:25]
	v_pk_fma_f32 v[4:5], v[0:1], v[4:5], v[26:27]
	global_load_dwordx2 v[84:85], v[32:33], off
	v_lshl_add_u64 v[32:33], v[32:33], 0, s[10:11]
	v_cvt_pk_bf16_f32 v30, v22, v23
	v_cvt_pk_bf16_f32 v31, v4, v5
	s_waitcnt vmcnt(30)
	global_store_dwordx2 v[34:35], v[30:31], off
	v_lshl_add_u64 v[34:35], v[34:35], 0, s[10:11]
	v_lshlrev_b32_e32 v24, 16, v86
	v_and_b32_e32 v25, 0xffff0000, v86
	v_lshlrev_b32_e32 v26, 16, v87
	v_and_b32_e32 v27, 0xffff0000, v87
	v_pk_fma_f32 v[22:23], v[0:1], v[22:23], v[24:25]
	v_pk_fma_f32 v[4:5], v[0:1], v[4:5], v[26:27]
	global_load_dwordx2 v[86:87], v[32:33], off
	v_lshl_add_u64 v[32:33], v[32:33], 0, s[10:11]
	v_cvt_pk_bf16_f32 v28, v22, v23
	v_cvt_pk_bf16_f32 v29, v4, v5
	s_waitcnt vmcnt(30)
	global_store_dwordx2 v[34:35], v[28:29], off
	v_lshl_add_u64 v[34:35], v[34:35], 0, s[10:11]
	v_lshlrev_b32_e32 v24, 16, v88
	v_and_b32_e32 v25, 0xffff0000, v88
	v_lshlrev_b32_e32 v26, 16, v89
	v_and_b32_e32 v27, 0xffff0000, v89
	v_pk_fma_f32 v[22:23], v[0:1], v[22:23], v[24:25]
	v_pk_fma_f32 v[4:5], v[0:1], v[4:5], v[26:27]
	global_load_dwordx2 v[88:89], v[32:33], off
	v_lshl_add_u64 v[32:33], v[32:33], 0, s[10:11]
	v_cvt_pk_bf16_f32 v30, v22, v23
	v_cvt_pk_bf16_f32 v31, v4, v5
	s_waitcnt vmcnt(30)
	global_store_dwordx2 v[34:35], v[30:31], off
	v_lshl_add_u64 v[34:35], v[34:35], 0, s[10:11]
	v_lshlrev_b32_e32 v24, 16, v90
	v_and_b32_e32 v25, 0xffff0000, v90
	v_lshlrev_b32_e32 v26, 16, v91
	v_and_b32_e32 v27, 0xffff0000, v91
	v_pk_fma_f32 v[22:23], v[0:1], v[22:23], v[24:25]
	v_pk_fma_f32 v[4:5], v[0:1], v[4:5], v[26:27]
	global_load_dwordx2 v[90:91], v[32:33], off
	v_lshl_add_u64 v[32:33], v[32:33], 0, s[10:11]
	v_cvt_pk_bf16_f32 v28, v22, v23
	v_cvt_pk_bf16_f32 v29, v4, v5
	s_waitcnt vmcnt(30)
	global_store_dwordx2 v[34:35], v[28:29], off
	v_lshl_add_u64 v[34:35], v[34:35], 0, s[10:11]
	v_lshlrev_b32_e32 v24, 16, v92
	v_and_b32_e32 v25, 0xffff0000, v92
	v_lshlrev_b32_e32 v26, 16, v93
	v_and_b32_e32 v27, 0xffff0000, v93
	v_pk_fma_f32 v[22:23], v[0:1], v[22:23], v[24:25]
	v_pk_fma_f32 v[4:5], v[0:1], v[4:5], v[26:27]
	global_load_dwordx2 v[92:93], v[32:33], off
	v_lshl_add_u64 v[32:33], v[32:33], 0, s[10:11]
	v_cvt_pk_bf16_f32 v30, v22, v23
	v_cvt_pk_bf16_f32 v31, v4, v5
	s_waitcnt vmcnt(30)
	global_store_dwordx2 v[34:35], v[30:31], off
	v_lshl_add_u64 v[34:35], v[34:35], 0, s[10:11]
	v_lshlrev_b32_e32 v24, 16, v94
	v_and_b32_e32 v25, 0xffff0000, v94
	v_lshlrev_b32_e32 v26, 16, v95
	v_and_b32_e32 v27, 0xffff0000, v95
	v_pk_fma_f32 v[22:23], v[0:1], v[22:23], v[24:25]
	v_pk_fma_f32 v[4:5], v[0:1], v[4:5], v[26:27]
	global_load_dwordx2 v[94:95], v[32:33], off
	v_lshl_add_u64 v[32:33], v[32:33], 0, s[10:11]
	v_cvt_pk_bf16_f32 v28, v22, v23
	v_cvt_pk_bf16_f32 v29, v4, v5
	s_waitcnt vmcnt(30)
	global_store_dwordx2 v[34:35], v[28:29], off
	v_lshl_add_u64 v[34:35], v[34:35], 0, s[10:11]
	v_lshlrev_b32_e32 v24, 16, v96
	v_and_b32_e32 v25, 0xffff0000, v96
	v_lshlrev_b32_e32 v26, 16, v97
	v_and_b32_e32 v27, 0xffff0000, v97
	v_pk_fma_f32 v[22:23], v[0:1], v[22:23], v[24:25]
	v_pk_fma_f32 v[4:5], v[0:1], v[4:5], v[26:27]
	global_load_dwordx2 v[96:97], v[32:33], off
	v_lshl_add_u64 v[32:33], v[32:33], 0, s[10:11]
	v_cvt_pk_bf16_f32 v30, v22, v23
	v_cvt_pk_bf16_f32 v31, v4, v5
	s_waitcnt vmcnt(30)
	global_store_dwordx2 v[34:35], v[30:31], off
	v_lshl_add_u64 v[34:35], v[34:35], 0, s[10:11]
	v_lshlrev_b32_e32 v24, 16, v98
	v_and_b32_e32 v25, 0xffff0000, v98
	v_lshlrev_b32_e32 v26, 16, v99
	v_and_b32_e32 v27, 0xffff0000, v99
	v_pk_fma_f32 v[22:23], v[0:1], v[22:23], v[24:25]
	v_pk_fma_f32 v[4:5], v[0:1], v[4:5], v[26:27]
	global_load_dwordx2 v[98:99], v[32:33], off
	v_lshl_add_u64 v[32:33], v[32:33], 0, s[10:11]
	v_cvt_pk_bf16_f32 v28, v22, v23
	v_cvt_pk_bf16_f32 v29, v4, v5
	s_waitcnt vmcnt(30)
	global_store_dwordx2 v[34:35], v[28:29], off
	v_lshl_add_u64 v[34:35], v[34:35], 0, s[10:11]
	v_lshlrev_b32_e32 v24, 16, v100
	v_and_b32_e32 v25, 0xffff0000, v100
	v_lshlrev_b32_e32 v26, 16, v101
	v_and_b32_e32 v27, 0xffff0000, v101
	v_pk_fma_f32 v[22:23], v[0:1], v[22:23], v[24:25]
	v_pk_fma_f32 v[4:5], v[0:1], v[4:5], v[26:27]
	global_load_dwordx2 v[100:101], v[32:33], off
	v_lshl_add_u64 v[32:33], v[32:33], 0, s[10:11]
	v_cvt_pk_bf16_f32 v30, v22, v23
	v_cvt_pk_bf16_f32 v31, v4, v5
	s_waitcnt vmcnt(30)
	global_store_dwordx2 v[34:35], v[30:31], off
	v_lshl_add_u64 v[34:35], v[34:35], 0, s[10:11]
	v_lshlrev_b32_e32 v24, 16, v102
	v_and_b32_e32 v25, 0xffff0000, v102
	v_lshlrev_b32_e32 v26, 16, v103
	v_and_b32_e32 v27, 0xffff0000, v103
	v_pk_fma_f32 v[22:23], v[0:1], v[22:23], v[24:25]
	v_pk_fma_f32 v[4:5], v[0:1], v[4:5], v[26:27]
	global_load_dwordx2 v[102:103], v[32:33], off
	v_lshl_add_u64 v[32:33], v[32:33], 0, s[10:11]
	v_cvt_pk_bf16_f32 v28, v22, v23
	v_cvt_pk_bf16_f32 v29, v4, v5
	s_waitcnt vmcnt(30)
	global_store_dwordx2 v[34:35], v[28:29], off
	v_lshl_add_u64 v[34:35], v[34:35], 0, s[10:11]
	v_lshlrev_b32_e32 v24, 16, v72
	v_and_b32_e32 v25, 0xffff0000, v72
	v_lshlrev_b32_e32 v26, 16, v73
	v_and_b32_e32 v27, 0xffff0000, v73
	v_pk_fma_f32 v[22:23], v[0:1], v[22:23], v[24:25]
	v_pk_fma_f32 v[4:5], v[0:1], v[4:5], v[26:27]
	global_load_dwordx2 v[72:73], v[32:33], off
	v_lshl_add_u64 v[32:33], v[32:33], 0, s[10:11]
	v_cvt_pk_bf16_f32 v30, v22, v23
	v_cvt_pk_bf16_f32 v31, v4, v5
	s_waitcnt vmcnt(30)
	global_store_dwordx2 v[34:35], v[30:31], off
	v_lshl_add_u64 v[34:35], v[34:35], 0, s[10:11]
	v_lshlrev_b32_e32 v24, 16, v74
	v_and_b32_e32 v25, 0xffff0000, v74
	v_lshlrev_b32_e32 v26, 16, v75
	v_and_b32_e32 v27, 0xffff0000, v75
	v_pk_fma_f32 v[22:23], v[0:1], v[22:23], v[24:25]
	v_pk_fma_f32 v[4:5], v[0:1], v[4:5], v[26:27]
	global_load_dwordx2 v[74:75], v[32:33], off
	v_lshl_add_u64 v[32:33], v[32:33], 0, s[10:11]
	v_cvt_pk_bf16_f32 v28, v22, v23
	v_cvt_pk_bf16_f32 v29, v4, v5
	s_waitcnt vmcnt(30)
	global_store_dwordx2 v[34:35], v[28:29], off
	v_lshl_add_u64 v[34:35], v[34:35], 0, s[10:11]
	v_lshlrev_b32_e32 v24, 16, v76
	v_and_b32_e32 v25, 0xffff0000, v76
	v_lshlrev_b32_e32 v26, 16, v77
	v_and_b32_e32 v27, 0xffff0000, v77
	v_pk_fma_f32 v[22:23], v[0:1], v[22:23], v[24:25]
	v_pk_fma_f32 v[4:5], v[0:1], v[4:5], v[26:27]
	global_load_dwordx2 v[76:77], v[32:33], off
	v_lshl_add_u64 v[32:33], v[32:33], 0, s[10:11]
	v_cvt_pk_bf16_f32 v30, v22, v23
	v_cvt_pk_bf16_f32 v31, v4, v5
	s_waitcnt vmcnt(30)
	global_store_dwordx2 v[34:35], v[30:31], off
	v_lshl_add_u64 v[34:35], v[34:35], 0, s[10:11]
	v_lshlrev_b32_e32 v24, 16, v78
	v_and_b32_e32 v25, 0xffff0000, v78
	v_lshlrev_b32_e32 v26, 16, v79
	v_and_b32_e32 v27, 0xffff0000, v79
	v_pk_fma_f32 v[22:23], v[0:1], v[22:23], v[24:25]
	v_pk_fma_f32 v[4:5], v[0:1], v[4:5], v[26:27]
	global_load_dwordx2 v[78:79], v[32:33], off
	v_lshl_add_u64 v[32:33], v[32:33], 0, s[10:11]
	v_cvt_pk_bf16_f32 v28, v22, v23
	v_cvt_pk_bf16_f32 v29, v4, v5
	s_waitcnt vmcnt(30)
	global_store_dwordx2 v[34:35], v[28:29], off
	v_lshl_add_u64 v[34:35], v[34:35], 0, s[10:11]
	v_lshlrev_b32_e32 v24, 16, v80
	v_and_b32_e32 v25, 0xffff0000, v80
	v_lshlrev_b32_e32 v26, 16, v81
	v_and_b32_e32 v27, 0xffff0000, v81
	v_pk_fma_f32 v[22:23], v[0:1], v[22:23], v[24:25]
	v_pk_fma_f32 v[4:5], v[0:1], v[4:5], v[26:27]
	global_load_dwordx2 v[80:81], v[32:33], off
	v_lshl_add_u64 v[32:33], v[32:33], 0, s[10:11]
	v_cvt_pk_bf16_f32 v30, v22, v23
	v_cvt_pk_bf16_f32 v31, v4, v5
	s_waitcnt vmcnt(30)
	global_store_dwordx2 v[34:35], v[30:31], off
	v_lshl_add_u64 v[34:35], v[34:35], 0, s[10:11]
	v_lshlrev_b32_e32 v24, 16, v82
	v_and_b32_e32 v25, 0xffff0000, v82
	v_lshlrev_b32_e32 v26, 16, v83
	v_and_b32_e32 v27, 0xffff0000, v83
	v_pk_fma_f32 v[22:23], v[0:1], v[22:23], v[24:25]
	v_pk_fma_f32 v[4:5], v[0:1], v[4:5], v[26:27]
	global_load_dwordx2 v[82:83], v[32:33], off
	v_lshl_add_u64 v[32:33], v[32:33], 0, s[10:11]
	v_cvt_pk_bf16_f32 v28, v22, v23
	v_cvt_pk_bf16_f32 v29, v4, v5
	s_waitcnt vmcnt(30)
	global_store_dwordx2 v[34:35], v[28:29], off
	v_lshl_add_u64 v[34:35], v[34:35], 0, s[10:11]
	v_lshlrev_b32_e32 v24, 16, v84
	v_and_b32_e32 v25, 0xffff0000, v84
	v_lshlrev_b32_e32 v26, 16, v85
	v_and_b32_e32 v27, 0xffff0000, v85
	v_pk_fma_f32 v[22:23], v[0:1], v[22:23], v[24:25]
	v_pk_fma_f32 v[4:5], v[0:1], v[4:5], v[26:27]
	global_load_dwordx2 v[84:85], v[32:33], off
	v_lshl_add_u64 v[32:33], v[32:33], 0, s[10:11]
	v_cvt_pk_bf16_f32 v30, v22, v23
	v_cvt_pk_bf16_f32 v31, v4, v5
	s_waitcnt vmcnt(30)
	global_store_dwordx2 v[34:35], v[30:31], off
	v_lshl_add_u64 v[34:35], v[34:35], 0, s[10:11]
	v_lshlrev_b32_e32 v24, 16, v86
	v_and_b32_e32 v25, 0xffff0000, v86
	v_lshlrev_b32_e32 v26, 16, v87
	v_and_b32_e32 v27, 0xffff0000, v87
	v_pk_fma_f32 v[22:23], v[0:1], v[22:23], v[24:25]
	v_pk_fma_f32 v[4:5], v[0:1], v[4:5], v[26:27]
	global_load_dwordx2 v[86:87], v[32:33], off
	v_lshl_add_u64 v[32:33], v[32:33], 0, s[10:11]
	v_cvt_pk_bf16_f32 v28, v22, v23
	v_cvt_pk_bf16_f32 v29, v4, v5
	s_waitcnt vmcnt(30)
	global_store_dwordx2 v[34:35], v[28:29], off
	v_lshl_add_u64 v[34:35], v[34:35], 0, s[10:11]
	v_lshlrev_b32_e32 v24, 16, v88
	v_and_b32_e32 v25, 0xffff0000, v88
	v_lshlrev_b32_e32 v26, 16, v89
	v_and_b32_e32 v27, 0xffff0000, v89
	v_pk_fma_f32 v[22:23], v[0:1], v[22:23], v[24:25]
	v_pk_fma_f32 v[4:5], v[0:1], v[4:5], v[26:27]
	global_load_dwordx2 v[88:89], v[32:33], off
	v_lshl_add_u64 v[32:33], v[32:33], 0, s[10:11]
	v_cvt_pk_bf16_f32 v30, v22, v23
	v_cvt_pk_bf16_f32 v31, v4, v5
	s_waitcnt vmcnt(30)
	global_store_dwordx2 v[34:35], v[30:31], off
	v_lshl_add_u64 v[34:35], v[34:35], 0, s[10:11]
	v_lshlrev_b32_e32 v24, 16, v90
	v_and_b32_e32 v25, 0xffff0000, v90
	v_lshlrev_b32_e32 v26, 16, v91
	v_and_b32_e32 v27, 0xffff0000, v91
	v_pk_fma_f32 v[22:23], v[0:1], v[22:23], v[24:25]
	v_pk_fma_f32 v[4:5], v[0:1], v[4:5], v[26:27]
	global_load_dwordx2 v[90:91], v[32:33], off
	v_lshl_add_u64 v[32:33], v[32:33], 0, s[10:11]
	v_cvt_pk_bf16_f32 v28, v22, v23
	v_cvt_pk_bf16_f32 v29, v4, v5
	s_waitcnt vmcnt(30)
	global_store_dwordx2 v[34:35], v[28:29], off
	v_lshl_add_u64 v[34:35], v[34:35], 0, s[10:11]
	v_lshlrev_b32_e32 v24, 16, v92
	v_and_b32_e32 v25, 0xffff0000, v92
	v_lshlrev_b32_e32 v26, 16, v93
	v_and_b32_e32 v27, 0xffff0000, v93
	v_pk_fma_f32 v[22:23], v[0:1], v[22:23], v[24:25]
	v_pk_fma_f32 v[4:5], v[0:1], v[4:5], v[26:27]
	global_load_dwordx2 v[92:93], v[32:33], off
	v_lshl_add_u64 v[32:33], v[32:33], 0, s[10:11]
	v_cvt_pk_bf16_f32 v30, v22, v23
	v_cvt_pk_bf16_f32 v31, v4, v5
	s_waitcnt vmcnt(30)
	global_store_dwordx2 v[34:35], v[30:31], off
	v_lshl_add_u64 v[34:35], v[34:35], 0, s[10:11]
	v_lshlrev_b32_e32 v24, 16, v94
	v_and_b32_e32 v25, 0xffff0000, v94
	v_lshlrev_b32_e32 v26, 16, v95
	v_and_b32_e32 v27, 0xffff0000, v95
	v_pk_fma_f32 v[22:23], v[0:1], v[22:23], v[24:25]
	v_pk_fma_f32 v[4:5], v[0:1], v[4:5], v[26:27]
	global_load_dwordx2 v[94:95], v[32:33], off
	v_lshl_add_u64 v[32:33], v[32:33], 0, s[10:11]
	v_cvt_pk_bf16_f32 v28, v22, v23
	v_cvt_pk_bf16_f32 v29, v4, v5
	s_waitcnt vmcnt(30)
	global_store_dwordx2 v[34:35], v[28:29], off
	v_lshl_add_u64 v[34:35], v[34:35], 0, s[10:11]
	v_lshlrev_b32_e32 v24, 16, v96
	v_and_b32_e32 v25, 0xffff0000, v96
	v_lshlrev_b32_e32 v26, 16, v97
	v_and_b32_e32 v27, 0xffff0000, v97
	v_pk_fma_f32 v[22:23], v[0:1], v[22:23], v[24:25]
	v_pk_fma_f32 v[4:5], v[0:1], v[4:5], v[26:27]
	global_load_dwordx2 v[96:97], v[32:33], off
	v_lshl_add_u64 v[32:33], v[32:33], 0, s[10:11]
	v_cvt_pk_bf16_f32 v30, v22, v23
	v_cvt_pk_bf16_f32 v31, v4, v5
	s_waitcnt vmcnt(30)
	global_store_dwordx2 v[34:35], v[30:31], off
	v_lshl_add_u64 v[34:35], v[34:35], 0, s[10:11]
	v_lshlrev_b32_e32 v24, 16, v98
	v_and_b32_e32 v25, 0xffff0000, v98
	v_lshlrev_b32_e32 v26, 16, v99
	v_and_b32_e32 v27, 0xffff0000, v99
	v_pk_fma_f32 v[22:23], v[0:1], v[22:23], v[24:25]
	v_pk_fma_f32 v[4:5], v[0:1], v[4:5], v[26:27]
	global_load_dwordx2 v[98:99], v[32:33], off
	v_lshl_add_u64 v[32:33], v[32:33], 0, s[10:11]
	v_cvt_pk_bf16_f32 v28, v22, v23
	v_cvt_pk_bf16_f32 v29, v4, v5
	s_waitcnt vmcnt(30)
	global_store_dwordx2 v[34:35], v[28:29], off
	v_lshl_add_u64 v[34:35], v[34:35], 0, s[10:11]
	v_lshlrev_b32_e32 v24, 16, v100
	v_and_b32_e32 v25, 0xffff0000, v100
	v_lshlrev_b32_e32 v26, 16, v101
	v_and_b32_e32 v27, 0xffff0000, v101
	v_pk_fma_f32 v[22:23], v[0:1], v[22:23], v[24:25]
	v_pk_fma_f32 v[4:5], v[0:1], v[4:5], v[26:27]
	global_load_dwordx2 v[100:101], v[32:33], off
	v_lshl_add_u64 v[32:33], v[32:33], 0, s[10:11]
	v_cvt_pk_bf16_f32 v30, v22, v23
	v_cvt_pk_bf16_f32 v31, v4, v5
	s_waitcnt vmcnt(30)
	global_store_dwordx2 v[34:35], v[30:31], off
	v_lshl_add_u64 v[34:35], v[34:35], 0, s[10:11]
	v_lshlrev_b32_e32 v24, 16, v102
	v_and_b32_e32 v25, 0xffff0000, v102
	v_lshlrev_b32_e32 v26, 16, v103
	v_and_b32_e32 v27, 0xffff0000, v103
	v_pk_fma_f32 v[22:23], v[0:1], v[22:23], v[24:25]
	v_pk_fma_f32 v[4:5], v[0:1], v[4:5], v[26:27]
	global_load_dwordx2 v[102:103], v[32:33], off
	v_lshl_add_u64 v[32:33], v[32:33], 0, s[10:11]
	v_cvt_pk_bf16_f32 v28, v22, v23
	v_cvt_pk_bf16_f32 v29, v4, v5
	s_waitcnt vmcnt(30)
	global_store_dwordx2 v[34:35], v[28:29], off
	v_lshl_add_u64 v[34:35], v[34:35], 0, s[10:11]
	v_lshlrev_b32_e32 v24, 16, v72
	v_and_b32_e32 v25, 0xffff0000, v72
	v_lshlrev_b32_e32 v26, 16, v73
	v_and_b32_e32 v27, 0xffff0000, v73
	v_pk_fma_f32 v[22:23], v[0:1], v[22:23], v[24:25]
	v_pk_fma_f32 v[4:5], v[0:1], v[4:5], v[26:27]
	global_load_dwordx2 v[72:73], v[32:33], off
	v_lshl_add_u64 v[32:33], v[32:33], 0, s[10:11]
	v_cvt_pk_bf16_f32 v30, v22, v23
	v_cvt_pk_bf16_f32 v31, v4, v5
	s_waitcnt vmcnt(30)
	global_store_dwordx2 v[34:35], v[30:31], off
	v_lshl_add_u64 v[34:35], v[34:35], 0, s[10:11]
	v_lshlrev_b32_e32 v24, 16, v74
	v_and_b32_e32 v25, 0xffff0000, v74
	v_lshlrev_b32_e32 v26, 16, v75
	v_and_b32_e32 v27, 0xffff0000, v75
	v_pk_fma_f32 v[22:23], v[0:1], v[22:23], v[24:25]
	v_pk_fma_f32 v[4:5], v[0:1], v[4:5], v[26:27]
	global_load_dwordx2 v[74:75], v[32:33], off
	v_lshl_add_u64 v[32:33], v[32:33], 0, s[10:11]
	v_cvt_pk_bf16_f32 v28, v22, v23
	v_cvt_pk_bf16_f32 v29, v4, v5
	s_waitcnt vmcnt(30)
	global_store_dwordx2 v[34:35], v[28:29], off
	v_lshl_add_u64 v[34:35], v[34:35], 0, s[10:11]
	v_lshlrev_b32_e32 v24, 16, v76
	v_and_b32_e32 v25, 0xffff0000, v76
	v_lshlrev_b32_e32 v26, 16, v77
	v_and_b32_e32 v27, 0xffff0000, v77
	v_pk_fma_f32 v[22:23], v[0:1], v[22:23], v[24:25]
	v_pk_fma_f32 v[4:5], v[0:1], v[4:5], v[26:27]
	global_load_dwordx2 v[76:77], v[32:33], off
	v_lshl_add_u64 v[32:33], v[32:33], 0, s[10:11]
	v_cvt_pk_bf16_f32 v30, v22, v23
	v_cvt_pk_bf16_f32 v31, v4, v5
	s_waitcnt vmcnt(30)
	global_store_dwordx2 v[34:35], v[30:31], off
	v_lshl_add_u64 v[34:35], v[34:35], 0, s[10:11]
	v_lshlrev_b32_e32 v24, 16, v78
	v_and_b32_e32 v25, 0xffff0000, v78
	v_lshlrev_b32_e32 v26, 16, v79
	v_and_b32_e32 v27, 0xffff0000, v79
	v_pk_fma_f32 v[22:23], v[0:1], v[22:23], v[24:25]
	v_pk_fma_f32 v[4:5], v[0:1], v[4:5], v[26:27]
	global_load_dwordx2 v[78:79], v[32:33], off
	v_lshl_add_u64 v[32:33], v[32:33], 0, s[10:11]
	v_cvt_pk_bf16_f32 v28, v22, v23
	v_cvt_pk_bf16_f32 v29, v4, v5
	s_waitcnt vmcnt(30)
	global_store_dwordx2 v[34:35], v[28:29], off
	v_lshl_add_u64 v[34:35], v[34:35], 0, s[10:11]
	v_lshlrev_b32_e32 v24, 16, v80
	v_and_b32_e32 v25, 0xffff0000, v80
	v_lshlrev_b32_e32 v26, 16, v81
	v_and_b32_e32 v27, 0xffff0000, v81
	v_pk_fma_f32 v[22:23], v[0:1], v[22:23], v[24:25]
	v_pk_fma_f32 v[4:5], v[0:1], v[4:5], v[26:27]
	global_load_dwordx2 v[80:81], v[32:33], off
	v_lshl_add_u64 v[32:33], v[32:33], 0, s[10:11]
	v_cvt_pk_bf16_f32 v30, v22, v23
	v_cvt_pk_bf16_f32 v31, v4, v5
	s_waitcnt vmcnt(30)
	global_store_dwordx2 v[34:35], v[30:31], off
	v_lshl_add_u64 v[34:35], v[34:35], 0, s[10:11]
	v_lshlrev_b32_e32 v24, 16, v82
	v_and_b32_e32 v25, 0xffff0000, v82
	v_lshlrev_b32_e32 v26, 16, v83
	v_and_b32_e32 v27, 0xffff0000, v83
	v_pk_fma_f32 v[22:23], v[0:1], v[22:23], v[24:25]
	v_pk_fma_f32 v[4:5], v[0:1], v[4:5], v[26:27]
	global_load_dwordx2 v[82:83], v[32:33], off
	v_lshl_add_u64 v[32:33], v[32:33], 0, s[10:11]
	v_cvt_pk_bf16_f32 v28, v22, v23
	v_cvt_pk_bf16_f32 v29, v4, v5
	s_waitcnt vmcnt(30)
	global_store_dwordx2 v[34:35], v[28:29], off
	v_lshl_add_u64 v[34:35], v[34:35], 0, s[10:11]
	v_lshlrev_b32_e32 v24, 16, v84
	v_and_b32_e32 v25, 0xffff0000, v84
	v_lshlrev_b32_e32 v26, 16, v85
	v_and_b32_e32 v27, 0xffff0000, v85
	v_pk_fma_f32 v[22:23], v[0:1], v[22:23], v[24:25]
	v_pk_fma_f32 v[4:5], v[0:1], v[4:5], v[26:27]
	global_load_dwordx2 v[84:85], v[32:33], off
	v_lshl_add_u64 v[32:33], v[32:33], 0, s[10:11]
	v_cvt_pk_bf16_f32 v30, v22, v23
	v_cvt_pk_bf16_f32 v31, v4, v5
	s_waitcnt vmcnt(30)
	global_store_dwordx2 v[34:35], v[30:31], off
	v_lshl_add_u64 v[34:35], v[34:35], 0, s[10:11]
	v_lshlrev_b32_e32 v24, 16, v86
	v_and_b32_e32 v25, 0xffff0000, v86
	v_lshlrev_b32_e32 v26, 16, v87
	v_and_b32_e32 v27, 0xffff0000, v87
	v_pk_fma_f32 v[22:23], v[0:1], v[22:23], v[24:25]
	v_pk_fma_f32 v[4:5], v[0:1], v[4:5], v[26:27]
	global_load_dwordx2 v[86:87], v[32:33], off
	v_lshl_add_u64 v[32:33], v[32:33], 0, s[10:11]
	v_cvt_pk_bf16_f32 v28, v22, v23
	v_cvt_pk_bf16_f32 v29, v4, v5
	s_waitcnt vmcnt(30)
	global_store_dwordx2 v[34:35], v[28:29], off
	v_lshl_add_u64 v[34:35], v[34:35], 0, s[10:11]
	v_lshlrev_b32_e32 v24, 16, v88
	v_and_b32_e32 v25, 0xffff0000, v88
	v_lshlrev_b32_e32 v26, 16, v89
	v_and_b32_e32 v27, 0xffff0000, v89
	v_pk_fma_f32 v[22:23], v[0:1], v[22:23], v[24:25]
	v_pk_fma_f32 v[4:5], v[0:1], v[4:5], v[26:27]
	global_load_dwordx2 v[88:89], v[32:33], off
	v_lshl_add_u64 v[32:33], v[32:33], 0, s[10:11]
	v_cvt_pk_bf16_f32 v30, v22, v23
	v_cvt_pk_bf16_f32 v31, v4, v5
	s_waitcnt vmcnt(30)
	global_store_dwordx2 v[34:35], v[30:31], off
	v_lshl_add_u64 v[34:35], v[34:35], 0, s[10:11]
	v_lshlrev_b32_e32 v24, 16, v90
	v_and_b32_e32 v25, 0xffff0000, v90
	v_lshlrev_b32_e32 v26, 16, v91
	v_and_b32_e32 v27, 0xffff0000, v91
	v_pk_fma_f32 v[22:23], v[0:1], v[22:23], v[24:25]
	v_pk_fma_f32 v[4:5], v[0:1], v[4:5], v[26:27]
	global_load_dwordx2 v[90:91], v[32:33], off
	v_lshl_add_u64 v[32:33], v[32:33], 0, s[10:11]
	v_cvt_pk_bf16_f32 v28, v22, v23
	v_cvt_pk_bf16_f32 v29, v4, v5
	s_waitcnt vmcnt(30)
	global_store_dwordx2 v[34:35], v[28:29], off
	v_lshl_add_u64 v[34:35], v[34:35], 0, s[10:11]
	v_lshlrev_b32_e32 v24, 16, v92
	v_and_b32_e32 v25, 0xffff0000, v92
	v_lshlrev_b32_e32 v26, 16, v93
	v_and_b32_e32 v27, 0xffff0000, v93
	v_pk_fma_f32 v[22:23], v[0:1], v[22:23], v[24:25]
	v_pk_fma_f32 v[4:5], v[0:1], v[4:5], v[26:27]
	global_load_dwordx2 v[92:93], v[32:33], off
	v_lshl_add_u64 v[32:33], v[32:33], 0, s[10:11]
	v_cvt_pk_bf16_f32 v30, v22, v23
	v_cvt_pk_bf16_f32 v31, v4, v5
	s_waitcnt vmcnt(30)
	global_store_dwordx2 v[34:35], v[30:31], off
	v_lshl_add_u64 v[34:35], v[34:35], 0, s[10:11]
	v_lshlrev_b32_e32 v24, 16, v94
	v_and_b32_e32 v25, 0xffff0000, v94
	v_lshlrev_b32_e32 v26, 16, v95
	v_and_b32_e32 v27, 0xffff0000, v95
	v_pk_fma_f32 v[22:23], v[0:1], v[22:23], v[24:25]
	v_pk_fma_f32 v[4:5], v[0:1], v[4:5], v[26:27]
	global_load_dwordx2 v[94:95], v[32:33], off
	v_lshl_add_u64 v[32:33], v[32:33], 0, s[10:11]
	v_cvt_pk_bf16_f32 v28, v22, v23
	v_cvt_pk_bf16_f32 v29, v4, v5
	s_waitcnt vmcnt(30)
	global_store_dwordx2 v[34:35], v[28:29], off
	v_lshl_add_u64 v[34:35], v[34:35], 0, s[10:11]
	v_lshlrev_b32_e32 v24, 16, v96
	v_and_b32_e32 v25, 0xffff0000, v96
	v_lshlrev_b32_e32 v26, 16, v97
	v_and_b32_e32 v27, 0xffff0000, v97
	v_pk_fma_f32 v[22:23], v[0:1], v[22:23], v[24:25]
	v_pk_fma_f32 v[4:5], v[0:1], v[4:5], v[26:27]
	global_load_dwordx2 v[96:97], v[32:33], off
	v_lshl_add_u64 v[32:33], v[32:33], 0, s[10:11]
	v_cvt_pk_bf16_f32 v30, v22, v23
	v_cvt_pk_bf16_f32 v31, v4, v5
	s_waitcnt vmcnt(30)
	global_store_dwordx2 v[34:35], v[30:31], off
	v_lshl_add_u64 v[34:35], v[34:35], 0, s[10:11]
	v_lshlrev_b32_e32 v24, 16, v98
	v_and_b32_e32 v25, 0xffff0000, v98
	v_lshlrev_b32_e32 v26, 16, v99
	v_and_b32_e32 v27, 0xffff0000, v99
	v_pk_fma_f32 v[22:23], v[0:1], v[22:23], v[24:25]
	v_pk_fma_f32 v[4:5], v[0:1], v[4:5], v[26:27]
	global_load_dwordx2 v[98:99], v[32:33], off
	v_lshl_add_u64 v[32:33], v[32:33], 0, s[10:11]
	v_cvt_pk_bf16_f32 v28, v22, v23
	v_cvt_pk_bf16_f32 v29, v4, v5
	s_waitcnt vmcnt(30)
	global_store_dwordx2 v[34:35], v[28:29], off
	v_lshl_add_u64 v[34:35], v[34:35], 0, s[10:11]
	v_lshlrev_b32_e32 v24, 16, v100
	v_and_b32_e32 v25, 0xffff0000, v100
	v_lshlrev_b32_e32 v26, 16, v101
	v_and_b32_e32 v27, 0xffff0000, v101
	v_pk_fma_f32 v[22:23], v[0:1], v[22:23], v[24:25]
	v_pk_fma_f32 v[4:5], v[0:1], v[4:5], v[26:27]
	global_load_dwordx2 v[100:101], v[32:33], off
	v_lshl_add_u64 v[32:33], v[32:33], 0, s[10:11]
	v_cvt_pk_bf16_f32 v30, v22, v23
	v_cvt_pk_bf16_f32 v31, v4, v5
	s_waitcnt vmcnt(30)
	global_store_dwordx2 v[34:35], v[30:31], off
	v_lshl_add_u64 v[34:35], v[34:35], 0, s[10:11]
	v_lshlrev_b32_e32 v24, 16, v102
	v_and_b32_e32 v25, 0xffff0000, v102
	v_lshlrev_b32_e32 v26, 16, v103
	v_and_b32_e32 v27, 0xffff0000, v103
	v_pk_fma_f32 v[22:23], v[0:1], v[22:23], v[24:25]
	v_pk_fma_f32 v[4:5], v[0:1], v[4:5], v[26:27]
	global_load_dwordx2 v[102:103], v[32:33], off
	v_lshl_add_u64 v[32:33], v[32:33], 0, s[10:11]
	v_cvt_pk_bf16_f32 v28, v22, v23
	v_cvt_pk_bf16_f32 v29, v4, v5
	s_waitcnt vmcnt(30)
	global_store_dwordx2 v[34:35], v[28:29], off
	v_lshl_add_u64 v[34:35], v[34:35], 0, s[10:11]
	v_lshlrev_b32_e32 v24, 16, v72
	v_and_b32_e32 v25, 0xffff0000, v72
	v_lshlrev_b32_e32 v26, 16, v73
	v_and_b32_e32 v27, 0xffff0000, v73
	v_pk_fma_f32 v[22:23], v[0:1], v[22:23], v[24:25]
	v_pk_fma_f32 v[4:5], v[0:1], v[4:5], v[26:27]
	global_load_dwordx2 v[72:73], v[32:33], off
	v_lshl_add_u64 v[32:33], v[32:33], 0, s[10:11]
	v_cvt_pk_bf16_f32 v30, v22, v23
	v_cvt_pk_bf16_f32 v31, v4, v5
	s_waitcnt vmcnt(30)
	global_store_dwordx2 v[34:35], v[30:31], off
	v_lshl_add_u64 v[34:35], v[34:35], 0, s[10:11]
	v_lshlrev_b32_e32 v24, 16, v74
	v_and_b32_e32 v25, 0xffff0000, v74
	v_lshlrev_b32_e32 v26, 16, v75
	v_and_b32_e32 v27, 0xffff0000, v75
	v_pk_fma_f32 v[22:23], v[0:1], v[22:23], v[24:25]
	v_pk_fma_f32 v[4:5], v[0:1], v[4:5], v[26:27]
	global_load_dwordx2 v[74:75], v[32:33], off
	v_lshl_add_u64 v[32:33], v[32:33], 0, s[10:11]
	v_cvt_pk_bf16_f32 v28, v22, v23
	v_cvt_pk_bf16_f32 v29, v4, v5
	s_waitcnt vmcnt(30)
	global_store_dwordx2 v[34:35], v[28:29], off
	v_lshl_add_u64 v[34:35], v[34:35], 0, s[10:11]
	v_lshlrev_b32_e32 v24, 16, v76
	v_and_b32_e32 v25, 0xffff0000, v76
	v_lshlrev_b32_e32 v26, 16, v77
	v_and_b32_e32 v27, 0xffff0000, v77
	v_pk_fma_f32 v[22:23], v[0:1], v[22:23], v[24:25]
	v_pk_fma_f32 v[4:5], v[0:1], v[4:5], v[26:27]
	global_load_dwordx2 v[76:77], v[32:33], off
	v_lshl_add_u64 v[32:33], v[32:33], 0, s[10:11]
	v_cvt_pk_bf16_f32 v30, v22, v23
	v_cvt_pk_bf16_f32 v31, v4, v5
	s_waitcnt vmcnt(30)
	global_store_dwordx2 v[34:35], v[30:31], off
	v_lshl_add_u64 v[34:35], v[34:35], 0, s[10:11]
	v_lshlrev_b32_e32 v24, 16, v78
	v_and_b32_e32 v25, 0xffff0000, v78
	v_lshlrev_b32_e32 v26, 16, v79
	v_and_b32_e32 v27, 0xffff0000, v79
	v_pk_fma_f32 v[22:23], v[0:1], v[22:23], v[24:25]
	v_pk_fma_f32 v[4:5], v[0:1], v[4:5], v[26:27]
	global_load_dwordx2 v[78:79], v[32:33], off
	v_lshl_add_u64 v[32:33], v[32:33], 0, s[10:11]
	v_cvt_pk_bf16_f32 v28, v22, v23
	v_cvt_pk_bf16_f32 v29, v4, v5
	s_waitcnt vmcnt(30)
	global_store_dwordx2 v[34:35], v[28:29], off
	v_lshl_add_u64 v[34:35], v[34:35], 0, s[10:11]
	v_lshlrev_b32_e32 v24, 16, v80
	v_and_b32_e32 v25, 0xffff0000, v80
	v_lshlrev_b32_e32 v26, 16, v81
	v_and_b32_e32 v27, 0xffff0000, v81
	v_pk_fma_f32 v[22:23], v[0:1], v[22:23], v[24:25]
	v_pk_fma_f32 v[4:5], v[0:1], v[4:5], v[26:27]
	global_load_dwordx2 v[80:81], v[32:33], off
	v_lshl_add_u64 v[32:33], v[32:33], 0, s[10:11]
	v_cvt_pk_bf16_f32 v30, v22, v23
	v_cvt_pk_bf16_f32 v31, v4, v5
	s_waitcnt vmcnt(30)
	global_store_dwordx2 v[34:35], v[30:31], off
	v_lshl_add_u64 v[34:35], v[34:35], 0, s[10:11]
	v_lshlrev_b32_e32 v24, 16, v82
	v_and_b32_e32 v25, 0xffff0000, v82
	v_lshlrev_b32_e32 v26, 16, v83
	v_and_b32_e32 v27, 0xffff0000, v83
	v_pk_fma_f32 v[22:23], v[0:1], v[22:23], v[24:25]
	v_pk_fma_f32 v[4:5], v[0:1], v[4:5], v[26:27]
	global_load_dwordx2 v[82:83], v[32:33], off
	v_lshl_add_u64 v[32:33], v[32:33], 0, s[10:11]
	v_cvt_pk_bf16_f32 v28, v22, v23
	v_cvt_pk_bf16_f32 v29, v4, v5
	s_waitcnt vmcnt(30)
	global_store_dwordx2 v[34:35], v[28:29], off
	v_lshl_add_u64 v[34:35], v[34:35], 0, s[10:11]
	v_lshlrev_b32_e32 v24, 16, v84
	v_and_b32_e32 v25, 0xffff0000, v84
	v_lshlrev_b32_e32 v26, 16, v85
	v_and_b32_e32 v27, 0xffff0000, v85
	v_pk_fma_f32 v[22:23], v[0:1], v[22:23], v[24:25]
	v_pk_fma_f32 v[4:5], v[0:1], v[4:5], v[26:27]
	global_load_dwordx2 v[84:85], v[32:33], off
	v_lshl_add_u64 v[32:33], v[32:33], 0, s[10:11]
	v_cvt_pk_bf16_f32 v30, v22, v23
	v_cvt_pk_bf16_f32 v31, v4, v5
	s_waitcnt vmcnt(30)
	global_store_dwordx2 v[34:35], v[30:31], off
	v_lshl_add_u64 v[34:35], v[34:35], 0, s[10:11]
	v_lshlrev_b32_e32 v24, 16, v86
	v_and_b32_e32 v25, 0xffff0000, v86
	v_lshlrev_b32_e32 v26, 16, v87
	v_and_b32_e32 v27, 0xffff0000, v87
	v_pk_fma_f32 v[22:23], v[0:1], v[22:23], v[24:25]
	v_pk_fma_f32 v[4:5], v[0:1], v[4:5], v[26:27]
	global_load_dwordx2 v[86:87], v[32:33], off
	v_lshl_add_u64 v[32:33], v[32:33], 0, s[10:11]
	v_cvt_pk_bf16_f32 v28, v22, v23
	v_cvt_pk_bf16_f32 v29, v4, v5
	s_waitcnt vmcnt(30)
	global_store_dwordx2 v[34:35], v[28:29], off
	v_lshl_add_u64 v[34:35], v[34:35], 0, s[10:11]
	v_lshlrev_b32_e32 v24, 16, v88
	v_and_b32_e32 v25, 0xffff0000, v88
	v_lshlrev_b32_e32 v26, 16, v89
	v_and_b32_e32 v27, 0xffff0000, v89
	v_pk_fma_f32 v[22:23], v[0:1], v[22:23], v[24:25]
	v_pk_fma_f32 v[4:5], v[0:1], v[4:5], v[26:27]
	global_load_dwordx2 v[88:89], v[32:33], off
	v_lshl_add_u64 v[32:33], v[32:33], 0, s[10:11]
	v_cvt_pk_bf16_f32 v30, v22, v23
	v_cvt_pk_bf16_f32 v31, v4, v5
	s_waitcnt vmcnt(30)
	global_store_dwordx2 v[34:35], v[30:31], off
	v_lshl_add_u64 v[34:35], v[34:35], 0, s[10:11]
	v_lshlrev_b32_e32 v24, 16, v90
	v_and_b32_e32 v25, 0xffff0000, v90
	v_lshlrev_b32_e32 v26, 16, v91
	v_and_b32_e32 v27, 0xffff0000, v91
	v_pk_fma_f32 v[22:23], v[0:1], v[22:23], v[24:25]
	v_pk_fma_f32 v[4:5], v[0:1], v[4:5], v[26:27]
	global_load_dwordx2 v[90:91], v[32:33], off
	v_lshl_add_u64 v[32:33], v[32:33], 0, s[10:11]
	v_cvt_pk_bf16_f32 v28, v22, v23
	v_cvt_pk_bf16_f32 v29, v4, v5
	s_waitcnt vmcnt(30)
	global_store_dwordx2 v[34:35], v[28:29], off
	v_lshl_add_u64 v[34:35], v[34:35], 0, s[10:11]
	v_lshlrev_b32_e32 v24, 16, v92
	v_and_b32_e32 v25, 0xffff0000, v92
	v_lshlrev_b32_e32 v26, 16, v93
	v_and_b32_e32 v27, 0xffff0000, v93
	v_pk_fma_f32 v[22:23], v[0:1], v[22:23], v[24:25]
	v_pk_fma_f32 v[4:5], v[0:1], v[4:5], v[26:27]
	global_load_dwordx2 v[92:93], v[32:33], off
	v_lshl_add_u64 v[32:33], v[32:33], 0, s[10:11]
	v_cvt_pk_bf16_f32 v30, v22, v23
	v_cvt_pk_bf16_f32 v31, v4, v5
	s_waitcnt vmcnt(30)
	global_store_dwordx2 v[34:35], v[30:31], off
	v_lshl_add_u64 v[34:35], v[34:35], 0, s[10:11]
	v_lshlrev_b32_e32 v24, 16, v94
	v_and_b32_e32 v25, 0xffff0000, v94
	v_lshlrev_b32_e32 v26, 16, v95
	v_and_b32_e32 v27, 0xffff0000, v95
	v_pk_fma_f32 v[22:23], v[0:1], v[22:23], v[24:25]
	v_pk_fma_f32 v[4:5], v[0:1], v[4:5], v[26:27]
	global_load_dwordx2 v[94:95], v[32:33], off
	v_lshl_add_u64 v[32:33], v[32:33], 0, s[10:11]
	v_cvt_pk_bf16_f32 v28, v22, v23
	v_cvt_pk_bf16_f32 v29, v4, v5
	s_waitcnt vmcnt(30)
	global_store_dwordx2 v[34:35], v[28:29], off
	v_lshl_add_u64 v[34:35], v[34:35], 0, s[10:11]
	v_lshlrev_b32_e32 v24, 16, v96
	v_and_b32_e32 v25, 0xffff0000, v96
	v_lshlrev_b32_e32 v26, 16, v97
	v_and_b32_e32 v27, 0xffff0000, v97
	v_pk_fma_f32 v[22:23], v[0:1], v[22:23], v[24:25]
	v_pk_fma_f32 v[4:5], v[0:1], v[4:5], v[26:27]
	global_load_dwordx2 v[96:97], v[32:33], off
	v_lshl_add_u64 v[32:33], v[32:33], 0, s[10:11]
	v_cvt_pk_bf16_f32 v30, v22, v23
	v_cvt_pk_bf16_f32 v31, v4, v5
	s_waitcnt vmcnt(30)
	global_store_dwordx2 v[34:35], v[30:31], off
	v_lshl_add_u64 v[34:35], v[34:35], 0, s[10:11]
	v_lshlrev_b32_e32 v24, 16, v98
	v_and_b32_e32 v25, 0xffff0000, v98
	v_lshlrev_b32_e32 v26, 16, v99
	v_and_b32_e32 v27, 0xffff0000, v99
	v_pk_fma_f32 v[22:23], v[0:1], v[22:23], v[24:25]
	v_pk_fma_f32 v[4:5], v[0:1], v[4:5], v[26:27]
	global_load_dwordx2 v[98:99], v[32:33], off
	v_lshl_add_u64 v[32:33], v[32:33], 0, s[10:11]
	v_cvt_pk_bf16_f32 v28, v22, v23
	v_cvt_pk_bf16_f32 v29, v4, v5
	s_waitcnt vmcnt(30)
	global_store_dwordx2 v[34:35], v[28:29], off
	v_lshl_add_u64 v[34:35], v[34:35], 0, s[10:11]
	v_lshlrev_b32_e32 v24, 16, v100
	v_and_b32_e32 v25, 0xffff0000, v100
	v_lshlrev_b32_e32 v26, 16, v101
	v_and_b32_e32 v27, 0xffff0000, v101
	v_pk_fma_f32 v[22:23], v[0:1], v[22:23], v[24:25]
	v_pk_fma_f32 v[4:5], v[0:1], v[4:5], v[26:27]
	global_load_dwordx2 v[100:101], v[32:33], off
	v_lshl_add_u64 v[32:33], v[32:33], 0, s[10:11]
	v_cvt_pk_bf16_f32 v30, v22, v23
	v_cvt_pk_bf16_f32 v31, v4, v5
	s_waitcnt vmcnt(30)
	global_store_dwordx2 v[34:35], v[30:31], off
	v_lshl_add_u64 v[34:35], v[34:35], 0, s[10:11]
	v_lshlrev_b32_e32 v24, 16, v102
	v_and_b32_e32 v25, 0xffff0000, v102
	v_lshlrev_b32_e32 v26, 16, v103
	v_and_b32_e32 v27, 0xffff0000, v103
	v_pk_fma_f32 v[22:23], v[0:1], v[22:23], v[24:25]
	v_pk_fma_f32 v[4:5], v[0:1], v[4:5], v[26:27]
	global_load_dwordx2 v[102:103], v[32:33], off
	v_lshl_add_u64 v[32:33], v[32:33], 0, s[10:11]
	v_cvt_pk_bf16_f32 v28, v22, v23
	v_cvt_pk_bf16_f32 v29, v4, v5
	s_waitcnt vmcnt(30)
	global_store_dwordx2 v[34:35], v[28:29], off
	v_lshl_add_u64 v[34:35], v[34:35], 0, s[10:11]
	v_lshlrev_b32_e32 v24, 16, v72
	v_and_b32_e32 v25, 0xffff0000, v72
	v_lshlrev_b32_e32 v26, 16, v73
	v_and_b32_e32 v27, 0xffff0000, v73
	v_pk_fma_f32 v[22:23], v[0:1], v[22:23], v[24:25]
	v_pk_fma_f32 v[4:5], v[0:1], v[4:5], v[26:27]
	v_cvt_pk_bf16_f32 v30, v22, v23
	v_cvt_pk_bf16_f32 v31, v4, v5
	s_waitcnt vmcnt(29)
	global_store_dwordx2 v[34:35], v[30:31], off
	v_lshl_add_u64 v[34:35], v[34:35], 0, s[10:11]
	v_lshlrev_b32_e32 v24, 16, v74
	v_and_b32_e32 v25, 0xffff0000, v74
	v_lshlrev_b32_e32 v26, 16, v75
	v_and_b32_e32 v27, 0xffff0000, v75
	v_pk_fma_f32 v[22:23], v[0:1], v[22:23], v[24:25]
	v_pk_fma_f32 v[4:5], v[0:1], v[4:5], v[26:27]
	v_cvt_pk_bf16_f32 v28, v22, v23
	v_cvt_pk_bf16_f32 v29, v4, v5
	s_waitcnt vmcnt(28)
	global_store_dwordx2 v[34:35], v[28:29], off
	v_lshl_add_u64 v[34:35], v[34:35], 0, s[10:11]
	v_lshlrev_b32_e32 v24, 16, v76
	v_and_b32_e32 v25, 0xffff0000, v76
	v_lshlrev_b32_e32 v26, 16, v77
	v_and_b32_e32 v27, 0xffff0000, v77
	v_pk_fma_f32 v[22:23], v[0:1], v[22:23], v[24:25]
	v_pk_fma_f32 v[4:5], v[0:1], v[4:5], v[26:27]
	v_cvt_pk_bf16_f32 v30, v22, v23
	v_cvt_pk_bf16_f32 v31, v4, v5
	s_waitcnt vmcnt(27)
	global_store_dwordx2 v[34:35], v[30:31], off
	v_lshl_add_u64 v[34:35], v[34:35], 0, s[10:11]
	v_lshlrev_b32_e32 v24, 16, v78
	v_and_b32_e32 v25, 0xffff0000, v78
	v_lshlrev_b32_e32 v26, 16, v79
	v_and_b32_e32 v27, 0xffff0000, v79
	v_pk_fma_f32 v[22:23], v[0:1], v[22:23], v[24:25]
	v_pk_fma_f32 v[4:5], v[0:1], v[4:5], v[26:27]
	v_cvt_pk_bf16_f32 v28, v22, v23
	v_cvt_pk_bf16_f32 v29, v4, v5
	s_waitcnt vmcnt(26)
	global_store_dwordx2 v[34:35], v[28:29], off
	v_lshl_add_u64 v[34:35], v[34:35], 0, s[10:11]
	v_lshlrev_b32_e32 v24, 16, v80
	v_and_b32_e32 v25, 0xffff0000, v80
	v_lshlrev_b32_e32 v26, 16, v81
	v_and_b32_e32 v27, 0xffff0000, v81
	v_pk_fma_f32 v[22:23], v[0:1], v[22:23], v[24:25]
	v_pk_fma_f32 v[4:5], v[0:1], v[4:5], v[26:27]
	v_cvt_pk_bf16_f32 v30, v22, v23
	v_cvt_pk_bf16_f32 v31, v4, v5
	s_waitcnt vmcnt(25)
	global_store_dwordx2 v[34:35], v[30:31], off
	v_lshl_add_u64 v[34:35], v[34:35], 0, s[10:11]
	v_lshlrev_b32_e32 v24, 16, v82
	v_and_b32_e32 v25, 0xffff0000, v82
	v_lshlrev_b32_e32 v26, 16, v83
	v_and_b32_e32 v27, 0xffff0000, v83
	v_pk_fma_f32 v[22:23], v[0:1], v[22:23], v[24:25]
	v_pk_fma_f32 v[4:5], v[0:1], v[4:5], v[26:27]
	v_cvt_pk_bf16_f32 v28, v22, v23
	v_cvt_pk_bf16_f32 v29, v4, v5
	s_waitcnt vmcnt(24)
	global_store_dwordx2 v[34:35], v[28:29], off
	v_lshl_add_u64 v[34:35], v[34:35], 0, s[10:11]
	v_lshlrev_b32_e32 v24, 16, v84
	v_and_b32_e32 v25, 0xffff0000, v84
	v_lshlrev_b32_e32 v26, 16, v85
	v_and_b32_e32 v27, 0xffff0000, v85
	v_pk_fma_f32 v[22:23], v[0:1], v[22:23], v[24:25]
	v_pk_fma_f32 v[4:5], v[0:1], v[4:5], v[26:27]
	v_cvt_pk_bf16_f32 v30, v22, v23
	v_cvt_pk_bf16_f32 v31, v4, v5
	s_waitcnt vmcnt(23)
	global_store_dwordx2 v[34:35], v[30:31], off
	v_lshl_add_u64 v[34:35], v[34:35], 0, s[10:11]
	v_lshlrev_b32_e32 v24, 16, v86
	v_and_b32_e32 v25, 0xffff0000, v86
	v_lshlrev_b32_e32 v26, 16, v87
	v_and_b32_e32 v27, 0xffff0000, v87
	v_pk_fma_f32 v[22:23], v[0:1], v[22:23], v[24:25]
	v_pk_fma_f32 v[4:5], v[0:1], v[4:5], v[26:27]
	v_cvt_pk_bf16_f32 v28, v22, v23
	v_cvt_pk_bf16_f32 v29, v4, v5
	s_waitcnt vmcnt(22)
	global_store_dwordx2 v[34:35], v[28:29], off
	v_lshl_add_u64 v[34:35], v[34:35], 0, s[10:11]
	v_lshlrev_b32_e32 v24, 16, v88
	v_and_b32_e32 v25, 0xffff0000, v88
	v_lshlrev_b32_e32 v26, 16, v89
	v_and_b32_e32 v27, 0xffff0000, v89
	v_pk_fma_f32 v[22:23], v[0:1], v[22:23], v[24:25]
	v_pk_fma_f32 v[4:5], v[0:1], v[4:5], v[26:27]
	v_cvt_pk_bf16_f32 v30, v22, v23
	v_cvt_pk_bf16_f32 v31, v4, v5
	s_waitcnt vmcnt(21)
	global_store_dwordx2 v[34:35], v[30:31], off
	v_lshl_add_u64 v[34:35], v[34:35], 0, s[10:11]
	v_lshlrev_b32_e32 v24, 16, v90
	v_and_b32_e32 v25, 0xffff0000, v90
	v_lshlrev_b32_e32 v26, 16, v91
	v_and_b32_e32 v27, 0xffff0000, v91
	v_pk_fma_f32 v[22:23], v[0:1], v[22:23], v[24:25]
	v_pk_fma_f32 v[4:5], v[0:1], v[4:5], v[26:27]
	v_cvt_pk_bf16_f32 v28, v22, v23
	v_cvt_pk_bf16_f32 v29, v4, v5
	s_waitcnt vmcnt(20)
	global_store_dwordx2 v[34:35], v[28:29], off
	v_lshl_add_u64 v[34:35], v[34:35], 0, s[10:11]
	v_lshlrev_b32_e32 v24, 16, v92
	v_and_b32_e32 v25, 0xffff0000, v92
	v_lshlrev_b32_e32 v26, 16, v93
	v_and_b32_e32 v27, 0xffff0000, v93
	v_pk_fma_f32 v[22:23], v[0:1], v[22:23], v[24:25]
	v_pk_fma_f32 v[4:5], v[0:1], v[4:5], v[26:27]
	v_cvt_pk_bf16_f32 v30, v22, v23
	v_cvt_pk_bf16_f32 v31, v4, v5
	s_waitcnt vmcnt(19)
	global_store_dwordx2 v[34:35], v[30:31], off
	v_lshl_add_u64 v[34:35], v[34:35], 0, s[10:11]
	v_lshlrev_b32_e32 v24, 16, v94
	v_and_b32_e32 v25, 0xffff0000, v94
	v_lshlrev_b32_e32 v26, 16, v95
	v_and_b32_e32 v27, 0xffff0000, v95
	v_pk_fma_f32 v[22:23], v[0:1], v[22:23], v[24:25]
	v_pk_fma_f32 v[4:5], v[0:1], v[4:5], v[26:27]
	v_cvt_pk_bf16_f32 v28, v22, v23
	v_cvt_pk_bf16_f32 v29, v4, v5
	s_waitcnt vmcnt(18)
	global_store_dwordx2 v[34:35], v[28:29], off
	v_lshl_add_u64 v[34:35], v[34:35], 0, s[10:11]
	v_lshlrev_b32_e32 v24, 16, v96
	v_and_b32_e32 v25, 0xffff0000, v96
	v_lshlrev_b32_e32 v26, 16, v97
	v_and_b32_e32 v27, 0xffff0000, v97
	v_pk_fma_f32 v[22:23], v[0:1], v[22:23], v[24:25]
	v_pk_fma_f32 v[4:5], v[0:1], v[4:5], v[26:27]
	v_cvt_pk_bf16_f32 v30, v22, v23
	v_cvt_pk_bf16_f32 v31, v4, v5
	s_waitcnt vmcnt(17)
	global_store_dwordx2 v[34:35], v[30:31], off
	v_lshl_add_u64 v[34:35], v[34:35], 0, s[10:11]
	v_lshlrev_b32_e32 v24, 16, v98
	v_and_b32_e32 v25, 0xffff0000, v98
	v_lshlrev_b32_e32 v26, 16, v99
	v_and_b32_e32 v27, 0xffff0000, v99
	v_pk_fma_f32 v[22:23], v[0:1], v[22:23], v[24:25]
	v_pk_fma_f32 v[4:5], v[0:1], v[4:5], v[26:27]
	v_cvt_pk_bf16_f32 v28, v22, v23
	v_cvt_pk_bf16_f32 v29, v4, v5
	s_waitcnt vmcnt(16)
	global_store_dwordx2 v[34:35], v[28:29], off
	v_lshl_add_u64 v[34:35], v[34:35], 0, s[10:11]
	v_lshlrev_b32_e32 v24, 16, v100
	v_and_b32_e32 v25, 0xffff0000, v100
	v_lshlrev_b32_e32 v26, 16, v101
	v_and_b32_e32 v27, 0xffff0000, v101
	v_pk_fma_f32 v[22:23], v[0:1], v[22:23], v[24:25]
	v_pk_fma_f32 v[4:5], v[0:1], v[4:5], v[26:27]
	v_cvt_pk_bf16_f32 v30, v22, v23
	v_cvt_pk_bf16_f32 v31, v4, v5
	s_waitcnt vmcnt(15)
	global_store_dwordx2 v[34:35], v[30:31], off
	v_lshl_add_u64 v[34:35], v[34:35], 0, s[10:11]
	v_lshlrev_b32_e32 v24, 16, v102
	v_and_b32_e32 v25, 0xffff0000, v102
	v_lshlrev_b32_e32 v26, 16, v103
	v_and_b32_e32 v27, 0xffff0000, v103
	v_pk_fma_f32 v[22:23], v[0:1], v[22:23], v[24:25]
	v_pk_fma_f32 v[4:5], v[0:1], v[4:5], v[26:27]

.LBB0_538:
	s_mov_b32 s10, 0xfff58000
	s_mov_b32 s11, -1
	v_lshl_add_u64 v[116:117], v[34:35], 0, s[10:11]
	v_lshl_add_u64 v[118:119], v[34:35], 0, s[10:11]
	s_mov_b32 s100, 0xffffc800
	s_mov_b32 s101, -1
	v_lshl_add_u64 v[120:121], v[32:33], 0, s[100:101]
	s_nop 0
	s_mov_b64 s[10:11], 0x18000
	s_mov_b64 s[100:101], 0x1000
	global_load_dwordx2 v[36:37], v[116:117], off
	global_load_dwordx4 v[0:3], v[120:121], off
	v_lshl_add_u64 v[116:117], v[116:117], 0, s[10:11]
	global_load_dwordx2 v[38:39], v[116:117], off
	global_load_dwordx4 v[4:7], v[120:121], off offset:2048
	v_lshl_add_u64 v[116:117], v[116:117], 0, s[10:11]
	v_lshl_add_u64 v[120:121], v[120:121], 0, s[100:101]
	global_load_dwordx2 v[40:41], v[116:117], off
	global_load_dwordx4 v[8:11], v[120:121], off
	v_lshl_add_u64 v[116:117], v[116:117], 0, s[10:11]
	global_load_dwordx2 v[42:43], v[116:117], off
	global_load_dwordx4 v[12:15], v[120:121], off offset:2048
	v_lshl_add_u64 v[116:117], v[116:117], 0, s[10:11]
	v_lshl_add_u64 v[120:121], v[120:121], 0, s[100:101]
	global_load_dwordx2 v[44:45], v[116:117], off
	global_load_dwordx4 v[16:19], v[120:121], off
	v_lshl_add_u64 v[116:117], v[116:117], 0, s[10:11]
	global_load_dwordx2 v[46:47], v[116:117], off
	global_load_dwordx4 v[20:23], v[120:121], off offset:2048
	v_lshl_add_u64 v[116:117], v[116:117], 0, s[10:11]
	v_lshl_add_u64 v[120:121], v[120:121], 0, s[100:101]
	global_load_dwordx2 v[48:49], v[116:117], off
	global_load_dwordx4 v[24:27], v[120:121], off
	v_lshl_add_u64 v[116:117], v[116:117], 0, s[10:11]
	global_load_dwordx2 v[50:51], v[116:117], off
	global_load_dwordx4 v[28:31], v[120:121], off offset:2048
	v_lshl_add_u64 v[116:117], v[116:117], 0, s[10:11]
	v_lshl_add_u64 v[120:121], v[120:121], 0, s[100:101]
	global_load_dwordx2 v[52:53], v[116:117], off
	global_load_dwordx4 v[72:75], v[120:121], off
	v_lshl_add_u64 v[116:117], v[116:117], 0, s[10:11]
	global_load_dwordx2 v[54:55], v[116:117], off
	global_load_dwordx4 v[76:79], v[120:121], off offset:2048
	v_lshl_add_u64 v[116:117], v[116:117], 0, s[10:11]
	v_lshl_add_u64 v[120:121], v[120:121], 0, s[100:101]
	global_load_dwordx2 v[56:57], v[116:117], off
	global_load_dwordx4 v[80:83], v[120:121], off
	v_lshl_add_u64 v[116:117], v[116:117], 0, s[10:11]
	global_load_dwordx2 v[58:59], v[116:117], off
	global_load_dwordx4 v[84:87], v[120:121], off offset:2048
	v_lshl_add_u64 v[116:117], v[116:117], 0, s[10:11]
	v_lshl_add_u64 v[120:121], v[120:121], 0, s[100:101]
	global_load_dwordx2 v[104:105], v[116:117], off
	global_load_dwordx4 v[88:91], v[120:121], off
	v_lshl_add_u64 v[116:117], v[116:117], 0, s[10:11]
	global_load_dwordx2 v[106:107], v[116:117], off
	global_load_dwordx4 v[92:95], v[120:121], off offset:2048
	v_lshl_add_u64 v[116:117], v[116:117], 0, s[10:11]
	v_lshl_add_u64 v[120:121], v[120:121], 0, s[100:101]
	global_load_dwordx2 v[108:109], v[116:117], off
	global_load_dwordx4 v[96:99], v[120:121], off
	v_lshl_add_u64 v[116:117], v[116:117], 0, s[10:11]
	global_load_dwordx2 v[110:111], v[116:117], off
	global_load_dwordx4 v[100:103], v[120:121], off offset:2048
	v_lshl_add_u64 v[116:117], v[116:117], 0, s[10:11]
	v_lshl_add_u64 v[120:121], v[120:121], 0, s[100:101]
	v_cvt_pk_bf16_f32 v112, v60, v61
	v_cvt_pk_bf16_f32 v113, v62, v63
	s_waitcnt vmcnt(30)
	global_store_dwordx2 v[118:119], v[112:113], off
	v_lshl_add_u64 v[118:119], v[118:119], 0, s[10:11]
	v_mul_f32_e32 v64, 0x3fb8aa3b, v0
	v_mul_f32_e32 v65, 0x3fb8aa3b, v1
	v_mul_f32_e32 v66, 0x3fb8aa3b, v2
	v_mul_f32_e32 v67, 0x3fb8aa3b, v3
	v_exp_f32_e32 v64, v64
	v_exp_f32_e32 v65, v65
	v_exp_f32_e32 v66, v66
	v_exp_f32_e32 v67, v67
	v_lshlrev_b32_e32 v68, 16, v36
	v_and_b32_e32 v69, 0xffff0000, v36
	v_lshlrev_b32_e32 v70, 16, v37
	v_and_b32_e32 v71, 0xffff0000, v37
	v_pk_fma_f32 v[60:61], v[60:61], v[64:65], v[68:69]
	v_pk_fma_f32 v[62:63], v[62:63], v[66:67], v[70:71]
	global_load_dwordx2 v[36:37], v[116:117], off
	global_load_dwordx4 v[0:3], v[120:121], off
	v_lshl_add_u64 v[116:117], v[116:117], 0, s[10:11]
	v_cvt_pk_bf16_f32 v114, v60, v61
	v_cvt_pk_bf16_f32 v115, v62, v63
	s_waitcnt vmcnt(31)
	global_store_dwordx2 v[118:119], v[114:115], off
	v_lshl_add_u64 v[118:119], v[118:119], 0, s[10:11]
	v_mul_f32_e32 v64, 0x3fb8aa3b, v4
	v_mul_f32_e32 v65, 0x3fb8aa3b, v5
	v_mul_f32_e32 v66, 0x3fb8aa3b, v6
	v_mul_f32_e32 v67, 0x3fb8aa3b, v7
	v_exp_f32_e32 v64, v64
	v_exp_f32_e32 v65, v65
	v_exp_f32_e32 v66, v66
	v_exp_f32_e32 v67, v67
	v_lshlrev_b32_e32 v68, 16, v38
	v_and_b32_e32 v69, 0xffff0000, v38
	v_lshlrev_b32_e32 v70, 16, v39
	v_and_b32_e32 v71, 0xffff0000, v39
	v_pk_fma_f32 v[60:61], v[60:61], v[64:65], v[68:69]
	v_pk_fma_f32 v[62:63], v[62:63], v[66:67], v[70:71]
	global_load_dwordx2 v[38:39], v[116:117], off
	global_load_dwordx4 v[4:7], v[120:121], off offset:2048
	v_lshl_add_u64 v[116:117], v[116:117], 0, s[10:11]
	v_lshl_add_u64 v[120:121], v[120:121], 0, s[100:101]
	v_cvt_pk_bf16_f32 v112, v60, v61
	v_cvt_pk_bf16_f32 v113, v62, v63
	s_waitcnt vmcnt(32)
	global_store_dwordx2 v[118:119], v[112:113], off
	v_lshl_add_u64 v[118:119], v[118:119], 0, s[10:11]
	v_mul_f32_e32 v64, 0x3fb8aa3b, v8
	v_mul_f32_e32 v65, 0x3fb8aa3b, v9
	v_mul_f32_e32 v66, 0x3fb8aa3b, v10
	v_mul_f32_e32 v67, 0x3fb8aa3b, v11
	v_exp_f32_e32 v64, v64
	v_exp_f32_e32 v65, v65
	v_exp_f32_e32 v66, v66
	v_exp_f32_e32 v67, v67
	v_lshlrev_b32_e32 v68, 16, v40
	v_and_b32_e32 v69, 0xffff0000, v40
	v_lshlrev_b32_e32 v70, 16, v41
	v_and_b32_e32 v71, 0xffff0000, v41
	v_pk_fma_f32 v[60:61], v[60:61], v[64:65], v[68:69]
	v_pk_fma_f32 v[62:63], v[62:63], v[66:67], v[70:71]
	global_load_dwordx2 v[40:41], v[116:117], off
	global_load_dwordx4 v[8:11], v[120:121], off
	v_lshl_add_u64 v[116:117], v[116:117], 0, s[10:11]
	v_cvt_pk_bf16_f32 v114, v60, v61
	v_cvt_pk_bf16_f32 v115, v62, v63
	s_waitcnt vmcnt(33)
	global_store_dwordx2 v[118:119], v[114:115], off
	v_lshl_add_u64 v[118:119], v[118:119], 0, s[10:11]
	v_mul_f32_e32 v64, 0x3fb8aa3b, v12
	v_mul_f32_e32 v65, 0x3fb8aa3b, v13
	v_mul_f32_e32 v66, 0x3fb8aa3b, v14
	v_mul_f32_e32 v67, 0x3fb8aa3b, v15
	v_exp_f32_e32 v64, v64
	v_exp_f32_e32 v65, v65
	v_exp_f32_e32 v66, v66
	v_exp_f32_e32 v67, v67
	v_lshlrev_b32_e32 v68, 16, v42
	v_and_b32_e32 v69, 0xffff0000, v42
	v_lshlrev_b32_e32 v70, 16, v43
	v_and_b32_e32 v71, 0xffff0000, v43
	v_pk_fma_f32 v[60:61], v[60:61], v[64:65], v[68:69]
	v_pk_fma_f32 v[62:63], v[62:63], v[66:67], v[70:71]
	global_load_dwordx2 v[42:43], v[116:117], off
	global_load_dwordx4 v[12:15], v[120:121], off offset:2048
	v_lshl_add_u64 v[116:117], v[116:117], 0, s[10:11]
	v_lshl_add_u64 v[120:121], v[120:121], 0, s[100:101]
	v_cvt_pk_bf16_f32 v112, v60, v61
	v_cvt_pk_bf16_f32 v113, v62, v63
	s_waitcnt vmcnt(34)
	global_store_dwordx2 v[118:119], v[112:113], off
	v_lshl_add_u64 v[118:119], v[118:119], 0, s[10:11]
	v_mul_f32_e32 v64, 0x3fb8aa3b, v16
	v_mul_f32_e32 v65, 0x3fb8aa3b, v17
	v_mul_f32_e32 v66, 0x3fb8aa3b, v18
	v_mul_f32_e32 v67, 0x3fb8aa3b, v19
	v_exp_f32_e32 v64, v64
	v_exp_f32_e32 v65, v65
	v_exp_f32_e32 v66, v66
	v_exp_f32_e32 v67, v67
	v_lshlrev_b32_e32 v68, 16, v44
	v_and_b32_e32 v69, 0xffff0000, v44
	v_lshlrev_b32_e32 v70, 16, v45
	v_and_b32_e32 v71, 0xffff0000, v45
	v_pk_fma_f32 v[60:61], v[60:61], v[64:65], v[68:69]
	v_pk_fma_f32 v[62:63], v[62:63], v[66:67], v[70:71]
	global_load_dwordx2 v[44:45], v[116:117], off
	global_load_dwordx4 v[16:19], v[120:121], off
	v_lshl_add_u64 v[116:117], v[116:117], 0, s[10:11]
	v_cvt_pk_bf16_f32 v114, v60, v61
	v_cvt_pk_bf16_f32 v115, v62, v63
	s_waitcnt vmcnt(35)
	global_store_dwordx2 v[118:119], v[114:115], off
	v_lshl_add_u64 v[118:119], v[118:119], 0, s[10:11]
	v_mul_f32_e32 v64, 0x3fb8aa3b, v20
	v_mul_f32_e32 v65, 0x3fb8aa3b, v21
	v_mul_f32_e32 v66, 0x3fb8aa3b, v22
	v_mul_f32_e32 v67, 0x3fb8aa3b, v23
	v_exp_f32_e32 v64, v64
	v_exp_f32_e32 v65, v65
	v_exp_f32_e32 v66, v66
	v_exp_f32_e32 v67, v67
	v_lshlrev_b32_e32 v68, 16, v46
	v_and_b32_e32 v69, 0xffff0000, v46
	v_lshlrev_b32_e32 v70, 16, v47
	v_and_b32_e32 v71, 0xffff0000, v47
	v_pk_fma_f32 v[60:61], v[60:61], v[64:65], v[68:69]
	v_pk_fma_f32 v[62:63], v[62:63], v[66:67], v[70:71]
	global_load_dwordx2 v[46:47], v[116:117], off
	global_load_dwordx4 v[20:23], v[120:121], off offset:2048
	v_lshl_add_u64 v[116:117], v[116:117], 0, s[10:11]
	v_lshl_add_u64 v[120:121], v[120:121], 0, s[100:101]
	v_cvt_pk_bf16_f32 v112, v60, v61
	v_cvt_pk_bf16_f32 v113, v62, v63
	s_waitcnt vmcnt(36)
	global_store_dwordx2 v[118:119], v[112:113], off
	v_lshl_add_u64 v[118:119], v[118:119], 0, s[10:11]
	v_mul_f32_e32 v64, 0x3fb8aa3b, v24
	v_mul_f32_e32 v65, 0x3fb8aa3b, v25
	v_mul_f32_e32 v66, 0x3fb8aa3b, v26
	v_mul_f32_e32 v67, 0x3fb8aa3b, v27
	v_exp_f32_e32 v64, v64
	v_exp_f32_e32 v65, v65
	v_exp_f32_e32 v66, v66
	v_exp_f32_e32 v67, v67
	v_lshlrev_b32_e32 v68, 16, v48
	v_and_b32_e32 v69, 0xffff0000, v48
	v_lshlrev_b32_e32 v70, 16, v49
	v_and_b32_e32 v71, 0xffff0000, v49
	v_pk_fma_f32 v[60:61], v[60:61], v[64:65], v[68:69]
	v_pk_fma_f32 v[62:63], v[62:63], v[66:67], v[70:71]
	global_load_dwordx2 v[48:49], v[116:117], off
	global_load_dwordx4 v[24:27], v[120:121], off
	v_lshl_add_u64 v[116:117], v[116:117], 0, s[10:11]
	v_cvt_pk_bf16_f32 v114, v60, v61
	v_cvt_pk_bf16_f32 v115, v62, v63
	s_waitcnt vmcnt(37)
	global_store_dwordx2 v[118:119], v[114:115], off
	v_lshl_add_u64 v[118:119], v[118:119], 0, s[10:11]
	v_mul_f32_e32 v64, 0x3fb8aa3b, v28
	v_mul_f32_e32 v65, 0x3fb8aa3b, v29
	v_mul_f32_e32 v66, 0x3fb8aa3b, v30
	v_mul_f32_e32 v67, 0x3fb8aa3b, v31
	v_exp_f32_e32 v64, v64
	v_exp_f32_e32 v65, v65
	v_exp_f32_e32 v66, v66
	v_exp_f32_e32 v67, v67
	v_lshlrev_b32_e32 v68, 16, v50
	v_and_b32_e32 v69, 0xffff0000, v50
	v_lshlrev_b32_e32 v70, 16, v51
	v_and_b32_e32 v71, 0xffff0000, v51
	v_pk_fma_f32 v[60:61], v[60:61], v[64:65], v[68:69]
	v_pk_fma_f32 v[62:63], v[62:63], v[66:67], v[70:71]
	global_load_dwordx2 v[50:51], v[116:117], off
	global_load_dwordx4 v[28:31], v[120:121], off offset:2048
	v_lshl_add_u64 v[116:117], v[116:117], 0, s[10:11]
	v_lshl_add_u64 v[120:121], v[120:121], 0, s[100:101]
	v_cvt_pk_bf16_f32 v112, v60, v61
	v_cvt_pk_bf16_f32 v113, v62, v63
	s_waitcnt vmcnt(38)
	global_store_dwordx2 v[118:119], v[112:113], off
	v_lshl_add_u64 v[118:119], v[118:119], 0, s[10:11]
	v_mul_f32_e32 v64, 0x3fb8aa3b, v72
	v_mul_f32_e32 v65, 0x3fb8aa3b, v73
	v_mul_f32_e32 v66, 0x3fb8aa3b, v74
	v_mul_f32_e32 v67, 0x3fb8aa3b, v75
	v_exp_f32_e32 v64, v64
	v_exp_f32_e32 v65, v65
	v_exp_f32_e32 v66, v66
	v_exp_f32_e32 v67, v67
	v_lshlrev_b32_e32 v68, 16, v52
	v_and_b32_e32 v69, 0xffff0000, v52
	v_lshlrev_b32_e32 v70, 16, v53
	v_and_b32_e32 v71, 0xffff0000, v53
	v_pk_fma_f32 v[60:61], v[60:61], v[64:65], v[68:69]
	v_pk_fma_f32 v[62:63], v[62:63], v[66:67], v[70:71]
	global_load_dwordx2 v[52:53], v[116:117], off
	global_load_dwordx4 v[72:75], v[120:121], off
	v_lshl_add_u64 v[116:117], v[116:117], 0, s[10:11]
	v_cvt_pk_bf16_f32 v114, v60, v61
	v_cvt_pk_bf16_f32 v115, v62, v63
	s_waitcnt vmcnt(39)
	global_store_dwordx2 v[118:119], v[114:115], off
	v_lshl_add_u64 v[118:119], v[118:119], 0, s[10:11]
	v_mul_f32_e32 v64, 0x3fb8aa3b, v76
	v_mul_f32_e32 v65, 0x3fb8aa3b, v77
	v_mul_f32_e32 v66, 0x3fb8aa3b, v78
	v_mul_f32_e32 v67, 0x3fb8aa3b, v79
	v_exp_f32_e32 v64, v64
	v_exp_f32_e32 v65, v65
	v_exp_f32_e32 v66, v66
	v_exp_f32_e32 v67, v67
	v_lshlrev_b32_e32 v68, 16, v54
	v_and_b32_e32 v69, 0xffff0000, v54
	v_lshlrev_b32_e32 v70, 16, v55
	v_and_b32_e32 v71, 0xffff0000, v55
	v_pk_fma_f32 v[60:61], v[60:61], v[64:65], v[68:69]
	v_pk_fma_f32 v[62:63], v[62:63], v[66:67], v[70:71]
	global_load_dwordx2 v[54:55], v[116:117], off
	global_load_dwordx4 v[76:79], v[120:121], off offset:2048
	v_lshl_add_u64 v[116:117], v[116:117], 0, s[10:11]
	v_lshl_add_u64 v[120:121], v[120:121], 0, s[100:101]
	v_cvt_pk_bf16_f32 v112, v60, v61
	v_cvt_pk_bf16_f32 v113, v62, v63
	s_waitcnt vmcnt(40)
	global_store_dwordx2 v[118:119], v[112:113], off
	v_lshl_add_u64 v[118:119], v[118:119], 0, s[10:11]
	v_mul_f32_e32 v64, 0x3fb8aa3b, v80
	v_mul_f32_e32 v65, 0x3fb8aa3b, v81
	v_mul_f32_e32 v66, 0x3fb8aa3b, v82
	v_mul_f32_e32 v67, 0x3fb8aa3b, v83
	v_exp_f32_e32 v64, v64
	v_exp_f32_e32 v65, v65
	v_exp_f32_e32 v66, v66
	v_exp_f32_e32 v67, v67
	v_lshlrev_b32_e32 v68, 16, v56
	v_and_b32_e32 v69, 0xffff0000, v56
	v_lshlrev_b32_e32 v70, 16, v57
	v_and_b32_e32 v71, 0xffff0000, v57
	v_pk_fma_f32 v[60:61], v[60:61], v[64:65], v[68:69]
	v_pk_fma_f32 v[62:63], v[62:63], v[66:67], v[70:71]
	global_load_dwordx2 v[56:57], v[116:117], off
	global_load_dwordx4 v[80:83], v[120:121], off
	v_lshl_add_u64 v[116:117], v[116:117], 0, s[10:11]
	v_cvt_pk_bf16_f32 v114, v60, v61
	v_cvt_pk_bf16_f32 v115, v62, v63
	s_waitcnt vmcnt(41)
	global_store_dwordx2 v[118:119], v[114:115], off
	v_lshl_add_u64 v[118:119], v[118:119], 0, s[10:11]
	v_mul_f32_e32 v64, 0x3fb8aa3b, v84
	v_mul_f32_e32 v65, 0x3fb8aa3b, v85
	v_mul_f32_e32 v66, 0x3fb8aa3b, v86
	v_mul_f32_e32 v67, 0x3fb8aa3b, v87
	v_exp_f32_e32 v64, v64
	v_exp_f32_e32 v65, v65
	v_exp_f32_e32 v66, v66
	v_exp_f32_e32 v67, v67
	v_lshlrev_b32_e32 v68, 16, v58
	v_and_b32_e32 v69, 0xffff0000, v58
	v_lshlrev_b32_e32 v70, 16, v59
	v_and_b32_e32 v71, 0xffff0000, v59
	v_pk_fma_f32 v[60:61], v[60:61], v[64:65], v[68:69]
	v_pk_fma_f32 v[62:63], v[62:63], v[66:67], v[70:71]
	global_load_dwordx2 v[58:59], v[116:117], off
	global_load_dwordx4 v[84:87], v[120:121], off offset:2048
	v_lshl_add_u64 v[116:117], v[116:117], 0, s[10:11]
	v_lshl_add_u64 v[120:121], v[120:121], 0, s[100:101]
	v_cvt_pk_bf16_f32 v112, v60, v61
	v_cvt_pk_bf16_f32 v113, v62, v63
	s_waitcnt vmcnt(42)
	global_store_dwordx2 v[118:119], v[112:113], off
	v_lshl_add_u64 v[118:119], v[118:119], 0, s[10:11]
	v_mul_f32_e32 v64, 0x3fb8aa3b, v88
	v_mul_f32_e32 v65, 0x3fb8aa3b, v89
	v_mul_f32_e32 v66, 0x3fb8aa3b, v90
	v_mul_f32_e32 v67, 0x3fb8aa3b, v91
	v_exp_f32_e32 v64, v64
	v_exp_f32_e32 v65, v65
	v_exp_f32_e32 v66, v66
	v_exp_f32_e32 v67, v67
	v_lshlrev_b32_e32 v68, 16, v104
	v_and_b32_e32 v69, 0xffff0000, v104
	v_lshlrev_b32_e32 v70, 16, v105
	v_and_b32_e32 v71, 0xffff0000, v105
	v_pk_fma_f32 v[60:61], v[60:61], v[64:65], v[68:69]
	v_pk_fma_f32 v[62:63], v[62:63], v[66:67], v[70:71]
	global_load_dwordx2 v[104:105], v[116:117], off
	global_load_dwordx4 v[88:91], v[120:121], off
	v_lshl_add_u64 v[116:117], v[116:117], 0, s[10:11]
	v_cvt_pk_bf16_f32 v114, v60, v61
	v_cvt_pk_bf16_f32 v115, v62, v63
	s_waitcnt vmcnt(43)
	global_store_dwordx2 v[118:119], v[114:115], off
	v_lshl_add_u64 v[118:119], v[118:119], 0, s[10:11]
	v_mul_f32_e32 v64, 0x3fb8aa3b, v92
	v_mul_f32_e32 v65, 0x3fb8aa3b, v93
	v_mul_f32_e32 v66, 0x3fb8aa3b, v94
	v_mul_f32_e32 v67, 0x3fb8aa3b, v95
	v_exp_f32_e32 v64, v64
	v_exp_f32_e32 v65, v65
	v_exp_f32_e32 v66, v66
	v_exp_f32_e32 v67, v67
	v_lshlrev_b32_e32 v68, 16, v106
	v_and_b32_e32 v69, 0xffff0000, v106
	v_lshlrev_b32_e32 v70, 16, v107
	v_and_b32_e32 v71, 0xffff0000, v107
	v_pk_fma_f32 v[60:61], v[60:61], v[64:65], v[68:69]
	v_pk_fma_f32 v[62:63], v[62:63], v[66:67], v[70:71]
	global_load_dwordx2 v[106:107], v[116:117], off
	global_load_dwordx4 v[92:95], v[120:121], off offset:2048
	v_lshl_add_u64 v[116:117], v[116:117], 0, s[10:11]
	v_lshl_add_u64 v[120:121], v[120:121], 0, s[100:101]
	v_cvt_pk_bf16_f32 v112, v60, v61
	v_cvt_pk_bf16_f32 v113, v62, v63
	s_waitcnt vmcnt(44)
	global_store_dwordx2 v[118:119], v[112:113], off
	v_lshl_add_u64 v[118:119], v[118:119], 0, s[10:11]
	v_mul_f32_e32 v64, 0x3fb8aa3b, v96
	v_mul_f32_e32 v65, 0x3fb8aa3b, v97
	v_mul_f32_e32 v66, 0x3fb8aa3b, v98
	v_mul_f32_e32 v67, 0x3fb8aa3b, v99
	v_exp_f32_e32 v64, v64
	v_exp_f32_e32 v65, v65
	v_exp_f32_e32 v66, v66
	v_exp_f32_e32 v67, v67
	v_lshlrev_b32_e32 v68, 16, v108
	v_and_b32_e32 v69, 0xffff0000, v108
	v_lshlrev_b32_e32 v70, 16, v109
	v_and_b32_e32 v71, 0xffff0000, v109
	v_pk_fma_f32 v[60:61], v[60:61], v[64:65], v[68:69]
	v_pk_fma_f32 v[62:63], v[62:63], v[66:67], v[70:71]
	global_load_dwordx2 v[108:109], v[116:117], off
	global_load_dwordx4 v[96:99], v[120:121], off
	v_lshl_add_u64 v[116:117], v[116:117], 0, s[10:11]
	v_cvt_pk_bf16_f32 v114, v60, v61
	v_cvt_pk_bf16_f32 v115, v62, v63
	s_waitcnt vmcnt(45)
	global_store_dwordx2 v[118:119], v[114:115], off
	v_lshl_add_u64 v[118:119], v[118:119], 0, s[10:11]
	v_mul_f32_e32 v64, 0x3fb8aa3b, v100
	v_mul_f32_e32 v65, 0x3fb8aa3b, v101
	v_mul_f32_e32 v66, 0x3fb8aa3b, v102
	v_mul_f32_e32 v67, 0x3fb8aa3b, v103
	v_exp_f32_e32 v64, v64
	v_exp_f32_e32 v65, v65
	v_exp_f32_e32 v66, v66
	v_exp_f32_e32 v67, v67
	v_lshlrev_b32_e32 v68, 16, v110
	v_and_b32_e32 v69, 0xffff0000, v110
	v_lshlrev_b32_e32 v70, 16, v111
	v_and_b32_e32 v71, 0xffff0000, v111
	v_pk_fma_f32 v[60:61], v[60:61], v[64:65], v[68:69]
	v_pk_fma_f32 v[62:63], v[62:63], v[66:67], v[70:71]
	global_load_dwordx2 v[110:111], v[116:117], off
	global_load_dwordx4 v[100:103], v[120:121], off offset:2048
	v_lshl_add_u64 v[116:117], v[116:117], 0, s[10:11]
	v_lshl_add_u64 v[120:121], v[120:121], 0, s[100:101]
	v_cvt_pk_bf16_f32 v112, v60, v61
	v_cvt_pk_bf16_f32 v113, v62, v63
	s_waitcnt vmcnt(45)
	global_store_dwordx2 v[118:119], v[112:113], off
	v_lshl_add_u64 v[118:119], v[118:119], 0, s[10:11]
	v_mul_f32_e32 v64, 0x3fb8aa3b, v0
	v_mul_f32_e32 v65, 0x3fb8aa3b, v1
	v_mul_f32_e32 v66, 0x3fb8aa3b, v2
	v_mul_f32_e32 v67, 0x3fb8aa3b, v3
	v_exp_f32_e32 v64, v64
	v_exp_f32_e32 v65, v65
	v_exp_f32_e32 v66, v66
	v_exp_f32_e32 v67, v67
	v_lshlrev_b32_e32 v68, 16, v36
	v_and_b32_e32 v69, 0xffff0000, v36
	v_lshlrev_b32_e32 v70, 16, v37
	v_and_b32_e32 v71, 0xffff0000, v37
	v_pk_fma_f32 v[60:61], v[60:61], v[64:65], v[68:69]
	v_pk_fma_f32 v[62:63], v[62:63], v[66:67], v[70:71]
	global_load_dwordx2 v[36:37], v[116:117], off
	global_load_dwordx4 v[0:3], v[120:121], off
	v_lshl_add_u64 v[116:117], v[116:117], 0, s[10:11]
	v_cvt_pk_bf16_f32 v114, v60, v61
	v_cvt_pk_bf16_f32 v115, v62, v63
	s_waitcnt vmcnt(45)
	global_store_dwordx2 v[118:119], v[114:115], off
	v_lshl_add_u64 v[118:119], v[118:119], 0, s[10:11]
	v_mul_f32_e32 v64, 0x3fb8aa3b, v4
	v_mul_f32_e32 v65, 0x3fb8aa3b, v5
	v_mul_f32_e32 v66, 0x3fb8aa3b, v6
	v_mul_f32_e32 v67, 0x3fb8aa3b, v7
	v_exp_f32_e32 v64, v64
	v_exp_f32_e32 v65, v65
	v_exp_f32_e32 v66, v66
	v_exp_f32_e32 v67, v67
	v_lshlrev_b32_e32 v68, 16, v38
	v_and_b32_e32 v69, 0xffff0000, v38
	v_lshlrev_b32_e32 v70, 16, v39
	v_and_b32_e32 v71, 0xffff0000, v39
	v_pk_fma_f32 v[60:61], v[60:61], v[64:65], v[68:69]
	v_pk_fma_f32 v[62:63], v[62:63], v[66:67], v[70:71]
	global_load_dwordx2 v[38:39], v[116:117], off
	global_load_dwordx4 v[4:7], v[120:121], off offset:2048
	v_lshl_add_u64 v[116:117], v[116:117], 0, s[10:11]
	v_lshl_add_u64 v[120:121], v[120:121], 0, s[100:101]
	v_cvt_pk_bf16_f32 v112, v60, v61
	v_cvt_pk_bf16_f32 v113, v62, v63
	s_waitcnt vmcnt(45)
	global_store_dwordx2 v[118:119], v[112:113], off
	v_lshl_add_u64 v[118:119], v[118:119], 0, s[10:11]
	v_mul_f32_e32 v64, 0x3fb8aa3b, v8
	v_mul_f32_e32 v65, 0x3fb8aa3b, v9
	v_mul_f32_e32 v66, 0x3fb8aa3b, v10
	v_mul_f32_e32 v67, 0x3fb8aa3b, v11
	v_exp_f32_e32 v64, v64
	v_exp_f32_e32 v65, v65
	v_exp_f32_e32 v66, v66
	v_exp_f32_e32 v67, v67
	v_lshlrev_b32_e32 v68, 16, v40
	v_and_b32_e32 v69, 0xffff0000, v40
	v_lshlrev_b32_e32 v70, 16, v41
	v_and_b32_e32 v71, 0xffff0000, v41
	v_pk_fma_f32 v[60:61], v[60:61], v[64:65], v[68:69]
	v_pk_fma_f32 v[62:63], v[62:63], v[66:67], v[70:71]
	global_load_dwordx2 v[40:41], v[116:117], off
	global_load_dwordx4 v[8:11], v[120:121], off
	v_lshl_add_u64 v[116:117], v[116:117], 0, s[10:11]
	v_cvt_pk_bf16_f32 v114, v60, v61
	v_cvt_pk_bf16_f32 v115, v62, v63
	s_waitcnt vmcnt(45)
	global_store_dwordx2 v[118:119], v[114:115], off
	v_lshl_add_u64 v[118:119], v[118:119], 0, s[10:11]
	v_mul_f32_e32 v64, 0x3fb8aa3b, v12
	v_mul_f32_e32 v65, 0x3fb8aa3b, v13
	v_mul_f32_e32 v66, 0x3fb8aa3b, v14
	v_mul_f32_e32 v67, 0x3fb8aa3b, v15
	v_exp_f32_e32 v64, v64
	v_exp_f32_e32 v65, v65
	v_exp_f32_e32 v66, v66
	v_exp_f32_e32 v67, v67
	v_lshlrev_b32_e32 v68, 16, v42
	v_and_b32_e32 v69, 0xffff0000, v42
	v_lshlrev_b32_e32 v70, 16, v43
	v_and_b32_e32 v71, 0xffff0000, v43
	v_pk_fma_f32 v[60:61], v[60:61], v[64:65], v[68:69]
	v_pk_fma_f32 v[62:63], v[62:63], v[66:67], v[70:71]
	global_load_dwordx2 v[42:43], v[116:117], off
	global_load_dwordx4 v[12:15], v[120:121], off offset:2048
	v_lshl_add_u64 v[116:117], v[116:117], 0, s[10:11]
	v_lshl_add_u64 v[120:121], v[120:121], 0, s[100:101]
	v_cvt_pk_bf16_f32 v112, v60, v61
	v_cvt_pk_bf16_f32 v113, v62, v63
	s_waitcnt vmcnt(45)
	global_store_dwordx2 v[118:119], v[112:113], off
	v_lshl_add_u64 v[118:119], v[118:119], 0, s[10:11]
	v_mul_f32_e32 v64, 0x3fb8aa3b, v16
	v_mul_f32_e32 v65, 0x3fb8aa3b, v17
	v_mul_f32_e32 v66, 0x3fb8aa3b, v18
	v_mul_f32_e32 v67, 0x3fb8aa3b, v19
	v_exp_f32_e32 v64, v64
	v_exp_f32_e32 v65, v65
	v_exp_f32_e32 v66, v66
	v_exp_f32_e32 v67, v67
	v_lshlrev_b32_e32 v68, 16, v44
	v_and_b32_e32 v69, 0xffff0000, v44
	v_lshlrev_b32_e32 v70, 16, v45
	v_and_b32_e32 v71, 0xffff0000, v45
	v_pk_fma_f32 v[60:61], v[60:61], v[64:65], v[68:69]
	v_pk_fma_f32 v[62:63], v[62:63], v[66:67], v[70:71]
	global_load_dwordx2 v[44:45], v[116:117], off
	global_load_dwordx4 v[16:19], v[120:121], off
	v_lshl_add_u64 v[116:117], v[116:117], 0, s[10:11]
	v_cvt_pk_bf16_f32 v114, v60, v61
	v_cvt_pk_bf16_f32 v115, v62, v63
	s_waitcnt vmcnt(45)
	global_store_dwordx2 v[118:119], v[114:115], off
	v_lshl_add_u64 v[118:119], v[118:119], 0, s[10:11]
	v_mul_f32_e32 v64, 0x3fb8aa3b, v20
	v_mul_f32_e32 v65, 0x3fb8aa3b, v21
	v_mul_f32_e32 v66, 0x3fb8aa3b, v22
	v_mul_f32_e32 v67, 0x3fb8aa3b, v23
	v_exp_f32_e32 v64, v64
	v_exp_f32_e32 v65, v65
	v_exp_f32_e32 v66, v66
	v_exp_f32_e32 v67, v67
	v_lshlrev_b32_e32 v68, 16, v46
	v_and_b32_e32 v69, 0xffff0000, v46
	v_lshlrev_b32_e32 v70, 16, v47
	v_and_b32_e32 v71, 0xffff0000, v47
	v_pk_fma_f32 v[60:61], v[60:61], v[64:65], v[68:69]
	v_pk_fma_f32 v[62:63], v[62:63], v[66:67], v[70:71]
	global_load_dwordx2 v[46:47], v[116:117], off
	global_load_dwordx4 v[20:23], v[120:121], off offset:2048
	v_lshl_add_u64 v[116:117], v[116:117], 0, s[10:11]
	v_lshl_add_u64 v[120:121], v[120:121], 0, s[100:101]
	v_cvt_pk_bf16_f32 v112, v60, v61
	v_cvt_pk_bf16_f32 v113, v62, v63
	s_waitcnt vmcnt(45)
	global_store_dwordx2 v[118:119], v[112:113], off
	v_lshl_add_u64 v[118:119], v[118:119], 0, s[10:11]
	v_mul_f32_e32 v64, 0x3fb8aa3b, v24
	v_mul_f32_e32 v65, 0x3fb8aa3b, v25
	v_mul_f32_e32 v66, 0x3fb8aa3b, v26
	v_mul_f32_e32 v67, 0x3fb8aa3b, v27
	v_exp_f32_e32 v64, v64
	v_exp_f32_e32 v65, v65
	v_exp_f32_e32 v66, v66
	v_exp_f32_e32 v67, v67
	v_lshlrev_b32_e32 v68, 16, v48
	v_and_b32_e32 v69, 0xffff0000, v48
	v_lshlrev_b32_e32 v70, 16, v49
	v_and_b32_e32 v71, 0xffff0000, v49
	v_pk_fma_f32 v[60:61], v[60:61], v[64:65], v[68:69]
	v_pk_fma_f32 v[62:63], v[62:63], v[66:67], v[70:71]
	global_load_dwordx2 v[48:49], v[116:117], off
	global_load_dwordx4 v[24:27], v[120:121], off
	v_lshl_add_u64 v[116:117], v[116:117], 0, s[10:11]
	v_cvt_pk_bf16_f32 v114, v60, v61
	v_cvt_pk_bf16_f32 v115, v62, v63
	s_waitcnt vmcnt(45)
	global_store_dwordx2 v[118:119], v[114:115], off
	v_lshl_add_u64 v[118:119], v[118:119], 0, s[10:11]
	v_mul_f32_e32 v64, 0x3fb8aa3b, v28
	v_mul_f32_e32 v65, 0x3fb8aa3b, v29
	v_mul_f32_e32 v66, 0x3fb8aa3b, v30
	v_mul_f32_e32 v67, 0x3fb8aa3b, v31
	v_exp_f32_e32 v64, v64
	v_exp_f32_e32 v65, v65
	v_exp_f32_e32 v66, v66
	v_exp_f32_e32 v67, v67
	v_lshlrev_b32_e32 v68, 16, v50
	v_and_b32_e32 v69, 0xffff0000, v50
	v_lshlrev_b32_e32 v70, 16, v51
	v_and_b32_e32 v71, 0xffff0000, v51
	v_pk_fma_f32 v[60:61], v[60:61], v[64:65], v[68:69]
	v_pk_fma_f32 v[62:63], v[62:63], v[66:67], v[70:71]
	global_load_dwordx2 v[50:51], v[116:117], off
	global_load_dwordx4 v[28:31], v[120:121], off offset:2048
	v_lshl_add_u64 v[116:117], v[116:117], 0, s[10:11]
	v_lshl_add_u64 v[120:121], v[120:121], 0, s[100:101]
	v_cvt_pk_bf16_f32 v112, v60, v61
	v_cvt_pk_bf16_f32 v113, v62, v63
	s_waitcnt vmcnt(45)
	global_store_dwordx2 v[118:119], v[112:113], off
	v_lshl_add_u64 v[118:119], v[118:119], 0, s[10:11]
	v_mul_f32_e32 v64, 0x3fb8aa3b, v72
	v_mul_f32_e32 v65, 0x3fb8aa3b, v73
	v_mul_f32_e32 v66, 0x3fb8aa3b, v74
	v_mul_f32_e32 v67, 0x3fb8aa3b, v75
	v_exp_f32_e32 v64, v64
	v_exp_f32_e32 v65, v65
	v_exp_f32_e32 v66, v66
	v_exp_f32_e32 v67, v67
	v_lshlrev_b32_e32 v68, 16, v52
	v_and_b32_e32 v69, 0xffff0000, v52
	v_lshlrev_b32_e32 v70, 16, v53
	v_and_b32_e32 v71, 0xffff0000, v53
	v_pk_fma_f32 v[60:61], v[60:61], v[64:65], v[68:69]
	v_pk_fma_f32 v[62:63], v[62:63], v[66:67], v[70:71]
	global_load_dwordx2 v[52:53], v[116:117], off
	global_load_dwordx4 v[72:75], v[120:121], off
	v_lshl_add_u64 v[116:117], v[116:117], 0, s[10:11]
	v_cvt_pk_bf16_f32 v114, v60, v61
	v_cvt_pk_bf16_f32 v115, v62, v63
	s_waitcnt vmcnt(45)
	global_store_dwordx2 v[118:119], v[114:115], off
	v_lshl_add_u64 v[118:119], v[118:119], 0, s[10:11]
	v_mul_f32_e32 v64, 0x3fb8aa3b, v76
	v_mul_f32_e32 v65, 0x3fb8aa3b, v77
	v_mul_f32_e32 v66, 0x3fb8aa3b, v78
	v_mul_f32_e32 v67, 0x3fb8aa3b, v79
	v_exp_f32_e32 v64, v64
	v_exp_f32_e32 v65, v65
	v_exp_f32_e32 v66, v66
	v_exp_f32_e32 v67, v67
	v_lshlrev_b32_e32 v68, 16, v54
	v_and_b32_e32 v69, 0xffff0000, v54
	v_lshlrev_b32_e32 v70, 16, v55
	v_and_b32_e32 v71, 0xffff0000, v55
	v_pk_fma_f32 v[60:61], v[60:61], v[64:65], v[68:69]
	v_pk_fma_f32 v[62:63], v[62:63], v[66:67], v[70:71]
	global_load_dwordx2 v[54:55], v[116:117], off
	global_load_dwordx4 v[76:79], v[120:121], off offset:2048
	v_lshl_add_u64 v[116:117], v[116:117], 0, s[10:11]
	v_lshl_add_u64 v[120:121], v[120:121], 0, s[100:101]
	v_cvt_pk_bf16_f32 v112, v60, v61
	v_cvt_pk_bf16_f32 v113, v62, v63
	s_waitcnt vmcnt(45)
	global_store_dwordx2 v[118:119], v[112:113], off
	v_lshl_add_u64 v[118:119], v[118:119], 0, s[10:11]
	v_mul_f32_e32 v64, 0x3fb8aa3b, v80
	v_mul_f32_e32 v65, 0x3fb8aa3b, v81
	v_mul_f32_e32 v66, 0x3fb8aa3b, v82
	v_mul_f32_e32 v67, 0x3fb8aa3b, v83
	v_exp_f32_e32 v64, v64
	v_exp_f32_e32 v65, v65
	v_exp_f32_e32 v66, v66
	v_exp_f32_e32 v67, v67
	v_lshlrev_b32_e32 v68, 16, v56
	v_and_b32_e32 v69, 0xffff0000, v56
	v_lshlrev_b32_e32 v70, 16, v57
	v_and_b32_e32 v71, 0xffff0000, v57
	v_pk_fma_f32 v[60:61], v[60:61], v[64:65], v[68:69]
	v_pk_fma_f32 v[62:63], v[62:63], v[66:67], v[70:71]
	global_load_dwordx2 v[56:57], v[116:117], off
	global_load_dwordx4 v[80:83], v[120:121], off
	v_lshl_add_u64 v[116:117], v[116:117], 0, s[10:11]
	v_cvt_pk_bf16_f32 v114, v60, v61
	v_cvt_pk_bf16_f32 v115, v62, v63
	s_waitcnt vmcnt(45)
	global_store_dwordx2 v[118:119], v[114:115], off
	v_lshl_add_u64 v[118:119], v[118:119], 0, s[10:11]
	v_mul_f32_e32 v64, 0x3fb8aa3b, v84
	v_mul_f32_e32 v65, 0x3fb8aa3b, v85
	v_mul_f32_e32 v66, 0x3fb8aa3b, v86
	v_mul_f32_e32 v67, 0x3fb8aa3b, v87
	v_exp_f32_e32 v64, v64
	v_exp_f32_e32 v65, v65
	v_exp_f32_e32 v66, v66
	v_exp_f32_e32 v67, v67
	v_lshlrev_b32_e32 v68, 16, v58
	v_and_b32_e32 v69, 0xffff0000, v58
	v_lshlrev_b32_e32 v70, 16, v59
	v_and_b32_e32 v71, 0xffff0000, v59
	v_pk_fma_f32 v[60:61], v[60:61], v[64:65], v[68:69]
	v_pk_fma_f32 v[62:63], v[62:63], v[66:67], v[70:71]
	global_load_dwordx2 v[58:59], v[116:117], off
	global_load_dwordx4 v[84:87], v[120:121], off offset:2048
	v_lshl_add_u64 v[116:117], v[116:117], 0, s[10:11]
	v_lshl_add_u64 v[120:121], v[120:121], 0, s[100:101]
	v_cvt_pk_bf16_f32 v112, v60, v61
	v_cvt_pk_bf16_f32 v113, v62, v63
	s_waitcnt vmcnt(45)
	global_store_dwordx2 v[118:119], v[112:113], off
	v_lshl_add_u64 v[118:119], v[118:119], 0, s[10:11]
	v_mul_f32_e32 v64, 0x3fb8aa3b, v88
	v_mul_f32_e32 v65, 0x3fb8aa3b, v89
	v_mul_f32_e32 v66, 0x3fb8aa3b, v90
	v_mul_f32_e32 v67, 0x3fb8aa3b, v91
	v_exp_f32_e32 v64, v64
	v_exp_f32_e32 v65, v65
	v_exp_f32_e32 v66, v66
	v_exp_f32_e32 v67, v67
	v_lshlrev_b32_e32 v68, 16, v104
	v_and_b32_e32 v69, 0xffff0000, v104
	v_lshlrev_b32_e32 v70, 16, v105
	v_and_b32_e32 v71, 0xffff0000, v105
	v_pk_fma_f32 v[60:61], v[60:61], v[64:65], v[68:69]
	v_pk_fma_f32 v[62:63], v[62:63], v[66:67], v[70:71]
	global_load_dwordx2 v[104:105], v[116:117], off
	global_load_dwordx4 v[88:91], v[120:121], off
	v_lshl_add_u64 v[116:117], v[116:117], 0, s[10:11]
	v_cvt_pk_bf16_f32 v114, v60, v61
	v_cvt_pk_bf16_f32 v115, v62, v63
	s_waitcnt vmcnt(45)
	global_store_dwordx2 v[118:119], v[114:115], off
	v_lshl_add_u64 v[118:119], v[118:119], 0, s[10:11]
	v_mul_f32_e32 v64, 0x3fb8aa3b, v92
	v_mul_f32_e32 v65, 0x3fb8aa3b, v93
	v_mul_f32_e32 v66, 0x3fb8aa3b, v94
	v_mul_f32_e32 v67, 0x3fb8aa3b, v95
	v_exp_f32_e32 v64, v64
	v_exp_f32_e32 v65, v65
	v_exp_f32_e32 v66, v66
	v_exp_f32_e32 v67, v67
	v_lshlrev_b32_e32 v68, 16, v106
	v_and_b32_e32 v69, 0xffff0000, v106
	v_lshlrev_b32_e32 v70, 16, v107
	v_and_b32_e32 v71, 0xffff0000, v107
	v_pk_fma_f32 v[60:61], v[60:61], v[64:65], v[68:69]
	v_pk_fma_f32 v[62:63], v[62:63], v[66:67], v[70:71]
	global_load_dwordx2 v[106:107], v[116:117], off
	global_load_dwordx4 v[92:95], v[120:121], off offset:2048
	v_lshl_add_u64 v[116:117], v[116:117], 0, s[10:11]
	v_lshl_add_u64 v[120:121], v[120:121], 0, s[100:101]
	v_cvt_pk_bf16_f32 v112, v60, v61
	v_cvt_pk_bf16_f32 v113, v62, v63
	s_waitcnt vmcnt(45)
	global_store_dwordx2 v[118:119], v[112:113], off
	v_lshl_add_u64 v[118:119], v[118:119], 0, s[10:11]
	v_mul_f32_e32 v64, 0x3fb8aa3b, v96
	v_mul_f32_e32 v65, 0x3fb8aa3b, v97
	v_mul_f32_e32 v66, 0x3fb8aa3b, v98
	v_mul_f32_e32 v67, 0x3fb8aa3b, v99
	v_exp_f32_e32 v64, v64
	v_exp_f32_e32 v65, v65
	v_exp_f32_e32 v66, v66
	v_exp_f32_e32 v67, v67
	v_lshlrev_b32_e32 v68, 16, v108
	v_and_b32_e32 v69, 0xffff0000, v108
	v_lshlrev_b32_e32 v70, 16, v109
	v_and_b32_e32 v71, 0xffff0000, v109
	v_pk_fma_f32 v[60:61], v[60:61], v[64:65], v[68:69]
	v_pk_fma_f32 v[62:63], v[62:63], v[66:67], v[70:71]
	global_load_dwordx2 v[108:109], v[116:117], off
	global_load_dwordx4 v[96:99], v[120:121], off
	v_lshl_add_u64 v[116:117], v[116:117], 0, s[10:11]
	v_cvt_pk_bf16_f32 v114, v60, v61
	v_cvt_pk_bf16_f32 v115, v62, v63
	s_waitcnt vmcnt(45)
	global_store_dwordx2 v[118:119], v[114:115], off
	v_lshl_add_u64 v[118:119], v[118:119], 0, s[10:11]
	v_mul_f32_e32 v64, 0x3fb8aa3b, v100
	v_mul_f32_e32 v65, 0x3fb8aa3b, v101
	v_mul_f32_e32 v66, 0x3fb8aa3b, v102
	v_mul_f32_e32 v67, 0x3fb8aa3b, v103
	v_exp_f32_e32 v64, v64
	v_exp_f32_e32 v65, v65
	v_exp_f32_e32 v66, v66
	v_exp_f32_e32 v67, v67
	v_lshlrev_b32_e32 v68, 16, v110
	v_and_b32_e32 v69, 0xffff0000, v110
	v_lshlrev_b32_e32 v70, 16, v111
	v_and_b32_e32 v71, 0xffff0000, v111
	v_pk_fma_f32 v[60:61], v[60:61], v[64:65], v[68:69]
	v_pk_fma_f32 v[62:63], v[62:63], v[66:67], v[70:71]
	global_load_dwordx2 v[110:111], v[116:117], off
	global_load_dwordx4 v[100:103], v[120:121], off offset:2048
	v_lshl_add_u64 v[116:117], v[116:117], 0, s[10:11]
	v_lshl_add_u64 v[120:121], v[120:121], 0, s[100:101]
	v_cvt_pk_bf16_f32 v112, v60, v61
	v_cvt_pk_bf16_f32 v113, v62, v63
	s_waitcnt vmcnt(45)
	global_store_dwordx2 v[118:119], v[112:113], off
	v_lshl_add_u64 v[118:119], v[118:119], 0, s[10:11]
	v_mul_f32_e32 v64, 0x3fb8aa3b, v0
	v_mul_f32_e32 v65, 0x3fb8aa3b, v1
	v_mul_f32_e32 v66, 0x3fb8aa3b, v2
	v_mul_f32_e32 v67, 0x3fb8aa3b, v3
	v_exp_f32_e32 v64, v64
	v_exp_f32_e32 v65, v65
	v_exp_f32_e32 v66, v66
	v_exp_f32_e32 v67, v67
	v_lshlrev_b32_e32 v68, 16, v36
	v_and_b32_e32 v69, 0xffff0000, v36
	v_lshlrev_b32_e32 v70, 16, v37
	v_and_b32_e32 v71, 0xffff0000, v37
	v_pk_fma_f32 v[60:61], v[60:61], v[64:65], v[68:69]
	v_pk_fma_f32 v[62:63], v[62:63], v[66:67], v[70:71]
	global_load_dwordx2 v[36:37], v[116:117], off
	global_load_dwordx4 v[0:3], v[120:121], off
	v_lshl_add_u64 v[116:117], v[116:117], 0, s[10:11]
	v_cvt_pk_bf16_f32 v114, v60, v61
	v_cvt_pk_bf16_f32 v115, v62, v63
	s_waitcnt vmcnt(45)
	global_store_dwordx2 v[118:119], v[114:115], off
	v_lshl_add_u64 v[118:119], v[118:119], 0, s[10:11]
	v_mul_f32_e32 v64, 0x3fb8aa3b, v4
	v_mul_f32_e32 v65, 0x3fb8aa3b, v5
	v_mul_f32_e32 v66, 0x3fb8aa3b, v6
	v_mul_f32_e32 v67, 0x3fb8aa3b, v7
	v_exp_f32_e32 v64, v64
	v_exp_f32_e32 v65, v65
	v_exp_f32_e32 v66, v66
	v_exp_f32_e32 v67, v67
	v_lshlrev_b32_e32 v68, 16, v38
	v_and_b32_e32 v69, 0xffff0000, v38
	v_lshlrev_b32_e32 v70, 16, v39
	v_and_b32_e32 v71, 0xffff0000, v39
	v_pk_fma_f32 v[60:61], v[60:61], v[64:65], v[68:69]
	v_pk_fma_f32 v[62:63], v[62:63], v[66:67], v[70:71]
	global_load_dwordx2 v[38:39], v[116:117], off
	global_load_dwordx4 v[4:7], v[120:121], off offset:2048
	v_lshl_add_u64 v[116:117], v[116:117], 0, s[10:11]
	v_lshl_add_u64 v[120:121], v[120:121], 0, s[100:101]
	v_cvt_pk_bf16_f32 v112, v60, v61
	v_cvt_pk_bf16_f32 v113, v62, v63
	s_waitcnt vmcnt(45)
	global_store_dwordx2 v[118:119], v[112:113], off
	v_lshl_add_u64 v[118:119], v[118:119], 0, s[10:11]
	v_mul_f32_e32 v64, 0x3fb8aa3b, v8
	v_mul_f32_e32 v65, 0x3fb8aa3b, v9
	v_mul_f32_e32 v66, 0x3fb8aa3b, v10
	v_mul_f32_e32 v67, 0x3fb8aa3b, v11
	v_exp_f32_e32 v64, v64
	v_exp_f32_e32 v65, v65
	v_exp_f32_e32 v66, v66
	v_exp_f32_e32 v67, v67
	v_lshlrev_b32_e32 v68, 16, v40
	v_and_b32_e32 v69, 0xffff0000, v40
	v_lshlrev_b32_e32 v70, 16, v41
	v_and_b32_e32 v71, 0xffff0000, v41
	v_pk_fma_f32 v[60:61], v[60:61], v[64:65], v[68:69]
	v_pk_fma_f32 v[62:63], v[62:63], v[66:67], v[70:71]
	global_load_dwordx2 v[40:41], v[116:117], off
	global_load_dwordx4 v[8:11], v[120:121], off
	v_lshl_add_u64 v[116:117], v[116:117], 0, s[10:11]
	v_cvt_pk_bf16_f32 v114, v60, v61
	v_cvt_pk_bf16_f32 v115, v62, v63
	s_waitcnt vmcnt(45)
	global_store_dwordx2 v[118:119], v[114:115], off
	v_lshl_add_u64 v[118:119], v[118:119], 0, s[10:11]
	v_mul_f32_e32 v64, 0x3fb8aa3b, v12
	v_mul_f32_e32 v65, 0x3fb8aa3b, v13
	v_mul_f32_e32 v66, 0x3fb8aa3b, v14
	v_mul_f32_e32 v67, 0x3fb8aa3b, v15
	v_exp_f32_e32 v64, v64
	v_exp_f32_e32 v65, v65
	v_exp_f32_e32 v66, v66
	v_exp_f32_e32 v67, v67
	v_lshlrev_b32_e32 v68, 16, v42
	v_and_b32_e32 v69, 0xffff0000, v42
	v_lshlrev_b32_e32 v70, 16, v43
	v_and_b32_e32 v71, 0xffff0000, v43
	v_pk_fma_f32 v[60:61], v[60:61], v[64:65], v[68:69]
	v_pk_fma_f32 v[62:63], v[62:63], v[66:67], v[70:71]
	global_load_dwordx2 v[42:43], v[116:117], off
	global_load_dwordx4 v[12:15], v[120:121], off offset:2048
	v_lshl_add_u64 v[116:117], v[116:117], 0, s[10:11]
	v_lshl_add_u64 v[120:121], v[120:121], 0, s[100:101]
	v_cvt_pk_bf16_f32 v112, v60, v61
	v_cvt_pk_bf16_f32 v113, v62, v63
	s_waitcnt vmcnt(45)
	global_store_dwordx2 v[118:119], v[112:113], off
	v_lshl_add_u64 v[118:119], v[118:119], 0, s[10:11]
	v_mul_f32_e32 v64, 0x3fb8aa3b, v16
	v_mul_f32_e32 v65, 0x3fb8aa3b, v17
	v_mul_f32_e32 v66, 0x3fb8aa3b, v18
	v_mul_f32_e32 v67, 0x3fb8aa3b, v19
	v_exp_f32_e32 v64, v64
	v_exp_f32_e32 v65, v65
	v_exp_f32_e32 v66, v66
	v_exp_f32_e32 v67, v67
	v_lshlrev_b32_e32 v68, 16, v44
	v_and_b32_e32 v69, 0xffff0000, v44
	v_lshlrev_b32_e32 v70, 16, v45
	v_and_b32_e32 v71, 0xffff0000, v45
	v_pk_fma_f32 v[60:61], v[60:61], v[64:65], v[68:69]
	v_pk_fma_f32 v[62:63], v[62:63], v[66:67], v[70:71]
	global_load_dwordx2 v[44:45], v[116:117], off
	global_load_dwordx4 v[16:19], v[120:121], off
	v_lshl_add_u64 v[116:117], v[116:117], 0, s[10:11]
	v_cvt_pk_bf16_f32 v114, v60, v61
	v_cvt_pk_bf16_f32 v115, v62, v63
	s_waitcnt vmcnt(45)
	global_store_dwordx2 v[118:119], v[114:115], off
	v_lshl_add_u64 v[118:119], v[118:119], 0, s[10:11]
	v_mul_f32_e32 v64, 0x3fb8aa3b, v20
	v_mul_f32_e32 v65, 0x3fb8aa3b, v21
	v_mul_f32_e32 v66, 0x3fb8aa3b, v22
	v_mul_f32_e32 v67, 0x3fb8aa3b, v23
	v_exp_f32_e32 v64, v64
	v_exp_f32_e32 v65, v65
	v_exp_f32_e32 v66, v66
	v_exp_f32_e32 v67, v67
	v_lshlrev_b32_e32 v68, 16, v46
	v_and_b32_e32 v69, 0xffff0000, v46
	v_lshlrev_b32_e32 v70, 16, v47
	v_and_b32_e32 v71, 0xffff0000, v47
	v_pk_fma_f32 v[60:61], v[60:61], v[64:65], v[68:69]
	v_pk_fma_f32 v[62:63], v[62:63], v[66:67], v[70:71]
	global_load_dwordx2 v[46:47], v[116:117], off
	global_load_dwordx4 v[20:23], v[120:121], off offset:2048
	v_lshl_add_u64 v[116:117], v[116:117], 0, s[10:11]
	v_lshl_add_u64 v[120:121], v[120:121], 0, s[100:101]
	v_cvt_pk_bf16_f32 v112, v60, v61
	v_cvt_pk_bf16_f32 v113, v62, v63
	s_waitcnt vmcnt(45)
	global_store_dwordx2 v[118:119], v[112:113], off
	v_lshl_add_u64 v[118:119], v[118:119], 0, s[10:11]
	v_mul_f32_e32 v64, 0x3fb8aa3b, v24
	v_mul_f32_e32 v65, 0x3fb8aa3b, v25
	v_mul_f32_e32 v66, 0x3fb8aa3b, v26
	v_mul_f32_e32 v67, 0x3fb8aa3b, v27
	v_exp_f32_e32 v64, v64
	v_exp_f32_e32 v65, v65
	v_exp_f32_e32 v66, v66
	v_exp_f32_e32 v67, v67
	v_lshlrev_b32_e32 v68, 16, v48
	v_and_b32_e32 v69, 0xffff0000, v48
	v_lshlrev_b32_e32 v70, 16, v49
	v_and_b32_e32 v71, 0xffff0000, v49
	v_pk_fma_f32 v[60:61], v[60:61], v[64:65], v[68:69]
	v_pk_fma_f32 v[62:63], v[62:63], v[66:67], v[70:71]
	global_load_dwordx2 v[48:49], v[116:117], off
	global_load_dwordx4 v[24:27], v[120:121], off
	v_lshl_add_u64 v[116:117], v[116:117], 0, s[10:11]
	v_cvt_pk_bf16_f32 v114, v60, v61
	v_cvt_pk_bf16_f32 v115, v62, v63
	s_waitcnt vmcnt(45)
	global_store_dwordx2 v[118:119], v[114:115], off
	v_lshl_add_u64 v[118:119], v[118:119], 0, s[10:11]
	v_mul_f32_e32 v64, 0x3fb8aa3b, v28
	v_mul_f32_e32 v65, 0x3fb8aa3b, v29
	v_mul_f32_e32 v66, 0x3fb8aa3b, v30
	v_mul_f32_e32 v67, 0x3fb8aa3b, v31
	v_exp_f32_e32 v64, v64
	v_exp_f32_e32 v65, v65
	v_exp_f32_e32 v66, v66
	v_exp_f32_e32 v67, v67
	v_lshlrev_b32_e32 v68, 16, v50
	v_and_b32_e32 v69, 0xffff0000, v50
	v_lshlrev_b32_e32 v70, 16, v51
	v_and_b32_e32 v71, 0xffff0000, v51
	v_pk_fma_f32 v[60:61], v[60:61], v[64:65], v[68:69]
	v_pk_fma_f32 v[62:63], v[62:63], v[66:67], v[70:71]
	global_load_dwordx2 v[50:51], v[116:117], off
	global_load_dwordx4 v[28:31], v[120:121], off offset:2048
	v_lshl_add_u64 v[116:117], v[116:117], 0, s[10:11]
	v_lshl_add_u64 v[120:121], v[120:121], 0, s[100:101]
	v_cvt_pk_bf16_f32 v112, v60, v61
	v_cvt_pk_bf16_f32 v113, v62, v63
	s_waitcnt vmcnt(45)
	global_store_dwordx2 v[118:119], v[112:113], off
	v_lshl_add_u64 v[118:119], v[118:119], 0, s[10:11]
	v_mul_f32_e32 v64, 0x3fb8aa3b, v72
	v_mul_f32_e32 v65, 0x3fb8aa3b, v73
	v_mul_f32_e32 v66, 0x3fb8aa3b, v74
	v_mul_f32_e32 v67, 0x3fb8aa3b, v75
	v_exp_f32_e32 v64, v64
	v_exp_f32_e32 v65, v65
	v_exp_f32_e32 v66, v66
	v_exp_f32_e32 v67, v67
	v_lshlrev_b32_e32 v68, 16, v52
	v_and_b32_e32 v69, 0xffff0000, v52
	v_lshlrev_b32_e32 v70, 16, v53
	v_and_b32_e32 v71, 0xffff0000, v53
	v_pk_fma_f32 v[60:61], v[60:61], v[64:65], v[68:69]
	v_pk_fma_f32 v[62:63], v[62:63], v[66:67], v[70:71]
	global_load_dwordx2 v[52:53], v[116:117], off
	global_load_dwordx4 v[72:75], v[120:121], off
	v_lshl_add_u64 v[116:117], v[116:117], 0, s[10:11]
	v_cvt_pk_bf16_f32 v114, v60, v61
	v_cvt_pk_bf16_f32 v115, v62, v63
	s_waitcnt vmcnt(45)
	global_store_dwordx2 v[118:119], v[114:115], off
	v_lshl_add_u64 v[118:119], v[118:119], 0, s[10:11]
	v_mul_f32_e32 v64, 0x3fb8aa3b, v76
	v_mul_f32_e32 v65, 0x3fb8aa3b, v77
	v_mul_f32_e32 v66, 0x3fb8aa3b, v78
	v_mul_f32_e32 v67, 0x3fb8aa3b, v79
	v_exp_f32_e32 v64, v64
	v_exp_f32_e32 v65, v65
	v_exp_f32_e32 v66, v66
	v_exp_f32_e32 v67, v67
	v_lshlrev_b32_e32 v68, 16, v54
	v_and_b32_e32 v69, 0xffff0000, v54
	v_lshlrev_b32_e32 v70, 16, v55
	v_and_b32_e32 v71, 0xffff0000, v55
	v_pk_fma_f32 v[60:61], v[60:61], v[64:65], v[68:69]
	v_pk_fma_f32 v[62:63], v[62:63], v[66:67], v[70:71]
	global_load_dwordx2 v[54:55], v[116:117], off
	global_load_dwordx4 v[76:79], v[120:121], off offset:2048
	v_lshl_add_u64 v[116:117], v[116:117], 0, s[10:11]
	v_lshl_add_u64 v[120:121], v[120:121], 0, s[100:101]
	v_cvt_pk_bf16_f32 v112, v60, v61
	v_cvt_pk_bf16_f32 v113, v62, v63
	s_waitcnt vmcnt(45)
	global_store_dwordx2 v[118:119], v[112:113], off
	v_lshl_add_u64 v[118:119], v[118:119], 0, s[10:11]
	v_mul_f32_e32 v64, 0x3fb8aa3b, v80
	v_mul_f32_e32 v65, 0x3fb8aa3b, v81
	v_mul_f32_e32 v66, 0x3fb8aa3b, v82
	v_mul_f32_e32 v67, 0x3fb8aa3b, v83
	v_exp_f32_e32 v64, v64
	v_exp_f32_e32 v65, v65
	v_exp_f32_e32 v66, v66
	v_exp_f32_e32 v67, v67
	v_lshlrev_b32_e32 v68, 16, v56
	v_and_b32_e32 v69, 0xffff0000, v56
	v_lshlrev_b32_e32 v70, 16, v57
	v_and_b32_e32 v71, 0xffff0000, v57
	v_pk_fma_f32 v[60:61], v[60:61], v[64:65], v[68:69]
	v_pk_fma_f32 v[62:63], v[62:63], v[66:67], v[70:71]
	global_load_dwordx2 v[56:57], v[116:117], off
	global_load_dwordx4 v[80:83], v[120:121], off
	v_lshl_add_u64 v[116:117], v[116:117], 0, s[10:11]
	v_cvt_pk_bf16_f32 v114, v60, v61
	v_cvt_pk_bf16_f32 v115, v62, v63
	s_waitcnt vmcnt(45)
	global_store_dwordx2 v[118:119], v[114:115], off
	v_lshl_add_u64 v[118:119], v[118:119], 0, s[10:11]
	v_mul_f32_e32 v64, 0x3fb8aa3b, v84
	v_mul_f32_e32 v65, 0x3fb8aa3b, v85
	v_mul_f32_e32 v66, 0x3fb8aa3b, v86
	v_mul_f32_e32 v67, 0x3fb8aa3b, v87
	v_exp_f32_e32 v64, v64
	v_exp_f32_e32 v65, v65
	v_exp_f32_e32 v66, v66
	v_exp_f32_e32 v67, v67
	v_lshlrev_b32_e32 v68, 16, v58
	v_and_b32_e32 v69, 0xffff0000, v58
	v_lshlrev_b32_e32 v70, 16, v59
	v_and_b32_e32 v71, 0xffff0000, v59
	v_pk_fma_f32 v[60:61], v[60:61], v[64:65], v[68:69]
	v_pk_fma_f32 v[62:63], v[62:63], v[66:67], v[70:71]
	global_load_dwordx2 v[58:59], v[116:117], off
	global_load_dwordx4 v[84:87], v[120:121], off offset:2048
	v_lshl_add_u64 v[116:117], v[116:117], 0, s[10:11]
	v_lshl_add_u64 v[120:121], v[120:121], 0, s[100:101]
	v_cvt_pk_bf16_f32 v112, v60, v61
	v_cvt_pk_bf16_f32 v113, v62, v63
	s_waitcnt vmcnt(45)
	global_store_dwordx2 v[118:119], v[112:113], off
	v_lshl_add_u64 v[118:119], v[118:119], 0, s[10:11]
	v_mul_f32_e32 v64, 0x3fb8aa3b, v88
	v_mul_f32_e32 v65, 0x3fb8aa3b, v89
	v_mul_f32_e32 v66, 0x3fb8aa3b, v90
	v_mul_f32_e32 v67, 0x3fb8aa3b, v91
	v_exp_f32_e32 v64, v64
	v_exp_f32_e32 v65, v65
	v_exp_f32_e32 v66, v66
	v_exp_f32_e32 v67, v67
	v_lshlrev_b32_e32 v68, 16, v104
	v_and_b32_e32 v69, 0xffff0000, v104
	v_lshlrev_b32_e32 v70, 16, v105
	v_and_b32_e32 v71, 0xffff0000, v105
	v_pk_fma_f32 v[60:61], v[60:61], v[64:65], v[68:69]
	v_pk_fma_f32 v[62:63], v[62:63], v[66:67], v[70:71]
	global_load_dwordx2 v[104:105], v[116:117], off
	global_load_dwordx4 v[88:91], v[120:121], off
	v_lshl_add_u64 v[116:117], v[116:117], 0, s[10:11]
	v_cvt_pk_bf16_f32 v114, v60, v61
	v_cvt_pk_bf16_f32 v115, v62, v63
	s_waitcnt vmcnt(45)
	global_store_dwordx2 v[118:119], v[114:115], off
	v_lshl_add_u64 v[118:119], v[118:119], 0, s[10:11]
	v_mul_f32_e32 v64, 0x3fb8aa3b, v92
	v_mul_f32_e32 v65, 0x3fb8aa3b, v93
	v_mul_f32_e32 v66, 0x3fb8aa3b, v94
	v_mul_f32_e32 v67, 0x3fb8aa3b, v95
	v_exp_f32_e32 v64, v64
	v_exp_f32_e32 v65, v65
	v_exp_f32_e32 v66, v66
	v_exp_f32_e32 v67, v67
	v_lshlrev_b32_e32 v68, 16, v106
	v_and_b32_e32 v69, 0xffff0000, v106
	v_lshlrev_b32_e32 v70, 16, v107
	v_and_b32_e32 v71, 0xffff0000, v107
	v_pk_fma_f32 v[60:61], v[60:61], v[64:65], v[68:69]
	v_pk_fma_f32 v[62:63], v[62:63], v[66:67], v[70:71]
	global_load_dwordx2 v[106:107], v[116:117], off
	global_load_dwordx4 v[92:95], v[120:121], off offset:2048
	v_lshl_add_u64 v[116:117], v[116:117], 0, s[10:11]
	v_lshl_add_u64 v[120:121], v[120:121], 0, s[100:101]
	v_cvt_pk_bf16_f32 v112, v60, v61
	v_cvt_pk_bf16_f32 v113, v62, v63
	s_waitcnt vmcnt(45)
	global_store_dwordx2 v[118:119], v[112:113], off
	v_lshl_add_u64 v[118:119], v[118:119], 0, s[10:11]
	v_mul_f32_e32 v64, 0x3fb8aa3b, v96
	v_mul_f32_e32 v65, 0x3fb8aa3b, v97
	v_mul_f32_e32 v66, 0x3fb8aa3b, v98
	v_mul_f32_e32 v67, 0x3fb8aa3b, v99
	v_exp_f32_e32 v64, v64
	v_exp_f32_e32 v65, v65
	v_exp_f32_e32 v66, v66
	v_exp_f32_e32 v67, v67
	v_lshlrev_b32_e32 v68, 16, v108
	v_and_b32_e32 v69, 0xffff0000, v108
	v_lshlrev_b32_e32 v70, 16, v109
	v_and_b32_e32 v71, 0xffff0000, v109
	v_pk_fma_f32 v[60:61], v[60:61], v[64:65], v[68:69]
	v_pk_fma_f32 v[62:63], v[62:63], v[66:67], v[70:71]
	global_load_dwordx2 v[108:109], v[116:117], off
	global_load_dwordx4 v[96:99], v[120:121], off
	v_lshl_add_u64 v[116:117], v[116:117], 0, s[10:11]
	v_cvt_pk_bf16_f32 v114, v60, v61
	v_cvt_pk_bf16_f32 v115, v62, v63
	s_waitcnt vmcnt(45)
	global_store_dwordx2 v[118:119], v[114:115], off
	v_lshl_add_u64 v[118:119], v[118:119], 0, s[10:11]
	v_mul_f32_e32 v64, 0x3fb8aa3b, v100
	v_mul_f32_e32 v65, 0x3fb8aa3b, v101
	v_mul_f32_e32 v66, 0x3fb8aa3b, v102
	v_mul_f32_e32 v67, 0x3fb8aa3b, v103
	v_exp_f32_e32 v64, v64
	v_exp_f32_e32 v65, v65
	v_exp_f32_e32 v66, v66
	v_exp_f32_e32 v67, v67
	v_lshlrev_b32_e32 v68, 16, v110
	v_and_b32_e32 v69, 0xffff0000, v110
	v_lshlrev_b32_e32 v70, 16, v111
	v_and_b32_e32 v71, 0xffff0000, v111
	v_pk_fma_f32 v[60:61], v[60:61], v[64:65], v[68:69]
	v_pk_fma_f32 v[62:63], v[62:63], v[66:67], v[70:71]
	global_load_dwordx2 v[110:111], v[116:117], off
	global_load_dwordx4 v[100:103], v[120:121], off offset:2048
	v_lshl_add_u64 v[116:117], v[116:117], 0, s[10:11]
	v_lshl_add_u64 v[120:121], v[120:121], 0, s[100:101]
	v_cvt_pk_bf16_f32 v112, v60, v61
	v_cvt_pk_bf16_f32 v113, v62, v63
	s_waitcnt vmcnt(45)
	global_store_dwordx2 v[118:119], v[112:113], off
	v_lshl_add_u64 v[118:119], v[118:119], 0, s[10:11]
	v_mul_f32_e32 v64, 0x3fb8aa3b, v0
	v_mul_f32_e32 v65, 0x3fb8aa3b, v1
	v_mul_f32_e32 v66, 0x3fb8aa3b, v2
	v_mul_f32_e32 v67, 0x3fb8aa3b, v3
	v_exp_f32_e32 v64, v64
	v_exp_f32_e32 v65, v65
	v_exp_f32_e32 v66, v66
	v_exp_f32_e32 v67, v67
	v_lshlrev_b32_e32 v68, 16, v36
	v_and_b32_e32 v69, 0xffff0000, v36
	v_lshlrev_b32_e32 v70, 16, v37
	v_and_b32_e32 v71, 0xffff0000, v37
	v_pk_fma_f32 v[60:61], v[60:61], v[64:65], v[68:69]
	v_pk_fma_f32 v[62:63], v[62:63], v[66:67], v[70:71]
	global_load_dwordx2 v[36:37], v[116:117], off
	global_load_dwordx4 v[0:3], v[120:121], off
	v_lshl_add_u64 v[116:117], v[116:117], 0, s[10:11]
	v_cvt_pk_bf16_f32 v114, v60, v61
	v_cvt_pk_bf16_f32 v115, v62, v63
	s_waitcnt vmcnt(45)
	global_store_dwordx2 v[118:119], v[114:115], off
	v_lshl_add_u64 v[118:119], v[118:119], 0, s[10:11]
	v_mul_f32_e32 v64, 0x3fb8aa3b, v4
	v_mul_f32_e32 v65, 0x3fb8aa3b, v5
	v_mul_f32_e32 v66, 0x3fb8aa3b, v6
	v_mul_f32_e32 v67, 0x3fb8aa3b, v7
	v_exp_f32_e32 v64, v64
	v_exp_f32_e32 v65, v65
	v_exp_f32_e32 v66, v66
	v_exp_f32_e32 v67, v67
	v_lshlrev_b32_e32 v68, 16, v38
	v_and_b32_e32 v69, 0xffff0000, v38
	v_lshlrev_b32_e32 v70, 16, v39
	v_and_b32_e32 v71, 0xffff0000, v39
	v_pk_fma_f32 v[60:61], v[60:61], v[64:65], v[68:69]
	v_pk_fma_f32 v[62:63], v[62:63], v[66:67], v[70:71]
	global_load_dwordx2 v[38:39], v[116:117], off
	global_load_dwordx4 v[4:7], v[120:121], off offset:2048
	v_lshl_add_u64 v[116:117], v[116:117], 0, s[10:11]
	v_lshl_add_u64 v[120:121], v[120:121], 0, s[100:101]
	v_cvt_pk_bf16_f32 v112, v60, v61
	v_cvt_pk_bf16_f32 v113, v62, v63
	s_waitcnt vmcnt(45)
	global_store_dwordx2 v[118:119], v[112:113], off
	v_lshl_add_u64 v[118:119], v[118:119], 0, s[10:11]
	v_mul_f32_e32 v64, 0x3fb8aa3b, v8
	v_mul_f32_e32 v65, 0x3fb8aa3b, v9
	v_mul_f32_e32 v66, 0x3fb8aa3b, v10
	v_mul_f32_e32 v67, 0x3fb8aa3b, v11
	v_exp_f32_e32 v64, v64
	v_exp_f32_e32 v65, v65
	v_exp_f32_e32 v66, v66
	v_exp_f32_e32 v67, v67
	v_lshlrev_b32_e32 v68, 16, v40
	v_and_b32_e32 v69, 0xffff0000, v40
	v_lshlrev_b32_e32 v70, 16, v41
	v_and_b32_e32 v71, 0xffff0000, v41
	v_pk_fma_f32 v[60:61], v[60:61], v[64:65], v[68:69]
	v_pk_fma_f32 v[62:63], v[62:63], v[66:67], v[70:71]
	global_load_dwordx2 v[40:41], v[116:117], off
	global_load_dwordx4 v[8:11], v[120:121], off
	v_lshl_add_u64 v[116:117], v[116:117], 0, s[10:11]
	v_cvt_pk_bf16_f32 v114, v60, v61
	v_cvt_pk_bf16_f32 v115, v62, v63
	s_waitcnt vmcnt(45)
	global_store_dwordx2 v[118:119], v[114:115], off
	v_lshl_add_u64 v[118:119], v[118:119], 0, s[10:11]
	v_mul_f32_e32 v64, 0x3fb8aa3b, v12
	v_mul_f32_e32 v65, 0x3fb8aa3b, v13
	v_mul_f32_e32 v66, 0x3fb8aa3b, v14
	v_mul_f32_e32 v67, 0x3fb8aa3b, v15
	v_exp_f32_e32 v64, v64
	v_exp_f32_e32 v65, v65
	v_exp_f32_e32 v66, v66
	v_exp_f32_e32 v67, v67
	v_lshlrev_b32_e32 v68, 16, v42
	v_and_b32_e32 v69, 0xffff0000, v42
	v_lshlrev_b32_e32 v70, 16, v43
	v_and_b32_e32 v71, 0xffff0000, v43
	v_pk_fma_f32 v[60:61], v[60:61], v[64:65], v[68:69]
	v_pk_fma_f32 v[62:63], v[62:63], v[66:67], v[70:71]
	global_load_dwordx2 v[42:43], v[116:117], off
	global_load_dwordx4 v[12:15], v[120:121], off offset:2048
	v_lshl_add_u64 v[116:117], v[116:117], 0, s[10:11]
	v_lshl_add_u64 v[120:121], v[120:121], 0, s[100:101]
	v_cvt_pk_bf16_f32 v112, v60, v61
	v_cvt_pk_bf16_f32 v113, v62, v63
	s_waitcnt vmcnt(45)
	global_store_dwordx2 v[118:119], v[112:113], off
	v_lshl_add_u64 v[118:119], v[118:119], 0, s[10:11]
	v_mul_f32_e32 v64, 0x3fb8aa3b, v16
	v_mul_f32_e32 v65, 0x3fb8aa3b, v17
	v_mul_f32_e32 v66, 0x3fb8aa3b, v18
	v_mul_f32_e32 v67, 0x3fb8aa3b, v19
	v_exp_f32_e32 v64, v64
	v_exp_f32_e32 v65, v65
	v_exp_f32_e32 v66, v66
	v_exp_f32_e32 v67, v67
	v_lshlrev_b32_e32 v68, 16, v44
	v_and_b32_e32 v69, 0xffff0000, v44
	v_lshlrev_b32_e32 v70, 16, v45
	v_and_b32_e32 v71, 0xffff0000, v45
	v_pk_fma_f32 v[60:61], v[60:61], v[64:65], v[68:69]
	v_pk_fma_f32 v[62:63], v[62:63], v[66:67], v[70:71]
	global_load_dwordx2 v[44:45], v[116:117], off
	global_load_dwordx4 v[16:19], v[120:121], off
	v_lshl_add_u64 v[116:117], v[116:117], 0, s[10:11]
	v_cvt_pk_bf16_f32 v114, v60, v61
	v_cvt_pk_bf16_f32 v115, v62, v63
	s_waitcnt vmcnt(45)
	global_store_dwordx2 v[118:119], v[114:115], off
	v_lshl_add_u64 v[118:119], v[118:119], 0, s[10:11]
	v_mul_f32_e32 v64, 0x3fb8aa3b, v20
	v_mul_f32_e32 v65, 0x3fb8aa3b, v21
	v_mul_f32_e32 v66, 0x3fb8aa3b, v22
	v_mul_f32_e32 v67, 0x3fb8aa3b, v23
	v_exp_f32_e32 v64, v64
	v_exp_f32_e32 v65, v65
	v_exp_f32_e32 v66, v66
	v_exp_f32_e32 v67, v67
	v_lshlrev_b32_e32 v68, 16, v46
	v_and_b32_e32 v69, 0xffff0000, v46
	v_lshlrev_b32_e32 v70, 16, v47
	v_and_b32_e32 v71, 0xffff0000, v47
	v_pk_fma_f32 v[60:61], v[60:61], v[64:65], v[68:69]
	v_pk_fma_f32 v[62:63], v[62:63], v[66:67], v[70:71]
	global_load_dwordx2 v[46:47], v[116:117], off
	global_load_dwordx4 v[20:23], v[120:121], off offset:2048
	v_lshl_add_u64 v[116:117], v[116:117], 0, s[10:11]
	v_lshl_add_u64 v[120:121], v[120:121], 0, s[100:101]
	v_cvt_pk_bf16_f32 v112, v60, v61
	v_cvt_pk_bf16_f32 v113, v62, v63
	s_waitcnt vmcnt(45)
	global_store_dwordx2 v[118:119], v[112:113], off
	v_lshl_add_u64 v[118:119], v[118:119], 0, s[10:11]
	v_mul_f32_e32 v64, 0x3fb8aa3b, v24
	v_mul_f32_e32 v65, 0x3fb8aa3b, v25
	v_mul_f32_e32 v66, 0x3fb8aa3b, v26
	v_mul_f32_e32 v67, 0x3fb8aa3b, v27
	v_exp_f32_e32 v64, v64
	v_exp_f32_e32 v65, v65
	v_exp_f32_e32 v66, v66
	v_exp_f32_e32 v67, v67
	v_lshlrev_b32_e32 v68, 16, v48
	v_and_b32_e32 v69, 0xffff0000, v48
	v_lshlrev_b32_e32 v70, 16, v49
	v_and_b32_e32 v71, 0xffff0000, v49
	v_pk_fma_f32 v[60:61], v[60:61], v[64:65], v[68:69]
	v_pk_fma_f32 v[62:63], v[62:63], v[66:67], v[70:71]
	global_load_dwordx2 v[48:49], v[116:117], off
	global_load_dwordx4 v[24:27], v[120:121], off
	v_lshl_add_u64 v[116:117], v[116:117], 0, s[10:11]
	v_cvt_pk_bf16_f32 v114, v60, v61
	v_cvt_pk_bf16_f32 v115, v62, v63
	s_waitcnt vmcnt(45)
	global_store_dwordx2 v[118:119], v[114:115], off
	v_lshl_add_u64 v[118:119], v[118:119], 0, s[10:11]
	v_mul_f32_e32 v64, 0x3fb8aa3b, v28
	v_mul_f32_e32 v65, 0x3fb8aa3b, v29
	v_mul_f32_e32 v66, 0x3fb8aa3b, v30
	v_mul_f32_e32 v67, 0x3fb8aa3b, v31
	v_exp_f32_e32 v64, v64
	v_exp_f32_e32 v65, v65
	v_exp_f32_e32 v66, v66
	v_exp_f32_e32 v67, v67
	v_lshlrev_b32_e32 v68, 16, v50
	v_and_b32_e32 v69, 0xffff0000, v50
	v_lshlrev_b32_e32 v70, 16, v51
	v_and_b32_e32 v71, 0xffff0000, v51
	v_pk_fma_f32 v[60:61], v[60:61], v[64:65], v[68:69]
	v_pk_fma_f32 v[62:63], v[62:63], v[66:67], v[70:71]
	global_load_dwordx2 v[50:51], v[116:117], off
	global_load_dwordx4 v[28:31], v[120:121], off offset:2048
	v_lshl_add_u64 v[116:117], v[116:117], 0, s[10:11]
	v_lshl_add_u64 v[120:121], v[120:121], 0, s[100:101]
	v_cvt_pk_bf16_f32 v112, v60, v61
	v_cvt_pk_bf16_f32 v113, v62, v63
	s_waitcnt vmcnt(45)
	global_store_dwordx2 v[118:119], v[112:113], off
	v_lshl_add_u64 v[118:119], v[118:119], 0, s[10:11]
	v_mul_f32_e32 v64, 0x3fb8aa3b, v72
	v_mul_f32_e32 v65, 0x3fb8aa3b, v73
	v_mul_f32_e32 v66, 0x3fb8aa3b, v74
	v_mul_f32_e32 v67, 0x3fb8aa3b, v75
	v_exp_f32_e32 v64, v64
	v_exp_f32_e32 v65, v65
	v_exp_f32_e32 v66, v66
	v_exp_f32_e32 v67, v67
	v_lshlrev_b32_e32 v68, 16, v52
	v_and_b32_e32 v69, 0xffff0000, v52
	v_lshlrev_b32_e32 v70, 16, v53
	v_and_b32_e32 v71, 0xffff0000, v53
	v_pk_fma_f32 v[60:61], v[60:61], v[64:65], v[68:69]
	v_pk_fma_f32 v[62:63], v[62:63], v[66:67], v[70:71]
	global_load_dwordx2 v[52:53], v[116:117], off
	global_load_dwordx4 v[72:75], v[120:121], off
	v_lshl_add_u64 v[116:117], v[116:117], 0, s[10:11]
	v_cvt_pk_bf16_f32 v114, v60, v61
	v_cvt_pk_bf16_f32 v115, v62, v63
	s_waitcnt vmcnt(45)
	global_store_dwordx2 v[118:119], v[114:115], off
	v_lshl_add_u64 v[118:119], v[118:119], 0, s[10:11]
	v_mul_f32_e32 v64, 0x3fb8aa3b, v76
	v_mul_f32_e32 v65, 0x3fb8aa3b, v77
	v_mul_f32_e32 v66, 0x3fb8aa3b, v78
	v_mul_f32_e32 v67, 0x3fb8aa3b, v79
	v_exp_f32_e32 v64, v64
	v_exp_f32_e32 v65, v65
	v_exp_f32_e32 v66, v66
	v_exp_f32_e32 v67, v67
	v_lshlrev_b32_e32 v68, 16, v54
	v_and_b32_e32 v69, 0xffff0000, v54
	v_lshlrev_b32_e32 v70, 16, v55
	v_and_b32_e32 v71, 0xffff0000, v55
	v_pk_fma_f32 v[60:61], v[60:61], v[64:65], v[68:69]
	v_pk_fma_f32 v[62:63], v[62:63], v[66:67], v[70:71]
	global_load_dwordx2 v[54:55], v[116:117], off
	global_load_dwordx4 v[76:79], v[120:121], off offset:2048
	v_lshl_add_u64 v[116:117], v[116:117], 0, s[10:11]
	v_lshl_add_u64 v[120:121], v[120:121], 0, s[100:101]
	v_cvt_pk_bf16_f32 v112, v60, v61
	v_cvt_pk_bf16_f32 v113, v62, v63
	s_waitcnt vmcnt(45)
	global_store_dwordx2 v[118:119], v[112:113], off
	v_lshl_add_u64 v[118:119], v[118:119], 0, s[10:11]
	v_mul_f32_e32 v64, 0x3fb8aa3b, v80
	v_mul_f32_e32 v65, 0x3fb8aa3b, v81
	v_mul_f32_e32 v66, 0x3fb8aa3b, v82
	v_mul_f32_e32 v67, 0x3fb8aa3b, v83
	v_exp_f32_e32 v64, v64
	v_exp_f32_e32 v65, v65
	v_exp_f32_e32 v66, v66
	v_exp_f32_e32 v67, v67
	v_lshlrev_b32_e32 v68, 16, v56
	v_and_b32_e32 v69, 0xffff0000, v56
	v_lshlrev_b32_e32 v70, 16, v57
	v_and_b32_e32 v71, 0xffff0000, v57
	v_pk_fma_f32 v[60:61], v[60:61], v[64:65], v[68:69]
	v_pk_fma_f32 v[62:63], v[62:63], v[66:67], v[70:71]
	global_load_dwordx2 v[56:57], v[116:117], off
	global_load_dwordx4 v[80:83], v[120:121], off
	v_lshl_add_u64 v[116:117], v[116:117], 0, s[10:11]
	v_cvt_pk_bf16_f32 v114, v60, v61
	v_cvt_pk_bf16_f32 v115, v62, v63
	s_waitcnt vmcnt(45)
	global_store_dwordx2 v[118:119], v[114:115], off
	v_lshl_add_u64 v[118:119], v[118:119], 0, s[10:11]
	v_mul_f32_e32 v64, 0x3fb8aa3b, v84
	v_mul_f32_e32 v65, 0x3fb8aa3b, v85
	v_mul_f32_e32 v66, 0x3fb8aa3b, v86
	v_mul_f32_e32 v67, 0x3fb8aa3b, v87
	v_exp_f32_e32 v64, v64
	v_exp_f32_e32 v65, v65
	v_exp_f32_e32 v66, v66
	v_exp_f32_e32 v67, v67
	v_lshlrev_b32_e32 v68, 16, v58
	v_and_b32_e32 v69, 0xffff0000, v58
	v_lshlrev_b32_e32 v70, 16, v59
	v_and_b32_e32 v71, 0xffff0000, v59
	v_pk_fma_f32 v[60:61], v[60:61], v[64:65], v[68:69]
	v_pk_fma_f32 v[62:63], v[62:63], v[66:67], v[70:71]
	global_load_dwordx2 v[58:59], v[116:117], off
	global_load_dwordx4 v[84:87], v[120:121], off offset:2048
	v_lshl_add_u64 v[116:117], v[116:117], 0, s[10:11]
	v_lshl_add_u64 v[120:121], v[120:121], 0, s[100:101]
	v_cvt_pk_bf16_f32 v112, v60, v61
	v_cvt_pk_bf16_f32 v113, v62, v63
	s_waitcnt vmcnt(45)
	global_store_dwordx2 v[118:119], v[112:113], off
	v_lshl_add_u64 v[118:119], v[118:119], 0, s[10:11]
	v_mul_f32_e32 v64, 0x3fb8aa3b, v88
	v_mul_f32_e32 v65, 0x3fb8aa3b, v89
	v_mul_f32_e32 v66, 0x3fb8aa3b, v90
	v_mul_f32_e32 v67, 0x3fb8aa3b, v91
	v_exp_f32_e32 v64, v64
	v_exp_f32_e32 v65, v65
	v_exp_f32_e32 v66, v66
	v_exp_f32_e32 v67, v67
	v_lshlrev_b32_e32 v68, 16, v104
	v_and_b32_e32 v69, 0xffff0000, v104
	v_lshlrev_b32_e32 v70, 16, v105
	v_and_b32_e32 v71, 0xffff0000, v105
	v_pk_fma_f32 v[60:61], v[60:61], v[64:65], v[68:69]
	v_pk_fma_f32 v[62:63], v[62:63], v[66:67], v[70:71]
	global_load_dwordx2 v[104:105], v[116:117], off
	global_load_dwordx4 v[88:91], v[120:121], off
	v_lshl_add_u64 v[116:117], v[116:117], 0, s[10:11]
	v_cvt_pk_bf16_f32 v114, v60, v61
	v_cvt_pk_bf16_f32 v115, v62, v63
	s_waitcnt vmcnt(45)
	global_store_dwordx2 v[118:119], v[114:115], off
	v_lshl_add_u64 v[118:119], v[118:119], 0, s[10:11]
	v_mul_f32_e32 v64, 0x3fb8aa3b, v92
	v_mul_f32_e32 v65, 0x3fb8aa3b, v93
	v_mul_f32_e32 v66, 0x3fb8aa3b, v94
	v_mul_f32_e32 v67, 0x3fb8aa3b, v95
	v_exp_f32_e32 v64, v64
	v_exp_f32_e32 v65, v65
	v_exp_f32_e32 v66, v66
	v_exp_f32_e32 v67, v67
	v_lshlrev_b32_e32 v68, 16, v106
	v_and_b32_e32 v69, 0xffff0000, v106
	v_lshlrev_b32_e32 v70, 16, v107
	v_and_b32_e32 v71, 0xffff0000, v107
	v_pk_fma_f32 v[60:61], v[60:61], v[64:65], v[68:69]
	v_pk_fma_f32 v[62:63], v[62:63], v[66:67], v[70:71]
	global_load_dwordx2 v[106:107], v[116:117], off
	global_load_dwordx4 v[92:95], v[120:121], off offset:2048
	v_lshl_add_u64 v[116:117], v[116:117], 0, s[10:11]
	v_lshl_add_u64 v[120:121], v[120:121], 0, s[100:101]
	v_cvt_pk_bf16_f32 v112, v60, v61
	v_cvt_pk_bf16_f32 v113, v62, v63
	s_waitcnt vmcnt(45)
	global_store_dwordx2 v[118:119], v[112:113], off
	v_lshl_add_u64 v[118:119], v[118:119], 0, s[10:11]
	v_mul_f32_e32 v64, 0x3fb8aa3b, v96
	v_mul_f32_e32 v65, 0x3fb8aa3b, v97
	v_mul_f32_e32 v66, 0x3fb8aa3b, v98
	v_mul_f32_e32 v67, 0x3fb8aa3b, v99
	v_exp_f32_e32 v64, v64
	v_exp_f32_e32 v65, v65
	v_exp_f32_e32 v66, v66
	v_exp_f32_e32 v67, v67
	v_lshlrev_b32_e32 v68, 16, v108
	v_and_b32_e32 v69, 0xffff0000, v108
	v_lshlrev_b32_e32 v70, 16, v109
	v_and_b32_e32 v71, 0xffff0000, v109
	v_pk_fma_f32 v[60:61], v[60:61], v[64:65], v[68:69]
	v_pk_fma_f32 v[62:63], v[62:63], v[66:67], v[70:71]
	global_load_dwordx2 v[108:109], v[116:117], off
	global_load_dwordx4 v[96:99], v[120:121], off
	v_lshl_add_u64 v[116:117], v[116:117], 0, s[10:11]
	v_cvt_pk_bf16_f32 v114, v60, v61
	v_cvt_pk_bf16_f32 v115, v62, v63
	s_waitcnt vmcnt(45)
	global_store_dwordx2 v[118:119], v[114:115], off
	v_lshl_add_u64 v[118:119], v[118:119], 0, s[10:11]
	v_mul_f32_e32 v64, 0x3fb8aa3b, v100
	v_mul_f32_e32 v65, 0x3fb8aa3b, v101
	v_mul_f32_e32 v66, 0x3fb8aa3b, v102
	v_mul_f32_e32 v67, 0x3fb8aa3b, v103
	v_exp_f32_e32 v64, v64
	v_exp_f32_e32 v65, v65
	v_exp_f32_e32 v66, v66
	v_exp_f32_e32 v67, v67
	v_lshlrev_b32_e32 v68, 16, v110
	v_and_b32_e32 v69, 0xffff0000, v110
	v_lshlrev_b32_e32 v70, 16, v111
	v_and_b32_e32 v71, 0xffff0000, v111
	v_pk_fma_f32 v[60:61], v[60:61], v[64:65], v[68:69]
	v_pk_fma_f32 v[62:63], v[62:63], v[66:67], v[70:71]
	global_load_dwordx2 v[110:111], v[116:117], off
	global_load_dwordx4 v[100:103], v[120:121], off offset:2048
	v_lshl_add_u64 v[116:117], v[116:117], 0, s[10:11]
	v_lshl_add_u64 v[120:121], v[120:121], 0, s[100:101]
	v_cvt_pk_bf16_f32 v112, v60, v61
	v_cvt_pk_bf16_f32 v113, v62, v63
	s_waitcnt vmcnt(45)
	global_store_dwordx2 v[118:119], v[112:113], off
	v_lshl_add_u64 v[118:119], v[118:119], 0, s[10:11]
	v_mul_f32_e32 v64, 0x3fb8aa3b, v0
	v_mul_f32_e32 v65, 0x3fb8aa3b, v1
	v_mul_f32_e32 v66, 0x3fb8aa3b, v2
	v_mul_f32_e32 v67, 0x3fb8aa3b, v3
	v_exp_f32_e32 v64, v64
	v_exp_f32_e32 v65, v65
	v_exp_f32_e32 v66, v66
	v_exp_f32_e32 v67, v67
	v_lshlrev_b32_e32 v68, 16, v36
	v_and_b32_e32 v69, 0xffff0000, v36
	v_lshlrev_b32_e32 v70, 16, v37
	v_and_b32_e32 v71, 0xffff0000, v37
	v_pk_fma_f32 v[60:61], v[60:61], v[64:65], v[68:69]
	v_pk_fma_f32 v[62:63], v[62:63], v[66:67], v[70:71]
	global_load_dwordx2 v[36:37], v[116:117], off
	global_load_dwordx4 v[0:3], v[120:121], off
	v_lshl_add_u64 v[116:117], v[116:117], 0, s[10:11]
	v_cvt_pk_bf16_f32 v114, v60, v61
	v_cvt_pk_bf16_f32 v115, v62, v63
	s_waitcnt vmcnt(45)
	global_store_dwordx2 v[118:119], v[114:115], off
	v_lshl_add_u64 v[118:119], v[118:119], 0, s[10:11]
	v_mul_f32_e32 v64, 0x3fb8aa3b, v4
	v_mul_f32_e32 v65, 0x3fb8aa3b, v5
	v_mul_f32_e32 v66, 0x3fb8aa3b, v6
	v_mul_f32_e32 v67, 0x3fb8aa3b, v7
	v_exp_f32_e32 v64, v64
	v_exp_f32_e32 v65, v65
	v_exp_f32_e32 v66, v66
	v_exp_f32_e32 v67, v67
	v_lshlrev_b32_e32 v68, 16, v38
	v_and_b32_e32 v69, 0xffff0000, v38
	v_lshlrev_b32_e32 v70, 16, v39
	v_and_b32_e32 v71, 0xffff0000, v39
	v_pk_fma_f32 v[60:61], v[60:61], v[64:65], v[68:69]
	v_pk_fma_f32 v[62:63], v[62:63], v[66:67], v[70:71]
	global_load_dwordx2 v[38:39], v[116:117], off
	global_load_dwordx4 v[4:7], v[120:121], off offset:2048
	v_lshl_add_u64 v[116:117], v[116:117], 0, s[10:11]
	v_lshl_add_u64 v[120:121], v[120:121], 0, s[100:101]
	v_cvt_pk_bf16_f32 v112, v60, v61
	v_cvt_pk_bf16_f32 v113, v62, v63
	s_waitcnt vmcnt(45)
	global_store_dwordx2 v[118:119], v[112:113], off
	v_lshl_add_u64 v[118:119], v[118:119], 0, s[10:11]
	v_mul_f32_e32 v64, 0x3fb8aa3b, v8
	v_mul_f32_e32 v65, 0x3fb8aa3b, v9
	v_mul_f32_e32 v66, 0x3fb8aa3b, v10
	v_mul_f32_e32 v67, 0x3fb8aa3b, v11
	v_exp_f32_e32 v64, v64
	v_exp_f32_e32 v65, v65
	v_exp_f32_e32 v66, v66
	v_exp_f32_e32 v67, v67
	v_lshlrev_b32_e32 v68, 16, v40
	v_and_b32_e32 v69, 0xffff0000, v40
	v_lshlrev_b32_e32 v70, 16, v41
	v_and_b32_e32 v71, 0xffff0000, v41
	v_pk_fma_f32 v[60:61], v[60:61], v[64:65], v[68:69]
	v_pk_fma_f32 v[62:63], v[62:63], v[66:67], v[70:71]
	global_load_dwordx2 v[40:41], v[116:117], off
	global_load_dwordx4 v[8:11], v[120:121], off
	v_lshl_add_u64 v[116:117], v[116:117], 0, s[10:11]
	v_cvt_pk_bf16_f32 v114, v60, v61
	v_cvt_pk_bf16_f32 v115, v62, v63
	s_waitcnt vmcnt(45)
	global_store_dwordx2 v[118:119], v[114:115], off
	v_lshl_add_u64 v[118:119], v[118:119], 0, s[10:11]
	v_mul_f32_e32 v64, 0x3fb8aa3b, v12
	v_mul_f32_e32 v65, 0x3fb8aa3b, v13
	v_mul_f32_e32 v66, 0x3fb8aa3b, v14
	v_mul_f32_e32 v67, 0x3fb8aa3b, v15
	v_exp_f32_e32 v64, v64
	v_exp_f32_e32 v65, v65
	v_exp_f32_e32 v66, v66
	v_exp_f32_e32 v67, v67
	v_lshlrev_b32_e32 v68, 16, v42
	v_and_b32_e32 v69, 0xffff0000, v42
	v_lshlrev_b32_e32 v70, 16, v43
	v_and_b32_e32 v71, 0xffff0000, v43
	v_pk_fma_f32 v[60:61], v[60:61], v[64:65], v[68:69]
	v_pk_fma_f32 v[62:63], v[62:63], v[66:67], v[70:71]
	global_load_dwordx2 v[42:43], v[116:117], off
	global_load_dwordx4 v[12:15], v[120:121], off offset:2048
	v_lshl_add_u64 v[116:117], v[116:117], 0, s[10:11]
	v_lshl_add_u64 v[120:121], v[120:121], 0, s[100:101]
	v_cvt_pk_bf16_f32 v112, v60, v61
	v_cvt_pk_bf16_f32 v113, v62, v63
	s_waitcnt vmcnt(45)
	global_store_dwordx2 v[118:119], v[112:113], off
	v_lshl_add_u64 v[118:119], v[118:119], 0, s[10:11]
	v_mul_f32_e32 v64, 0x3fb8aa3b, v16
	v_mul_f32_e32 v65, 0x3fb8aa3b, v17
	v_mul_f32_e32 v66, 0x3fb8aa3b, v18
	v_mul_f32_e32 v67, 0x3fb8aa3b, v19
	v_exp_f32_e32 v64, v64
	v_exp_f32_e32 v65, v65
	v_exp_f32_e32 v66, v66
	v_exp_f32_e32 v67, v67
	v_lshlrev_b32_e32 v68, 16, v44
	v_and_b32_e32 v69, 0xffff0000, v44
	v_lshlrev_b32_e32 v70, 16, v45
	v_and_b32_e32 v71, 0xffff0000, v45
	v_pk_fma_f32 v[60:61], v[60:61], v[64:65], v[68:69]
	v_pk_fma_f32 v[62:63], v[62:63], v[66:67], v[70:71]
	global_load_dwordx2 v[44:45], v[116:117], off
	global_load_dwordx4 v[16:19], v[120:121], off
	v_lshl_add_u64 v[116:117], v[116:117], 0, s[10:11]
	v_cvt_pk_bf16_f32 v114, v60, v61
	v_cvt_pk_bf16_f32 v115, v62, v63
	s_waitcnt vmcnt(45)
	global_store_dwordx2 v[118:119], v[114:115], off
	v_lshl_add_u64 v[118:119], v[118:119], 0, s[10:11]
	v_mul_f32_e32 v64, 0x3fb8aa3b, v20
	v_mul_f32_e32 v65, 0x3fb8aa3b, v21
	v_mul_f32_e32 v66, 0x3fb8aa3b, v22
	v_mul_f32_e32 v67, 0x3fb8aa3b, v23
	v_exp_f32_e32 v64, v64
	v_exp_f32_e32 v65, v65
	v_exp_f32_e32 v66, v66
	v_exp_f32_e32 v67, v67
	v_lshlrev_b32_e32 v68, 16, v46
	v_and_b32_e32 v69, 0xffff0000, v46
	v_lshlrev_b32_e32 v70, 16, v47
	v_and_b32_e32 v71, 0xffff0000, v47
	v_pk_fma_f32 v[60:61], v[60:61], v[64:65], v[68:69]
	v_pk_fma_f32 v[62:63], v[62:63], v[66:67], v[70:71]
	global_load_dwordx2 v[46:47], v[116:117], off
	global_load_dwordx4 v[20:23], v[120:121], off offset:2048
	v_lshl_add_u64 v[116:117], v[116:117], 0, s[10:11]
	v_lshl_add_u64 v[120:121], v[120:121], 0, s[100:101]
	v_cvt_pk_bf16_f32 v112, v60, v61
	v_cvt_pk_bf16_f32 v113, v62, v63
	s_waitcnt vmcnt(45)
	global_store_dwordx2 v[118:119], v[112:113], off
	v_lshl_add_u64 v[118:119], v[118:119], 0, s[10:11]
	v_mul_f32_e32 v64, 0x3fb8aa3b, v24
	v_mul_f32_e32 v65, 0x3fb8aa3b, v25
	v_mul_f32_e32 v66, 0x3fb8aa3b, v26
	v_mul_f32_e32 v67, 0x3fb8aa3b, v27
	v_exp_f32_e32 v64, v64
	v_exp_f32_e32 v65, v65
	v_exp_f32_e32 v66, v66
	v_exp_f32_e32 v67, v67
	v_lshlrev_b32_e32 v68, 16, v48
	v_and_b32_e32 v69, 0xffff0000, v48
	v_lshlrev_b32_e32 v70, 16, v49
	v_and_b32_e32 v71, 0xffff0000, v49
	v_pk_fma_f32 v[60:61], v[60:61], v[64:65], v[68:69]
	v_pk_fma_f32 v[62:63], v[62:63], v[66:67], v[70:71]
	global_load_dwordx2 v[48:49], v[116:117], off
	global_load_dwordx4 v[24:27], v[120:121], off
	v_lshl_add_u64 v[116:117], v[116:117], 0, s[10:11]
	v_cvt_pk_bf16_f32 v114, v60, v61
	v_cvt_pk_bf16_f32 v115, v62, v63
	s_waitcnt vmcnt(45)
	global_store_dwordx2 v[118:119], v[114:115], off
	v_lshl_add_u64 v[118:119], v[118:119], 0, s[10:11]
	v_mul_f32_e32 v64, 0x3fb8aa3b, v28
	v_mul_f32_e32 v65, 0x3fb8aa3b, v29
	v_mul_f32_e32 v66, 0x3fb8aa3b, v30
	v_mul_f32_e32 v67, 0x3fb8aa3b, v31
	v_exp_f32_e32 v64, v64
	v_exp_f32_e32 v65, v65
	v_exp_f32_e32 v66, v66
	v_exp_f32_e32 v67, v67
	v_lshlrev_b32_e32 v68, 16, v50
	v_and_b32_e32 v69, 0xffff0000, v50
	v_lshlrev_b32_e32 v70, 16, v51
	v_and_b32_e32 v71, 0xffff0000, v51
	v_pk_fma_f32 v[60:61], v[60:61], v[64:65], v[68:69]
	v_pk_fma_f32 v[62:63], v[62:63], v[66:67], v[70:71]
	global_load_dwordx2 v[50:51], v[116:117], off
	global_load_dwordx4 v[28:31], v[120:121], off offset:2048
	v_lshl_add_u64 v[116:117], v[116:117], 0, s[10:11]
	v_lshl_add_u64 v[120:121], v[120:121], 0, s[100:101]
	v_cvt_pk_bf16_f32 v112, v60, v61
	v_cvt_pk_bf16_f32 v113, v62, v63
	s_waitcnt vmcnt(45)
	global_store_dwordx2 v[118:119], v[112:113], off
	v_lshl_add_u64 v[118:119], v[118:119], 0, s[10:11]
	v_mul_f32_e32 v64, 0x3fb8aa3b, v72
	v_mul_f32_e32 v65, 0x3fb8aa3b, v73
	v_mul_f32_e32 v66, 0x3fb8aa3b, v74
	v_mul_f32_e32 v67, 0x3fb8aa3b, v75
	v_exp_f32_e32 v64, v64
	v_exp_f32_e32 v65, v65
	v_exp_f32_e32 v66, v66
	v_exp_f32_e32 v67, v67
	v_lshlrev_b32_e32 v68, 16, v52
	v_and_b32_e32 v69, 0xffff0000, v52
	v_lshlrev_b32_e32 v70, 16, v53
	v_and_b32_e32 v71, 0xffff0000, v53
	v_pk_fma_f32 v[60:61], v[60:61], v[64:65], v[68:69]
	v_pk_fma_f32 v[62:63], v[62:63], v[66:67], v[70:71]
	global_load_dwordx2 v[52:53], v[116:117], off
	global_load_dwordx4 v[72:75], v[120:121], off
	v_lshl_add_u64 v[116:117], v[116:117], 0, s[10:11]
	v_cvt_pk_bf16_f32 v114, v60, v61
	v_cvt_pk_bf16_f32 v115, v62, v63
	s_waitcnt vmcnt(45)
	global_store_dwordx2 v[118:119], v[114:115], off
	v_lshl_add_u64 v[118:119], v[118:119], 0, s[10:11]
	v_mul_f32_e32 v64, 0x3fb8aa3b, v76
	v_mul_f32_e32 v65, 0x3fb8aa3b, v77
	v_mul_f32_e32 v66, 0x3fb8aa3b, v78
	v_mul_f32_e32 v67, 0x3fb8aa3b, v79
	v_exp_f32_e32 v64, v64
	v_exp_f32_e32 v65, v65
	v_exp_f32_e32 v66, v66
	v_exp_f32_e32 v67, v67
	v_lshlrev_b32_e32 v68, 16, v54
	v_and_b32_e32 v69, 0xffff0000, v54
	v_lshlrev_b32_e32 v70, 16, v55
	v_and_b32_e32 v71, 0xffff0000, v55
	v_pk_fma_f32 v[60:61], v[60:61], v[64:65], v[68:69]
	v_pk_fma_f32 v[62:63], v[62:63], v[66:67], v[70:71]
	global_load_dwordx2 v[54:55], v[116:117], off
	global_load_dwordx4 v[76:79], v[120:121], off offset:2048
	v_lshl_add_u64 v[116:117], v[116:117], 0, s[10:11]
	v_lshl_add_u64 v[120:121], v[120:121], 0, s[100:101]
	v_cvt_pk_bf16_f32 v112, v60, v61
	v_cvt_pk_bf16_f32 v113, v62, v63
	s_waitcnt vmcnt(45)
	global_store_dwordx2 v[118:119], v[112:113], off
	v_lshl_add_u64 v[118:119], v[118:119], 0, s[10:11]
	v_mul_f32_e32 v64, 0x3fb8aa3b, v80
	v_mul_f32_e32 v65, 0x3fb8aa3b, v81
	v_mul_f32_e32 v66, 0x3fb8aa3b, v82
	v_mul_f32_e32 v67, 0x3fb8aa3b, v83
	v_exp_f32_e32 v64, v64
	v_exp_f32_e32 v65, v65
	v_exp_f32_e32 v66, v66
	v_exp_f32_e32 v67, v67
	v_lshlrev_b32_e32 v68, 16, v56
	v_and_b32_e32 v69, 0xffff0000, v56
	v_lshlrev_b32_e32 v70, 16, v57
	v_and_b32_e32 v71, 0xffff0000, v57
	v_pk_fma_f32 v[60:61], v[60:61], v[64:65], v[68:69]
	v_pk_fma_f32 v[62:63], v[62:63], v[66:67], v[70:71]
	global_load_dwordx2 v[56:57], v[116:117], off
	global_load_dwordx4 v[80:83], v[120:121], off
	v_lshl_add_u64 v[116:117], v[116:117], 0, s[10:11]
	v_cvt_pk_bf16_f32 v114, v60, v61
	v_cvt_pk_bf16_f32 v115, v62, v63
	s_waitcnt vmcnt(45)
	global_store_dwordx2 v[118:119], v[114:115], off
	v_lshl_add_u64 v[118:119], v[118:119], 0, s[10:11]
	v_mul_f32_e32 v64, 0x3fb8aa3b, v84
	v_mul_f32_e32 v65, 0x3fb8aa3b, v85
	v_mul_f32_e32 v66, 0x3fb8aa3b, v86
	v_mul_f32_e32 v67, 0x3fb8aa3b, v87
	v_exp_f32_e32 v64, v64
	v_exp_f32_e32 v65, v65
	v_exp_f32_e32 v66, v66
	v_exp_f32_e32 v67, v67
	v_lshlrev_b32_e32 v68, 16, v58
	v_and_b32_e32 v69, 0xffff0000, v58
	v_lshlrev_b32_e32 v70, 16, v59
	v_and_b32_e32 v71, 0xffff0000, v59
	v_pk_fma_f32 v[60:61], v[60:61], v[64:65], v[68:69]
	v_pk_fma_f32 v[62:63], v[62:63], v[66:67], v[70:71]
	global_load_dwordx2 v[58:59], v[116:117], off
	global_load_dwordx4 v[84:87], v[120:121], off offset:2048
	v_lshl_add_u64 v[116:117], v[116:117], 0, s[10:11]
	v_lshl_add_u64 v[120:121], v[120:121], 0, s[100:101]
	v_cvt_pk_bf16_f32 v112, v60, v61
	v_cvt_pk_bf16_f32 v113, v62, v63
	s_waitcnt vmcnt(45)
	global_store_dwordx2 v[118:119], v[112:113], off
	v_lshl_add_u64 v[118:119], v[118:119], 0, s[10:11]
	v_mul_f32_e32 v64, 0x3fb8aa3b, v88
	v_mul_f32_e32 v65, 0x3fb8aa3b, v89
	v_mul_f32_e32 v66, 0x3fb8aa3b, v90
	v_mul_f32_e32 v67, 0x3fb8aa3b, v91
	v_exp_f32_e32 v64, v64
	v_exp_f32_e32 v65, v65
	v_exp_f32_e32 v66, v66
	v_exp_f32_e32 v67, v67
	v_lshlrev_b32_e32 v68, 16, v104
	v_and_b32_e32 v69, 0xffff0000, v104
	v_lshlrev_b32_e32 v70, 16, v105
	v_and_b32_e32 v71, 0xffff0000, v105
	v_pk_fma_f32 v[60:61], v[60:61], v[64:65], v[68:69]
	v_pk_fma_f32 v[62:63], v[62:63], v[66:67], v[70:71]
	global_load_dwordx2 v[104:105], v[116:117], off
	global_load_dwordx4 v[88:91], v[120:121], off
	v_lshl_add_u64 v[116:117], v[116:117], 0, s[10:11]
	v_cvt_pk_bf16_f32 v114, v60, v61
	v_cvt_pk_bf16_f32 v115, v62, v63
	s_waitcnt vmcnt(45)
	global_store_dwordx2 v[118:119], v[114:115], off
	v_lshl_add_u64 v[118:119], v[118:119], 0, s[10:11]
	v_mul_f32_e32 v64, 0x3fb8aa3b, v92
	v_mul_f32_e32 v65, 0x3fb8aa3b, v93
	v_mul_f32_e32 v66, 0x3fb8aa3b, v94
	v_mul_f32_e32 v67, 0x3fb8aa3b, v95
	v_exp_f32_e32 v64, v64
	v_exp_f32_e32 v65, v65
	v_exp_f32_e32 v66, v66
	v_exp_f32_e32 v67, v67
	v_lshlrev_b32_e32 v68, 16, v106
	v_and_b32_e32 v69, 0xffff0000, v106
	v_lshlrev_b32_e32 v70, 16, v107
	v_and_b32_e32 v71, 0xffff0000, v107
	v_pk_fma_f32 v[60:61], v[60:61], v[64:65], v[68:69]
	v_pk_fma_f32 v[62:63], v[62:63], v[66:67], v[70:71]
	global_load_dwordx2 v[106:107], v[116:117], off
	global_load_dwordx4 v[92:95], v[120:121], off offset:2048
	v_lshl_add_u64 v[116:117], v[116:117], 0, s[10:11]
	v_lshl_add_u64 v[120:121], v[120:121], 0, s[100:101]
	v_cvt_pk_bf16_f32 v112, v60, v61
	v_cvt_pk_bf16_f32 v113, v62, v63
	s_waitcnt vmcnt(45)
	global_store_dwordx2 v[118:119], v[112:113], off
	v_lshl_add_u64 v[118:119], v[118:119], 0, s[10:11]
	v_mul_f32_e32 v64, 0x3fb8aa3b, v96
	v_mul_f32_e32 v65, 0x3fb8aa3b, v97
	v_mul_f32_e32 v66, 0x3fb8aa3b, v98
	v_mul_f32_e32 v67, 0x3fb8aa3b, v99
	v_exp_f32_e32 v64, v64
	v_exp_f32_e32 v65, v65
	v_exp_f32_e32 v66, v66
	v_exp_f32_e32 v67, v67
	v_lshlrev_b32_e32 v68, 16, v108
	v_and_b32_e32 v69, 0xffff0000, v108
	v_lshlrev_b32_e32 v70, 16, v109
	v_and_b32_e32 v71, 0xffff0000, v109
	v_pk_fma_f32 v[60:61], v[60:61], v[64:65], v[68:69]
	v_pk_fma_f32 v[62:63], v[62:63], v[66:67], v[70:71]
	global_load_dwordx2 v[108:109], v[116:117], off
	global_load_dwordx4 v[96:99], v[120:121], off
	v_lshl_add_u64 v[116:117], v[116:117], 0, s[10:11]
	v_cvt_pk_bf16_f32 v114, v60, v61
	v_cvt_pk_bf16_f32 v115, v62, v63
	s_waitcnt vmcnt(45)
	global_store_dwordx2 v[118:119], v[114:115], off
	v_lshl_add_u64 v[118:119], v[118:119], 0, s[10:11]
	v_mul_f32_e32 v64, 0x3fb8aa3b, v100
	v_mul_f32_e32 v65, 0x3fb8aa3b, v101
	v_mul_f32_e32 v66, 0x3fb8aa3b, v102
	v_mul_f32_e32 v67, 0x3fb8aa3b, v103
	v_exp_f32_e32 v64, v64
	v_exp_f32_e32 v65, v65
	v_exp_f32_e32 v66, v66
	v_exp_f32_e32 v67, v67
	v_lshlrev_b32_e32 v68, 16, v110
	v_and_b32_e32 v69, 0xffff0000, v110
	v_lshlrev_b32_e32 v70, 16, v111
	v_and_b32_e32 v71, 0xffff0000, v111
	v_pk_fma_f32 v[60:61], v[60:61], v[64:65], v[68:69]
	v_pk_fma_f32 v[62:63], v[62:63], v[66:67], v[70:71]
	global_load_dwordx2 v[110:111], v[116:117], off
	global_load_dwordx4 v[100:103], v[120:121], off offset:2048
	v_lshl_add_u64 v[116:117], v[116:117], 0, s[10:11]
	v_lshl_add_u64 v[120:121], v[120:121], 0, s[100:101]
	v_cvt_pk_bf16_f32 v112, v60, v61
	v_cvt_pk_bf16_f32 v113, v62, v63
	s_waitcnt vmcnt(45)
	global_store_dwordx2 v[118:119], v[112:113], off
	v_lshl_add_u64 v[118:119], v[118:119], 0, s[10:11]
	v_mul_f32_e32 v64, 0x3fb8aa3b, v0
	v_mul_f32_e32 v65, 0x3fb8aa3b, v1
	v_mul_f32_e32 v66, 0x3fb8aa3b, v2
	v_mul_f32_e32 v67, 0x3fb8aa3b, v3
	v_exp_f32_e32 v64, v64
	v_exp_f32_e32 v65, v65
	v_exp_f32_e32 v66, v66
	v_exp_f32_e32 v67, v67
	v_lshlrev_b32_e32 v68, 16, v36
	v_and_b32_e32 v69, 0xffff0000, v36
	v_lshlrev_b32_e32 v70, 16, v37
	v_and_b32_e32 v71, 0xffff0000, v37
	v_pk_fma_f32 v[60:61], v[60:61], v[64:65], v[68:69]
	v_pk_fma_f32 v[62:63], v[62:63], v[66:67], v[70:71]
	global_load_dwordx2 v[36:37], v[116:117], off
	global_load_dwordx4 v[0:3], v[120:121], off
	v_lshl_add_u64 v[116:117], v[116:117], 0, s[10:11]
	v_cvt_pk_bf16_f32 v114, v60, v61
	v_cvt_pk_bf16_f32 v115, v62, v63
	s_waitcnt vmcnt(45)
	global_store_dwordx2 v[118:119], v[114:115], off
	v_lshl_add_u64 v[118:119], v[118:119], 0, s[10:11]
	v_mul_f32_e32 v64, 0x3fb8aa3b, v4
	v_mul_f32_e32 v65, 0x3fb8aa3b, v5
	v_mul_f32_e32 v66, 0x3fb8aa3b, v6
	v_mul_f32_e32 v67, 0x3fb8aa3b, v7
	v_exp_f32_e32 v64, v64
	v_exp_f32_e32 v65, v65
	v_exp_f32_e32 v66, v66
	v_exp_f32_e32 v67, v67
	v_lshlrev_b32_e32 v68, 16, v38
	v_and_b32_e32 v69, 0xffff0000, v38
	v_lshlrev_b32_e32 v70, 16, v39
	v_and_b32_e32 v71, 0xffff0000, v39
	v_pk_fma_f32 v[60:61], v[60:61], v[64:65], v[68:69]
	v_pk_fma_f32 v[62:63], v[62:63], v[66:67], v[70:71]
	global_load_dwordx2 v[38:39], v[116:117], off
	global_load_dwordx4 v[4:7], v[120:121], off offset:2048
	v_lshl_add_u64 v[116:117], v[116:117], 0, s[10:11]
	v_lshl_add_u64 v[120:121], v[120:121], 0, s[100:101]
	v_cvt_pk_bf16_f32 v112, v60, v61
	v_cvt_pk_bf16_f32 v113, v62, v63
	s_waitcnt vmcnt(45)
	global_store_dwordx2 v[118:119], v[112:113], off
	v_lshl_add_u64 v[118:119], v[118:119], 0, s[10:11]
	v_mul_f32_e32 v64, 0x3fb8aa3b, v8
	v_mul_f32_e32 v65, 0x3fb8aa3b, v9
	v_mul_f32_e32 v66, 0x3fb8aa3b, v10
	v_mul_f32_e32 v67, 0x3fb8aa3b, v11
	v_exp_f32_e32 v64, v64
	v_exp_f32_e32 v65, v65
	v_exp_f32_e32 v66, v66
	v_exp_f32_e32 v67, v67
	v_lshlrev_b32_e32 v68, 16, v40
	v_and_b32_e32 v69, 0xffff0000, v40
	v_lshlrev_b32_e32 v70, 16, v41
	v_and_b32_e32 v71, 0xffff0000, v41
	v_pk_fma_f32 v[60:61], v[60:61], v[64:65], v[68:69]
	v_pk_fma_f32 v[62:63], v[62:63], v[66:67], v[70:71]
	global_load_dwordx2 v[40:41], v[116:117], off
	global_load_dwordx4 v[8:11], v[120:121], off
	v_lshl_add_u64 v[116:117], v[116:117], 0, s[10:11]
	v_cvt_pk_bf16_f32 v114, v60, v61
	v_cvt_pk_bf16_f32 v115, v62, v63
	s_waitcnt vmcnt(45)
	global_store_dwordx2 v[118:119], v[114:115], off
	v_lshl_add_u64 v[118:119], v[118:119], 0, s[10:11]
	v_mul_f32_e32 v64, 0x3fb8aa3b, v12
	v_mul_f32_e32 v65, 0x3fb8aa3b, v13
	v_mul_f32_e32 v66, 0x3fb8aa3b, v14
	v_mul_f32_e32 v67, 0x3fb8aa3b, v15
	v_exp_f32_e32 v64, v64
	v_exp_f32_e32 v65, v65
	v_exp_f32_e32 v66, v66
	v_exp_f32_e32 v67, v67
	v_lshlrev_b32_e32 v68, 16, v42
	v_and_b32_e32 v69, 0xffff0000, v42
	v_lshlrev_b32_e32 v70, 16, v43
	v_and_b32_e32 v71, 0xffff0000, v43
	v_pk_fma_f32 v[60:61], v[60:61], v[64:65], v[68:69]
	v_pk_fma_f32 v[62:63], v[62:63], v[66:67], v[70:71]
	global_load_dwordx2 v[42:43], v[116:117], off
	global_load_dwordx4 v[12:15], v[120:121], off offset:2048
	v_lshl_add_u64 v[116:117], v[116:117], 0, s[10:11]
	v_lshl_add_u64 v[120:121], v[120:121], 0, s[100:101]
	v_cvt_pk_bf16_f32 v112, v60, v61
	v_cvt_pk_bf16_f32 v113, v62, v63
	s_waitcnt vmcnt(45)
	global_store_dwordx2 v[118:119], v[112:113], off
	v_lshl_add_u64 v[118:119], v[118:119], 0, s[10:11]
	v_mul_f32_e32 v64, 0x3fb8aa3b, v16
	v_mul_f32_e32 v65, 0x3fb8aa3b, v17
	v_mul_f32_e32 v66, 0x3fb8aa3b, v18
	v_mul_f32_e32 v67, 0x3fb8aa3b, v19
	v_exp_f32_e32 v64, v64
	v_exp_f32_e32 v65, v65
	v_exp_f32_e32 v66, v66
	v_exp_f32_e32 v67, v67
	v_lshlrev_b32_e32 v68, 16, v44
	v_and_b32_e32 v69, 0xffff0000, v44
	v_lshlrev_b32_e32 v70, 16, v45
	v_and_b32_e32 v71, 0xffff0000, v45
	v_pk_fma_f32 v[60:61], v[60:61], v[64:65], v[68:69]
	v_pk_fma_f32 v[62:63], v[62:63], v[66:67], v[70:71]
	global_load_dwordx2 v[44:45], v[116:117], off
	global_load_dwordx4 v[16:19], v[120:121], off
	v_lshl_add_u64 v[116:117], v[116:117], 0, s[10:11]
	v_cvt_pk_bf16_f32 v114, v60, v61
	v_cvt_pk_bf16_f32 v115, v62, v63
	s_waitcnt vmcnt(45)
	global_store_dwordx2 v[118:119], v[114:115], off
	v_lshl_add_u64 v[118:119], v[118:119], 0, s[10:11]
	v_mul_f32_e32 v64, 0x3fb8aa3b, v20
	v_mul_f32_e32 v65, 0x3fb8aa3b, v21
	v_mul_f32_e32 v66, 0x3fb8aa3b, v22
	v_mul_f32_e32 v67, 0x3fb8aa3b, v23
	v_exp_f32_e32 v64, v64
	v_exp_f32_e32 v65, v65
	v_exp_f32_e32 v66, v66
	v_exp_f32_e32 v67, v67
	v_lshlrev_b32_e32 v68, 16, v46
	v_and_b32_e32 v69, 0xffff0000, v46
	v_lshlrev_b32_e32 v70, 16, v47
	v_and_b32_e32 v71, 0xffff0000, v47
	v_pk_fma_f32 v[60:61], v[60:61], v[64:65], v[68:69]
	v_pk_fma_f32 v[62:63], v[62:63], v[66:67], v[70:71]
	global_load_dwordx2 v[46:47], v[116:117], off
	global_load_dwordx4 v[20:23], v[120:121], off offset:2048
	v_lshl_add_u64 v[116:117], v[116:117], 0, s[10:11]
	v_lshl_add_u64 v[120:121], v[120:121], 0, s[100:101]
	v_cvt_pk_bf16_f32 v112, v60, v61
	v_cvt_pk_bf16_f32 v113, v62, v63
	s_waitcnt vmcnt(45)
	global_store_dwordx2 v[118:119], v[112:113], off
	v_lshl_add_u64 v[118:119], v[118:119], 0, s[10:11]
	v_mul_f32_e32 v64, 0x3fb8aa3b, v24
	v_mul_f32_e32 v65, 0x3fb8aa3b, v25
	v_mul_f32_e32 v66, 0x3fb8aa3b, v26
	v_mul_f32_e32 v67, 0x3fb8aa3b, v27
	v_exp_f32_e32 v64, v64
	v_exp_f32_e32 v65, v65
	v_exp_f32_e32 v66, v66
	v_exp_f32_e32 v67, v67
	v_lshlrev_b32_e32 v68, 16, v48
	v_and_b32_e32 v69, 0xffff0000, v48
	v_lshlrev_b32_e32 v70, 16, v49
	v_and_b32_e32 v71, 0xffff0000, v49
	v_pk_fma_f32 v[60:61], v[60:61], v[64:65], v[68:69]
	v_pk_fma_f32 v[62:63], v[62:63], v[66:67], v[70:71]
	global_load_dwordx2 v[48:49], v[116:117], off
	global_load_dwordx4 v[24:27], v[120:121], off
	v_lshl_add_u64 v[116:117], v[116:117], 0, s[10:11]
	v_cvt_pk_bf16_f32 v114, v60, v61
	v_cvt_pk_bf16_f32 v115, v62, v63
	s_waitcnt vmcnt(45)
	global_store_dwordx2 v[118:119], v[114:115], off
	v_lshl_add_u64 v[118:119], v[118:119], 0, s[10:11]
	v_mul_f32_e32 v64, 0x3fb8aa3b, v28
	v_mul_f32_e32 v65, 0x3fb8aa3b, v29
	v_mul_f32_e32 v66, 0x3fb8aa3b, v30
	v_mul_f32_e32 v67, 0x3fb8aa3b, v31
	v_exp_f32_e32 v64, v64
	v_exp_f32_e32 v65, v65
	v_exp_f32_e32 v66, v66
	v_exp_f32_e32 v67, v67
	v_lshlrev_b32_e32 v68, 16, v50
	v_and_b32_e32 v69, 0xffff0000, v50
	v_lshlrev_b32_e32 v70, 16, v51
	v_and_b32_e32 v71, 0xffff0000, v51
	v_pk_fma_f32 v[60:61], v[60:61], v[64:65], v[68:69]
	v_pk_fma_f32 v[62:63], v[62:63], v[66:67], v[70:71]
	global_load_dwordx2 v[50:51], v[116:117], off
	global_load_dwordx4 v[28:31], v[120:121], off offset:2048
	v_lshl_add_u64 v[116:117], v[116:117], 0, s[10:11]
	v_lshl_add_u64 v[120:121], v[120:121], 0, s[100:101]
	v_cvt_pk_bf16_f32 v112, v60, v61
	v_cvt_pk_bf16_f32 v113, v62, v63
	s_waitcnt vmcnt(45)
	global_store_dwordx2 v[118:119], v[112:113], off
	v_lshl_add_u64 v[118:119], v[118:119], 0, s[10:11]
	v_mul_f32_e32 v64, 0x3fb8aa3b, v72
	v_mul_f32_e32 v65, 0x3fb8aa3b, v73
	v_mul_f32_e32 v66, 0x3fb8aa3b, v74
	v_mul_f32_e32 v67, 0x3fb8aa3b, v75
	v_exp_f32_e32 v64, v64
	v_exp_f32_e32 v65, v65
	v_exp_f32_e32 v66, v66
	v_exp_f32_e32 v67, v67
	v_lshlrev_b32_e32 v68, 16, v52
	v_and_b32_e32 v69, 0xffff0000, v52
	v_lshlrev_b32_e32 v70, 16, v53
	v_and_b32_e32 v71, 0xffff0000, v53
	v_pk_fma_f32 v[60:61], v[60:61], v[64:65], v[68:69]
	v_pk_fma_f32 v[62:63], v[62:63], v[66:67], v[70:71]
	global_load_dwordx2 v[52:53], v[116:117], off
	global_load_dwordx4 v[72:75], v[120:121], off
	v_lshl_add_u64 v[116:117], v[116:117], 0, s[10:11]
	v_cvt_pk_bf16_f32 v114, v60, v61
	v_cvt_pk_bf16_f32 v115, v62, v63
	s_waitcnt vmcnt(45)
	global_store_dwordx2 v[118:119], v[114:115], off
	v_lshl_add_u64 v[118:119], v[118:119], 0, s[10:11]
	v_mul_f32_e32 v64, 0x3fb8aa3b, v76
	v_mul_f32_e32 v65, 0x3fb8aa3b, v77
	v_mul_f32_e32 v66, 0x3fb8aa3b, v78
	v_mul_f32_e32 v67, 0x3fb8aa3b, v79
	v_exp_f32_e32 v64, v64
	v_exp_f32_e32 v65, v65
	v_exp_f32_e32 v66, v66
	v_exp_f32_e32 v67, v67
	v_lshlrev_b32_e32 v68, 16, v54
	v_and_b32_e32 v69, 0xffff0000, v54
	v_lshlrev_b32_e32 v70, 16, v55
	v_and_b32_e32 v71, 0xffff0000, v55
	v_pk_fma_f32 v[60:61], v[60:61], v[64:65], v[68:69]
	v_pk_fma_f32 v[62:63], v[62:63], v[66:67], v[70:71]
	global_load_dwordx2 v[54:55], v[116:117], off
	global_load_dwordx4 v[76:79], v[120:121], off offset:2048
	v_lshl_add_u64 v[116:117], v[116:117], 0, s[10:11]
	v_lshl_add_u64 v[120:121], v[120:121], 0, s[100:101]
	v_cvt_pk_bf16_f32 v112, v60, v61
	v_cvt_pk_bf16_f32 v113, v62, v63
	s_waitcnt vmcnt(45)
	global_store_dwordx2 v[118:119], v[112:113], off
	v_lshl_add_u64 v[118:119], v[118:119], 0, s[10:11]
	v_mul_f32_e32 v64, 0x3fb8aa3b, v80
	v_mul_f32_e32 v65, 0x3fb8aa3b, v81
	v_mul_f32_e32 v66, 0x3fb8aa3b, v82
	v_mul_f32_e32 v67, 0x3fb8aa3b, v83
	v_exp_f32_e32 v64, v64
	v_exp_f32_e32 v65, v65
	v_exp_f32_e32 v66, v66
	v_exp_f32_e32 v67, v67
	v_lshlrev_b32_e32 v68, 16, v56
	v_and_b32_e32 v69, 0xffff0000, v56
	v_lshlrev_b32_e32 v70, 16, v57
	v_and_b32_e32 v71, 0xffff0000, v57
	v_pk_fma_f32 v[60:61], v[60:61], v[64:65], v[68:69]
	v_pk_fma_f32 v[62:63], v[62:63], v[66:67], v[70:71]
	global_load_dwordx2 v[56:57], v[116:117], off
	global_load_dwordx4 v[80:83], v[120:121], off
	v_lshl_add_u64 v[116:117], v[116:117], 0, s[10:11]
	v_cvt_pk_bf16_f32 v114, v60, v61
	v_cvt_pk_bf16_f32 v115, v62, v63
	s_waitcnt vmcnt(45)
	global_store_dwordx2 v[118:119], v[114:115], off
	v_lshl_add_u64 v[118:119], v[118:119], 0, s[10:11]
	v_mul_f32_e32 v64, 0x3fb8aa3b, v84
	v_mul_f32_e32 v65, 0x3fb8aa3b, v85
	v_mul_f32_e32 v66, 0x3fb8aa3b, v86
	v_mul_f32_e32 v67, 0x3fb8aa3b, v87
	v_exp_f32_e32 v64, v64
	v_exp_f32_e32 v65, v65
	v_exp_f32_e32 v66, v66
	v_exp_f32_e32 v67, v67
	v_lshlrev_b32_e32 v68, 16, v58
	v_and_b32_e32 v69, 0xffff0000, v58
	v_lshlrev_b32_e32 v70, 16, v59
	v_and_b32_e32 v71, 0xffff0000, v59
	v_pk_fma_f32 v[60:61], v[60:61], v[64:65], v[68:69]
	v_pk_fma_f32 v[62:63], v[62:63], v[66:67], v[70:71]
	global_load_dwordx2 v[58:59], v[116:117], off
	global_load_dwordx4 v[84:87], v[120:121], off offset:2048
	v_lshl_add_u64 v[116:117], v[116:117], 0, s[10:11]
	v_lshl_add_u64 v[120:121], v[120:121], 0, s[100:101]
	v_cvt_pk_bf16_f32 v112, v60, v61
	v_cvt_pk_bf16_f32 v113, v62, v63
	s_waitcnt vmcnt(45)
	global_store_dwordx2 v[118:119], v[112:113], off
	v_lshl_add_u64 v[118:119], v[118:119], 0, s[10:11]
	v_mul_f32_e32 v64, 0x3fb8aa3b, v88
	v_mul_f32_e32 v65, 0x3fb8aa3b, v89
	v_mul_f32_e32 v66, 0x3fb8aa3b, v90
	v_mul_f32_e32 v67, 0x3fb8aa3b, v91
	v_exp_f32_e32 v64, v64
	v_exp_f32_e32 v65, v65
	v_exp_f32_e32 v66, v66
	v_exp_f32_e32 v67, v67
	v_lshlrev_b32_e32 v68, 16, v104
	v_and_b32_e32 v69, 0xffff0000, v104
	v_lshlrev_b32_e32 v70, 16, v105
	v_and_b32_e32 v71, 0xffff0000, v105
	v_pk_fma_f32 v[60:61], v[60:61], v[64:65], v[68:69]
	v_pk_fma_f32 v[62:63], v[62:63], v[66:67], v[70:71]
	global_load_dwordx2 v[104:105], v[116:117], off
	global_load_dwordx4 v[88:91], v[120:121], off
	v_lshl_add_u64 v[116:117], v[116:117], 0, s[10:11]
	v_cvt_pk_bf16_f32 v114, v60, v61
	v_cvt_pk_bf16_f32 v115, v62, v63
	s_waitcnt vmcnt(45)
	global_store_dwordx2 v[118:119], v[114:115], off
	v_lshl_add_u64 v[118:119], v[118:119], 0, s[10:11]
	v_mul_f32_e32 v64, 0x3fb8aa3b, v92
	v_mul_f32_e32 v65, 0x3fb8aa3b, v93
	v_mul_f32_e32 v66, 0x3fb8aa3b, v94
	v_mul_f32_e32 v67, 0x3fb8aa3b, v95
	v_exp_f32_e32 v64, v64
	v_exp_f32_e32 v65, v65
	v_exp_f32_e32 v66, v66
	v_exp_f32_e32 v67, v67
	v_lshlrev_b32_e32 v68, 16, v106
	v_and_b32_e32 v69, 0xffff0000, v106
	v_lshlrev_b32_e32 v70, 16, v107
	v_and_b32_e32 v71, 0xffff0000, v107
	v_pk_fma_f32 v[60:61], v[60:61], v[64:65], v[68:69]
	v_pk_fma_f32 v[62:63], v[62:63], v[66:67], v[70:71]
	global_load_dwordx2 v[106:107], v[116:117], off
	global_load_dwordx4 v[92:95], v[120:121], off offset:2048
	v_lshl_add_u64 v[116:117], v[116:117], 0, s[10:11]
	v_lshl_add_u64 v[120:121], v[120:121], 0, s[100:101]
	v_cvt_pk_bf16_f32 v112, v60, v61
	v_cvt_pk_bf16_f32 v113, v62, v63
	s_waitcnt vmcnt(45)
	global_store_dwordx2 v[118:119], v[112:113], off
	v_lshl_add_u64 v[118:119], v[118:119], 0, s[10:11]
	v_mul_f32_e32 v64, 0x3fb8aa3b, v96
	v_mul_f32_e32 v65, 0x3fb8aa3b, v97
	v_mul_f32_e32 v66, 0x3fb8aa3b, v98
	v_mul_f32_e32 v67, 0x3fb8aa3b, v99
	v_exp_f32_e32 v64, v64
	v_exp_f32_e32 v65, v65
	v_exp_f32_e32 v66, v66
	v_exp_f32_e32 v67, v67
	v_lshlrev_b32_e32 v68, 16, v108
	v_and_b32_e32 v69, 0xffff0000, v108
	v_lshlrev_b32_e32 v70, 16, v109
	v_and_b32_e32 v71, 0xffff0000, v109
	v_pk_fma_f32 v[60:61], v[60:61], v[64:65], v[68:69]
	v_pk_fma_f32 v[62:63], v[62:63], v[66:67], v[70:71]
	global_load_dwordx2 v[108:109], v[116:117], off
	global_load_dwordx4 v[96:99], v[120:121], off
	v_lshl_add_u64 v[116:117], v[116:117], 0, s[10:11]
	v_cvt_pk_bf16_f32 v114, v60, v61
	v_cvt_pk_bf16_f32 v115, v62, v63
	s_waitcnt vmcnt(45)
	global_store_dwordx2 v[118:119], v[114:115], off
	v_lshl_add_u64 v[118:119], v[118:119], 0, s[10:11]
	v_mul_f32_e32 v64, 0x3fb8aa3b, v100
	v_mul_f32_e32 v65, 0x3fb8aa3b, v101
	v_mul_f32_e32 v66, 0x3fb8aa3b, v102
	v_mul_f32_e32 v67, 0x3fb8aa3b, v103
	v_exp_f32_e32 v64, v64
	v_exp_f32_e32 v65, v65
	v_exp_f32_e32 v66, v66
	v_exp_f32_e32 v67, v67
	v_lshlrev_b32_e32 v68, 16, v110
	v_and_b32_e32 v69, 0xffff0000, v110
	v_lshlrev_b32_e32 v70, 16, v111
	v_and_b32_e32 v71, 0xffff0000, v111
	v_pk_fma_f32 v[60:61], v[60:61], v[64:65], v[68:69]
	v_pk_fma_f32 v[62:63], v[62:63], v[66:67], v[70:71]
	global_load_dwordx2 v[110:111], v[116:117], off
	global_load_dwordx4 v[100:103], v[120:121], off offset:2048
	v_lshl_add_u64 v[116:117], v[116:117], 0, s[10:11]
	v_lshl_add_u64 v[120:121], v[120:121], 0, s[100:101]
	v_cvt_pk_bf16_f32 v112, v60, v61
	v_cvt_pk_bf16_f32 v113, v62, v63
	s_waitcnt vmcnt(45)
	global_store_dwordx2 v[118:119], v[112:113], off
	v_lshl_add_u64 v[118:119], v[118:119], 0, s[10:11]
	v_mul_f32_e32 v64, 0x3fb8aa3b, v0
	v_mul_f32_e32 v65, 0x3fb8aa3b, v1
	v_mul_f32_e32 v66, 0x3fb8aa3b, v2
	v_mul_f32_e32 v67, 0x3fb8aa3b, v3
	v_exp_f32_e32 v64, v64
	v_exp_f32_e32 v65, v65
	v_exp_f32_e32 v66, v66
	v_exp_f32_e32 v67, v67
	v_lshlrev_b32_e32 v68, 16, v36
	v_and_b32_e32 v69, 0xffff0000, v36
	v_lshlrev_b32_e32 v70, 16, v37
	v_and_b32_e32 v71, 0xffff0000, v37
	v_pk_fma_f32 v[60:61], v[60:61], v[64:65], v[68:69]
	v_pk_fma_f32 v[62:63], v[62:63], v[66:67], v[70:71]
	global_load_dwordx2 v[36:37], v[116:117], off
	global_load_dwordx4 v[0:3], v[120:121], off
	v_lshl_add_u64 v[116:117], v[116:117], 0, s[10:11]
	v_cvt_pk_bf16_f32 v114, v60, v61
	v_cvt_pk_bf16_f32 v115, v62, v63
	s_waitcnt vmcnt(45)
	global_store_dwordx2 v[118:119], v[114:115], off
	v_lshl_add_u64 v[118:119], v[118:119], 0, s[10:11]
	v_mul_f32_e32 v64, 0x3fb8aa3b, v4
	v_mul_f32_e32 v65, 0x3fb8aa3b, v5
	v_mul_f32_e32 v66, 0x3fb8aa3b, v6
	v_mul_f32_e32 v67, 0x3fb8aa3b, v7
	v_exp_f32_e32 v64, v64
	v_exp_f32_e32 v65, v65
	v_exp_f32_e32 v66, v66
	v_exp_f32_e32 v67, v67
	v_lshlrev_b32_e32 v68, 16, v38
	v_and_b32_e32 v69, 0xffff0000, v38
	v_lshlrev_b32_e32 v70, 16, v39
	v_and_b32_e32 v71, 0xffff0000, v39
	v_pk_fma_f32 v[60:61], v[60:61], v[64:65], v[68:69]
	v_pk_fma_f32 v[62:63], v[62:63], v[66:67], v[70:71]
	global_load_dwordx2 v[38:39], v[116:117], off
	global_load_dwordx4 v[4:7], v[120:121], off offset:2048
	v_lshl_add_u64 v[116:117], v[116:117], 0, s[10:11]
	v_lshl_add_u64 v[120:121], v[120:121], 0, s[100:101]
	v_cvt_pk_bf16_f32 v112, v60, v61
	v_cvt_pk_bf16_f32 v113, v62, v63
	s_waitcnt vmcnt(45)
	global_store_dwordx2 v[118:119], v[112:113], off
	v_lshl_add_u64 v[118:119], v[118:119], 0, s[10:11]
	v_mul_f32_e32 v64, 0x3fb8aa3b, v8
	v_mul_f32_e32 v65, 0x3fb8aa3b, v9
	v_mul_f32_e32 v66, 0x3fb8aa3b, v10
	v_mul_f32_e32 v67, 0x3fb8aa3b, v11
	v_exp_f32_e32 v64, v64
	v_exp_f32_e32 v65, v65
	v_exp_f32_e32 v66, v66
	v_exp_f32_e32 v67, v67
	v_lshlrev_b32_e32 v68, 16, v40
	v_and_b32_e32 v69, 0xffff0000, v40
	v_lshlrev_b32_e32 v70, 16, v41
	v_and_b32_e32 v71, 0xffff0000, v41
	v_pk_fma_f32 v[60:61], v[60:61], v[64:65], v[68:69]
	v_pk_fma_f32 v[62:63], v[62:63], v[66:67], v[70:71]
	global_load_dwordx2 v[40:41], v[116:117], off
	global_load_dwordx4 v[8:11], v[120:121], off
	v_lshl_add_u64 v[116:117], v[116:117], 0, s[10:11]
	v_cvt_pk_bf16_f32 v114, v60, v61
	v_cvt_pk_bf16_f32 v115, v62, v63
	s_waitcnt vmcnt(45)
	global_store_dwordx2 v[118:119], v[114:115], off
	v_lshl_add_u64 v[118:119], v[118:119], 0, s[10:11]
	v_mul_f32_e32 v64, 0x3fb8aa3b, v12
	v_mul_f32_e32 v65, 0x3fb8aa3b, v13
	v_mul_f32_e32 v66, 0x3fb8aa3b, v14
	v_mul_f32_e32 v67, 0x3fb8aa3b, v15
	v_exp_f32_e32 v64, v64
	v_exp_f32_e32 v65, v65
	v_exp_f32_e32 v66, v66
	v_exp_f32_e32 v67, v67
	v_lshlrev_b32_e32 v68, 16, v42
	v_and_b32_e32 v69, 0xffff0000, v42
	v_lshlrev_b32_e32 v70, 16, v43
	v_and_b32_e32 v71, 0xffff0000, v43
	v_pk_fma_f32 v[60:61], v[60:61], v[64:65], v[68:69]
	v_pk_fma_f32 v[62:63], v[62:63], v[66:67], v[70:71]
	global_load_dwordx2 v[42:43], v[116:117], off
	global_load_dwordx4 v[12:15], v[120:121], off offset:2048
	v_lshl_add_u64 v[116:117], v[116:117], 0, s[10:11]
	v_lshl_add_u64 v[120:121], v[120:121], 0, s[100:101]
	v_cvt_pk_bf16_f32 v112, v60, v61
	v_cvt_pk_bf16_f32 v113, v62, v63
	s_waitcnt vmcnt(45)
	global_store_dwordx2 v[118:119], v[112:113], off
	v_lshl_add_u64 v[118:119], v[118:119], 0, s[10:11]
	v_mul_f32_e32 v64, 0x3fb8aa3b, v16
	v_mul_f32_e32 v65, 0x3fb8aa3b, v17
	v_mul_f32_e32 v66, 0x3fb8aa3b, v18
	v_mul_f32_e32 v67, 0x3fb8aa3b, v19
	v_exp_f32_e32 v64, v64
	v_exp_f32_e32 v65, v65
	v_exp_f32_e32 v66, v66
	v_exp_f32_e32 v67, v67
	v_lshlrev_b32_e32 v68, 16, v44
	v_and_b32_e32 v69, 0xffff0000, v44
	v_lshlrev_b32_e32 v70, 16, v45
	v_and_b32_e32 v71, 0xffff0000, v45
	v_pk_fma_f32 v[60:61], v[60:61], v[64:65], v[68:69]
	v_pk_fma_f32 v[62:63], v[62:63], v[66:67], v[70:71]
	global_load_dwordx2 v[44:45], v[116:117], off
	global_load_dwordx4 v[16:19], v[120:121], off
	v_lshl_add_u64 v[116:117], v[116:117], 0, s[10:11]
	v_cvt_pk_bf16_f32 v114, v60, v61
	v_cvt_pk_bf16_f32 v115, v62, v63
	s_waitcnt vmcnt(45)
	global_store_dwordx2 v[118:119], v[114:115], off
	v_lshl_add_u64 v[118:119], v[118:119], 0, s[10:11]
	v_mul_f32_e32 v64, 0x3fb8aa3b, v20
	v_mul_f32_e32 v65, 0x3fb8aa3b, v21
	v_mul_f32_e32 v66, 0x3fb8aa3b, v22
	v_mul_f32_e32 v67, 0x3fb8aa3b, v23
	v_exp_f32_e32 v64, v64
	v_exp_f32_e32 v65, v65
	v_exp_f32_e32 v66, v66
	v_exp_f32_e32 v67, v67
	v_lshlrev_b32_e32 v68, 16, v46
	v_and_b32_e32 v69, 0xffff0000, v46
	v_lshlrev_b32_e32 v70, 16, v47
	v_and_b32_e32 v71, 0xffff0000, v47
	v_pk_fma_f32 v[60:61], v[60:61], v[64:65], v[68:69]
	v_pk_fma_f32 v[62:63], v[62:63], v[66:67], v[70:71]
	global_load_dwordx2 v[46:47], v[116:117], off
	global_load_dwordx4 v[20:23], v[120:121], off offset:2048
	v_lshl_add_u64 v[116:117], v[116:117], 0, s[10:11]
	v_lshl_add_u64 v[120:121], v[120:121], 0, s[100:101]
	v_cvt_pk_bf16_f32 v112, v60, v61
	v_cvt_pk_bf16_f32 v113, v62, v63
	s_waitcnt vmcnt(45)
	global_store_dwordx2 v[118:119], v[112:113], off
	v_lshl_add_u64 v[118:119], v[118:119], 0, s[10:11]
	v_mul_f32_e32 v64, 0x3fb8aa3b, v24
	v_mul_f32_e32 v65, 0x3fb8aa3b, v25
	v_mul_f32_e32 v66, 0x3fb8aa3b, v26
	v_mul_f32_e32 v67, 0x3fb8aa3b, v27
	v_exp_f32_e32 v64, v64
	v_exp_f32_e32 v65, v65
	v_exp_f32_e32 v66, v66
	v_exp_f32_e32 v67, v67
	v_lshlrev_b32_e32 v68, 16, v48
	v_and_b32_e32 v69, 0xffff0000, v48
	v_lshlrev_b32_e32 v70, 16, v49
	v_and_b32_e32 v71, 0xffff0000, v49
	v_pk_fma_f32 v[60:61], v[60:61], v[64:65], v[68:69]
	v_pk_fma_f32 v[62:63], v[62:63], v[66:67], v[70:71]
	global_load_dwordx2 v[48:49], v[116:117], off
	global_load_dwordx4 v[24:27], v[120:121], off
	v_lshl_add_u64 v[116:117], v[116:117], 0, s[10:11]
	v_cvt_pk_bf16_f32 v114, v60, v61
	v_cvt_pk_bf16_f32 v115, v62, v63
	s_waitcnt vmcnt(45)
	global_store_dwordx2 v[118:119], v[114:115], off
	v_lshl_add_u64 v[118:119], v[118:119], 0, s[10:11]
	v_mul_f32_e32 v64, 0x3fb8aa3b, v28
	v_mul_f32_e32 v65, 0x3fb8aa3b, v29
	v_mul_f32_e32 v66, 0x3fb8aa3b, v30
	v_mul_f32_e32 v67, 0x3fb8aa3b, v31
	v_exp_f32_e32 v64, v64
	v_exp_f32_e32 v65, v65
	v_exp_f32_e32 v66, v66
	v_exp_f32_e32 v67, v67
	v_lshlrev_b32_e32 v68, 16, v50
	v_and_b32_e32 v69, 0xffff0000, v50
	v_lshlrev_b32_e32 v70, 16, v51
	v_and_b32_e32 v71, 0xffff0000, v51
	v_pk_fma_f32 v[60:61], v[60:61], v[64:65], v[68:69]
	v_pk_fma_f32 v[62:63], v[62:63], v[66:67], v[70:71]
	global_load_dwordx2 v[50:51], v[116:117], off
	global_load_dwordx4 v[28:31], v[120:121], off offset:2048
	v_lshl_add_u64 v[116:117], v[116:117], 0, s[10:11]
	v_lshl_add_u64 v[120:121], v[120:121], 0, s[100:101]
	v_cvt_pk_bf16_f32 v112, v60, v61
	v_cvt_pk_bf16_f32 v113, v62, v63
	s_waitcnt vmcnt(45)
	global_store_dwordx2 v[118:119], v[112:113], off
	v_lshl_add_u64 v[118:119], v[118:119], 0, s[10:11]
	v_mul_f32_e32 v64, 0x3fb8aa3b, v72
	v_mul_f32_e32 v65, 0x3fb8aa3b, v73
	v_mul_f32_e32 v66, 0x3fb8aa3b, v74
	v_mul_f32_e32 v67, 0x3fb8aa3b, v75
	v_exp_f32_e32 v64, v64
	v_exp_f32_e32 v65, v65
	v_exp_f32_e32 v66, v66
	v_exp_f32_e32 v67, v67
	v_lshlrev_b32_e32 v68, 16, v52
	v_and_b32_e32 v69, 0xffff0000, v52
	v_lshlrev_b32_e32 v70, 16, v53
	v_and_b32_e32 v71, 0xffff0000, v53
	v_pk_fma_f32 v[60:61], v[60:61], v[64:65], v[68:69]
	v_pk_fma_f32 v[62:63], v[62:63], v[66:67], v[70:71]
	global_load_dwordx2 v[52:53], v[116:117], off
	global_load_dwordx4 v[72:75], v[120:121], off
	v_lshl_add_u64 v[116:117], v[116:117], 0, s[10:11]
	v_cvt_pk_bf16_f32 v114, v60, v61
	v_cvt_pk_bf16_f32 v115, v62, v63
	s_waitcnt vmcnt(45)
	global_store_dwordx2 v[118:119], v[114:115], off
	v_lshl_add_u64 v[118:119], v[118:119], 0, s[10:11]
	v_mul_f32_e32 v64, 0x3fb8aa3b, v76
	v_mul_f32_e32 v65, 0x3fb8aa3b, v77
	v_mul_f32_e32 v66, 0x3fb8aa3b, v78
	v_mul_f32_e32 v67, 0x3fb8aa3b, v79
	v_exp_f32_e32 v64, v64
	v_exp_f32_e32 v65, v65
	v_exp_f32_e32 v66, v66
	v_exp_f32_e32 v67, v67
	v_lshlrev_b32_e32 v68, 16, v54
	v_and_b32_e32 v69, 0xffff0000, v54
	v_lshlrev_b32_e32 v70, 16, v55
	v_and_b32_e32 v71, 0xffff0000, v55
	v_pk_fma_f32 v[60:61], v[60:61], v[64:65], v[68:69]
	v_pk_fma_f32 v[62:63], v[62:63], v[66:67], v[70:71]
	global_load_dwordx2 v[54:55], v[116:117], off
	global_load_dwordx4 v[76:79], v[120:121], off offset:2048
	v_lshl_add_u64 v[116:117], v[116:117], 0, s[10:11]
	v_lshl_add_u64 v[120:121], v[120:121], 0, s[100:101]
	v_cvt_pk_bf16_f32 v112, v60, v61
	v_cvt_pk_bf16_f32 v113, v62, v63
	s_waitcnt vmcnt(45)
	global_store_dwordx2 v[118:119], v[112:113], off
	v_lshl_add_u64 v[118:119], v[118:119], 0, s[10:11]
	v_mul_f32_e32 v64, 0x3fb8aa3b, v80
	v_mul_f32_e32 v65, 0x3fb8aa3b, v81
	v_mul_f32_e32 v66, 0x3fb8aa3b, v82
	v_mul_f32_e32 v67, 0x3fb8aa3b, v83
	v_exp_f32_e32 v64, v64
	v_exp_f32_e32 v65, v65
	v_exp_f32_e32 v66, v66
	v_exp_f32_e32 v67, v67
	v_lshlrev_b32_e32 v68, 16, v56
	v_and_b32_e32 v69, 0xffff0000, v56
	v_lshlrev_b32_e32 v70, 16, v57
	v_and_b32_e32 v71, 0xffff0000, v57
	v_pk_fma_f32 v[60:61], v[60:61], v[64:65], v[68:69]
	v_pk_fma_f32 v[62:63], v[62:63], v[66:67], v[70:71]
	global_load_dwordx2 v[56:57], v[116:117], off
	global_load_dwordx4 v[80:83], v[120:121], off
	v_lshl_add_u64 v[116:117], v[116:117], 0, s[10:11]
	v_cvt_pk_bf16_f32 v114, v60, v61
	v_cvt_pk_bf16_f32 v115, v62, v63
	s_waitcnt vmcnt(45)
	global_store_dwordx2 v[118:119], v[114:115], off
	v_lshl_add_u64 v[118:119], v[118:119], 0, s[10:11]
	v_mul_f32_e32 v64, 0x3fb8aa3b, v84
	v_mul_f32_e32 v65, 0x3fb8aa3b, v85
	v_mul_f32_e32 v66, 0x3fb8aa3b, v86
	v_mul_f32_e32 v67, 0x3fb8aa3b, v87
	v_exp_f32_e32 v64, v64
	v_exp_f32_e32 v65, v65
	v_exp_f32_e32 v66, v66
	v_exp_f32_e32 v67, v67
	v_lshlrev_b32_e32 v68, 16, v58
	v_and_b32_e32 v69, 0xffff0000, v58
	v_lshlrev_b32_e32 v70, 16, v59
	v_and_b32_e32 v71, 0xffff0000, v59
	v_pk_fma_f32 v[60:61], v[60:61], v[64:65], v[68:69]
	v_pk_fma_f32 v[62:63], v[62:63], v[66:67], v[70:71]
	global_load_dwordx2 v[58:59], v[116:117], off
	global_load_dwordx4 v[84:87], v[120:121], off offset:2048
	v_lshl_add_u64 v[116:117], v[116:117], 0, s[10:11]
	v_lshl_add_u64 v[120:121], v[120:121], 0, s[100:101]
	v_cvt_pk_bf16_f32 v112, v60, v61
	v_cvt_pk_bf16_f32 v113, v62, v63
	s_waitcnt vmcnt(45)
	global_store_dwordx2 v[118:119], v[112:113], off
	v_lshl_add_u64 v[118:119], v[118:119], 0, s[10:11]
	v_mul_f32_e32 v64, 0x3fb8aa3b, v88
	v_mul_f32_e32 v65, 0x3fb8aa3b, v89
	v_mul_f32_e32 v66, 0x3fb8aa3b, v90
	v_mul_f32_e32 v67, 0x3fb8aa3b, v91
	v_exp_f32_e32 v64, v64
	v_exp_f32_e32 v65, v65
	v_exp_f32_e32 v66, v66
	v_exp_f32_e32 v67, v67
	v_lshlrev_b32_e32 v68, 16, v104
	v_and_b32_e32 v69, 0xffff0000, v104
	v_lshlrev_b32_e32 v70, 16, v105
	v_and_b32_e32 v71, 0xffff0000, v105
	v_pk_fma_f32 v[60:61], v[60:61], v[64:65], v[68:69]
	v_pk_fma_f32 v[62:63], v[62:63], v[66:67], v[70:71]
	global_load_dwordx2 v[104:105], v[116:117], off
	global_load_dwordx4 v[88:91], v[120:121], off
	v_lshl_add_u64 v[116:117], v[116:117], 0, s[10:11]
	v_cvt_pk_bf16_f32 v114, v60, v61
	v_cvt_pk_bf16_f32 v115, v62, v63
	s_waitcnt vmcnt(45)
	global_store_dwordx2 v[118:119], v[114:115], off
	v_lshl_add_u64 v[118:119], v[118:119], 0, s[10:11]
	v_mul_f32_e32 v64, 0x3fb8aa3b, v92
	v_mul_f32_e32 v65, 0x3fb8aa3b, v93
	v_mul_f32_e32 v66, 0x3fb8aa3b, v94
	v_mul_f32_e32 v67, 0x3fb8aa3b, v95
	v_exp_f32_e32 v64, v64
	v_exp_f32_e32 v65, v65
	v_exp_f32_e32 v66, v66
	v_exp_f32_e32 v67, v67
	v_lshlrev_b32_e32 v68, 16, v106
	v_and_b32_e32 v69, 0xffff0000, v106
	v_lshlrev_b32_e32 v70, 16, v107
	v_and_b32_e32 v71, 0xffff0000, v107
	v_pk_fma_f32 v[60:61], v[60:61], v[64:65], v[68:69]
	v_pk_fma_f32 v[62:63], v[62:63], v[66:67], v[70:71]
	global_load_dwordx2 v[106:107], v[116:117], off
	global_load_dwordx4 v[92:95], v[120:121], off offset:2048
	v_lshl_add_u64 v[116:117], v[116:117], 0, s[10:11]
	v_lshl_add_u64 v[120:121], v[120:121], 0, s[100:101]
	v_cvt_pk_bf16_f32 v112, v60, v61
	v_cvt_pk_bf16_f32 v113, v62, v63
	s_waitcnt vmcnt(45)
	global_store_dwordx2 v[118:119], v[112:113], off
	v_lshl_add_u64 v[118:119], v[118:119], 0, s[10:11]
	v_mul_f32_e32 v64, 0x3fb8aa3b, v96
	v_mul_f32_e32 v65, 0x3fb8aa3b, v97
	v_mul_f32_e32 v66, 0x3fb8aa3b, v98
	v_mul_f32_e32 v67, 0x3fb8aa3b, v99
	v_exp_f32_e32 v64, v64
	v_exp_f32_e32 v65, v65
	v_exp_f32_e32 v66, v66
	v_exp_f32_e32 v67, v67
	v_lshlrev_b32_e32 v68, 16, v108
	v_and_b32_e32 v69, 0xffff0000, v108
	v_lshlrev_b32_e32 v70, 16, v109
	v_and_b32_e32 v71, 0xffff0000, v109
	v_pk_fma_f32 v[60:61], v[60:61], v[64:65], v[68:69]
	v_pk_fma_f32 v[62:63], v[62:63], v[66:67], v[70:71]
	global_load_dwordx2 v[108:109], v[116:117], off
	global_load_dwordx4 v[96:99], v[120:121], off
	v_lshl_add_u64 v[116:117], v[116:117], 0, s[10:11]
	v_cvt_pk_bf16_f32 v114, v60, v61
	v_cvt_pk_bf16_f32 v115, v62, v63
	s_waitcnt vmcnt(45)
	global_store_dwordx2 v[118:119], v[114:115], off
	v_lshl_add_u64 v[118:119], v[118:119], 0, s[10:11]
	v_mul_f32_e32 v64, 0x3fb8aa3b, v100
	v_mul_f32_e32 v65, 0x3fb8aa3b, v101
	v_mul_f32_e32 v66, 0x3fb8aa3b, v102
	v_mul_f32_e32 v67, 0x3fb8aa3b, v103
	v_exp_f32_e32 v64, v64
	v_exp_f32_e32 v65, v65
	v_exp_f32_e32 v66, v66
	v_exp_f32_e32 v67, v67
	v_lshlrev_b32_e32 v68, 16, v110
	v_and_b32_e32 v69, 0xffff0000, v110
	v_lshlrev_b32_e32 v70, 16, v111
	v_and_b32_e32 v71, 0xffff0000, v111
	v_pk_fma_f32 v[60:61], v[60:61], v[64:65], v[68:69]
	v_pk_fma_f32 v[62:63], v[62:63], v[66:67], v[70:71]
	global_load_dwordx2 v[110:111], v[116:117], off
	global_load_dwordx4 v[100:103], v[120:121], off offset:2048
	v_lshl_add_u64 v[116:117], v[116:117], 0, s[10:11]
	v_lshl_add_u64 v[120:121], v[120:121], 0, s[100:101]
	v_cvt_pk_bf16_f32 v112, v60, v61
	v_cvt_pk_bf16_f32 v113, v62, v63
	s_waitcnt vmcnt(45)
	global_store_dwordx2 v[118:119], v[112:113], off
	v_lshl_add_u64 v[118:119], v[118:119], 0, s[10:11]
	v_mul_f32_e32 v64, 0x3fb8aa3b, v0
	v_mul_f32_e32 v65, 0x3fb8aa3b, v1
	v_mul_f32_e32 v66, 0x3fb8aa3b, v2
	v_mul_f32_e32 v67, 0x3fb8aa3b, v3
	v_exp_f32_e32 v64, v64
	v_exp_f32_e32 v65, v65
	v_exp_f32_e32 v66, v66
	v_exp_f32_e32 v67, v67
	v_lshlrev_b32_e32 v68, 16, v36
	v_and_b32_e32 v69, 0xffff0000, v36
	v_lshlrev_b32_e32 v70, 16, v37
	v_and_b32_e32 v71, 0xffff0000, v37
	v_pk_fma_f32 v[60:61], v[60:61], v[64:65], v[68:69]
	v_pk_fma_f32 v[62:63], v[62:63], v[66:67], v[70:71]
	v_cvt_pk_bf16_f32 v114, v60, v61
	v_cvt_pk_bf16_f32 v115, v62, v63
	s_waitcnt vmcnt(43)
	global_store_dwordx2 v[118:119], v[114:115], off
	v_lshl_add_u64 v[118:119], v[118:119], 0, s[10:11]
	v_mul_f32_e32 v64, 0x3fb8aa3b, v4
	v_mul_f32_e32 v65, 0x3fb8aa3b, v5
	v_mul_f32_e32 v66, 0x3fb8aa3b, v6
	v_mul_f32_e32 v67, 0x3fb8aa3b, v7
	v_exp_f32_e32 v64, v64
	v_exp_f32_e32 v65, v65
	v_exp_f32_e32 v66, v66
	v_exp_f32_e32 v67, v67
	v_lshlrev_b32_e32 v68, 16, v38
	v_and_b32_e32 v69, 0xffff0000, v38
	v_lshlrev_b32_e32 v70, 16, v39
	v_and_b32_e32 v71, 0xffff0000, v39
	v_pk_fma_f32 v[60:61], v[60:61], v[64:65], v[68:69]
	v_pk_fma_f32 v[62:63], v[62:63], v[66:67], v[70:71]
	v_cvt_pk_bf16_f32 v112, v60, v61
	v_cvt_pk_bf16_f32 v113, v62, v63
	s_waitcnt vmcnt(41)
	global_store_dwordx2 v[118:119], v[112:113], off
	v_lshl_add_u64 v[118:119], v[118:119], 0, s[10:11]
	v_mul_f32_e32 v64, 0x3fb8aa3b, v8
	v_mul_f32_e32 v65, 0x3fb8aa3b, v9
	v_mul_f32_e32 v66, 0x3fb8aa3b, v10
	v_mul_f32_e32 v67, 0x3fb8aa3b, v11
	v_exp_f32_e32 v64, v64
	v_exp_f32_e32 v65, v65
	v_exp_f32_e32 v66, v66
	v_exp_f32_e32 v67, v67
	v_lshlrev_b32_e32 v68, 16, v40
	v_and_b32_e32 v69, 0xffff0000, v40
	v_lshlrev_b32_e32 v70, 16, v41
	v_and_b32_e32 v71, 0xffff0000, v41
	v_pk_fma_f32 v[60:61], v[60:61], v[64:65], v[68:69]
	v_pk_fma_f32 v[62:63], v[62:63], v[66:67], v[70:71]
	v_cvt_pk_bf16_f32 v114, v60, v61
	v_cvt_pk_bf16_f32 v115, v62, v63
	s_waitcnt vmcnt(39)
	global_store_dwordx2 v[118:119], v[114:115], off
	v_lshl_add_u64 v[118:119], v[118:119], 0, s[10:11]
	v_mul_f32_e32 v64, 0x3fb8aa3b, v12
	v_mul_f32_e32 v65, 0x3fb8aa3b, v13
	v_mul_f32_e32 v66, 0x3fb8aa3b, v14
	v_mul_f32_e32 v67, 0x3fb8aa3b, v15
	v_exp_f32_e32 v64, v64
	v_exp_f32_e32 v65, v65
	v_exp_f32_e32 v66, v66
	v_exp_f32_e32 v67, v67
	v_lshlrev_b32_e32 v68, 16, v42
	v_and_b32_e32 v69, 0xffff0000, v42
	v_lshlrev_b32_e32 v70, 16, v43
	v_and_b32_e32 v71, 0xffff0000, v43
	v_pk_fma_f32 v[60:61], v[60:61], v[64:65], v[68:69]
	v_pk_fma_f32 v[62:63], v[62:63], v[66:67], v[70:71]
	v_cvt_pk_bf16_f32 v112, v60, v61
	v_cvt_pk_bf16_f32 v113, v62, v63
	s_waitcnt vmcnt(37)
	global_store_dwordx2 v[118:119], v[112:113], off
	v_lshl_add_u64 v[118:119], v[118:119], 0, s[10:11]
	v_mul_f32_e32 v64, 0x3fb8aa3b, v16
	v_mul_f32_e32 v65, 0x3fb8aa3b, v17
	v_mul_f32_e32 v66, 0x3fb8aa3b, v18
	v_mul_f32_e32 v67, 0x3fb8aa3b, v19
	v_exp_f32_e32 v64, v64
	v_exp_f32_e32 v65, v65
	v_exp_f32_e32 v66, v66
	v_exp_f32_e32 v67, v67
	v_lshlrev_b32_e32 v68, 16, v44
	v_and_b32_e32 v69, 0xffff0000, v44
	v_lshlrev_b32_e32 v70, 16, v45
	v_and_b32_e32 v71, 0xffff0000, v45
	v_pk_fma_f32 v[60:61], v[60:61], v[64:65], v[68:69]
	v_pk_fma_f32 v[62:63], v[62:63], v[66:67], v[70:71]
	v_cvt_pk_bf16_f32 v114, v60, v61
	v_cvt_pk_bf16_f32 v115, v62, v63
	s_waitcnt vmcnt(35)
	global_store_dwordx2 v[118:119], v[114:115], off
	v_lshl_add_u64 v[118:119], v[118:119], 0, s[10:11]
	v_mul_f32_e32 v64, 0x3fb8aa3b, v20
	v_mul_f32_e32 v65, 0x3fb8aa3b, v21
	v_mul_f32_e32 v66, 0x3fb8aa3b, v22
	v_mul_f32_e32 v67, 0x3fb8aa3b, v23
	v_exp_f32_e32 v64, v64
	v_exp_f32_e32 v65, v65
	v_exp_f32_e32 v66, v66
	v_exp_f32_e32 v67, v67
	v_lshlrev_b32_e32 v68, 16, v46
	v_and_b32_e32 v69, 0xffff0000, v46
	v_lshlrev_b32_e32 v70, 16, v47
	v_and_b32_e32 v71, 0xffff0000, v47
	v_pk_fma_f32 v[60:61], v[60:61], v[64:65], v[68:69]
	v_pk_fma_f32 v[62:63], v[62:63], v[66:67], v[70:71]
	v_cvt_pk_bf16_f32 v112, v60, v61
	v_cvt_pk_bf16_f32 v113, v62, v63
	s_waitcnt vmcnt(33)
	global_store_dwordx2 v[118:119], v[112:113], off
	v_lshl_add_u64 v[118:119], v[118:119], 0, s[10:11]
	v_mul_f32_e32 v64, 0x3fb8aa3b, v24
	v_mul_f32_e32 v65, 0x3fb8aa3b, v25
	v_mul_f32_e32 v66, 0x3fb8aa3b, v26
	v_mul_f32_e32 v67, 0x3fb8aa3b, v27
	v_exp_f32_e32 v64, v64
	v_exp_f32_e32 v65, v65
	v_exp_f32_e32 v66, v66
	v_exp_f32_e32 v67, v67
	v_lshlrev_b32_e32 v68, 16, v48
	v_and_b32_e32 v69, 0xffff0000, v48
	v_lshlrev_b32_e32 v70, 16, v49
	v_and_b32_e32 v71, 0xffff0000, v49
	v_pk_fma_f32 v[60:61], v[60:61], v[64:65], v[68:69]
	v_pk_fma_f32 v[62:63], v[62:63], v[66:67], v[70:71]
	v_cvt_pk_bf16_f32 v114, v60, v61
	v_cvt_pk_bf16_f32 v115, v62, v63
	s_waitcnt vmcnt(31)
	global_store_dwordx2 v[118:119], v[114:115], off
	v_lshl_add_u64 v[118:119], v[118:119], 0, s[10:11]
	v_mul_f32_e32 v64, 0x3fb8aa3b, v28
	v_mul_f32_e32 v65, 0x3fb8aa3b, v29
	v_mul_f32_e32 v66, 0x3fb8aa3b, v30
	v_mul_f32_e32 v67, 0x3fb8aa3b, v31
	v_exp_f32_e32 v64, v64
	v_exp_f32_e32 v65, v65
	v_exp_f32_e32 v66, v66
	v_exp_f32_e32 v67, v67
	v_lshlrev_b32_e32 v68, 16, v50
	v_and_b32_e32 v69, 0xffff0000, v50
	v_lshlrev_b32_e32 v70, 16, v51
	v_and_b32_e32 v71, 0xffff0000, v51
	v_pk_fma_f32 v[60:61], v[60:61], v[64:65], v[68:69]
	v_pk_fma_f32 v[62:63], v[62:63], v[66:67], v[70:71]
	v_cvt_pk_bf16_f32 v112, v60, v61
	v_cvt_pk_bf16_f32 v113, v62, v63
	s_waitcnt vmcnt(29)
	global_store_dwordx2 v[118:119], v[112:113], off
	v_lshl_add_u64 v[118:119], v[118:119], 0, s[10:11]
	v_mul_f32_e32 v64, 0x3fb8aa3b, v72
	v_mul_f32_e32 v65, 0x3fb8aa3b, v73
	v_mul_f32_e32 v66, 0x3fb8aa3b, v74
	v_mul_f32_e32 v67, 0x3fb8aa3b, v75
	v_exp_f32_e32 v64, v64
	v_exp_f32_e32 v65, v65
	v_exp_f32_e32 v66, v66
	v_exp_f32_e32 v67, v67
	v_lshlrev_b32_e32 v68, 16, v52
	v_and_b32_e32 v69, 0xffff0000, v52
	v_lshlrev_b32_e32 v70, 16, v53
	v_and_b32_e32 v71, 0xffff0000, v53
	v_pk_fma_f32 v[60:61], v[60:61], v[64:65], v[68:69]
	v_pk_fma_f32 v[62:63], v[62:63], v[66:67], v[70:71]
	v_cvt_pk_bf16_f32 v114, v60, v61
	v_cvt_pk_bf16_f32 v115, v62, v63
	s_waitcnt vmcnt(27)
	global_store_dwordx2 v[118:119], v[114:115], off
	v_lshl_add_u64 v[118:119], v[118:119], 0, s[10:11]
	v_mul_f32_e32 v64, 0x3fb8aa3b, v76
	v_mul_f32_e32 v65, 0x3fb8aa3b, v77
	v_mul_f32_e32 v66, 0x3fb8aa3b, v78
	v_mul_f32_e32 v67, 0x3fb8aa3b, v79
	v_exp_f32_e32 v64, v64
	v_exp_f32_e32 v65, v65
	v_exp_f32_e32 v66, v66
	v_exp_f32_e32 v67, v67
	v_lshlrev_b32_e32 v68, 16, v54
	v_and_b32_e32 v69, 0xffff0000, v54
	v_lshlrev_b32_e32 v70, 16, v55
	v_and_b32_e32 v71, 0xffff0000, v55
	v_pk_fma_f32 v[60:61], v[60:61], v[64:65], v[68:69]
	v_pk_fma_f32 v[62:63], v[62:63], v[66:67], v[70:71]
	v_cvt_pk_bf16_f32 v112, v60, v61
	v_cvt_pk_bf16_f32 v113, v62, v63
	s_waitcnt vmcnt(25)
	global_store_dwordx2 v[118:119], v[112:113], off
	v_lshl_add_u64 v[118:119], v[118:119], 0, s[10:11]
	v_mul_f32_e32 v64, 0x3fb8aa3b, v80
	v_mul_f32_e32 v65, 0x3fb8aa3b, v81
	v_mul_f32_e32 v66, 0x3fb8aa3b, v82
	v_mul_f32_e32 v67, 0x3fb8aa3b, v83
	v_exp_f32_e32 v64, v64
	v_exp_f32_e32 v65, v65
	v_exp_f32_e32 v66, v66
	v_exp_f32_e32 v67, v67
	v_lshlrev_b32_e32 v68, 16, v56
	v_and_b32_e32 v69, 0xffff0000, v56
	v_lshlrev_b32_e32 v70, 16, v57
	v_and_b32_e32 v71, 0xffff0000, v57
	v_pk_fma_f32 v[60:61], v[60:61], v[64:65], v[68:69]
	v_pk_fma_f32 v[62:63], v[62:63], v[66:67], v[70:71]
	v_cvt_pk_bf16_f32 v114, v60, v61
	v_cvt_pk_bf16_f32 v115, v62, v63
	s_waitcnt vmcnt(23)
	global_store_dwordx2 v[118:119], v[114:115], off
	v_lshl_add_u64 v[118:119], v[118:119], 0, s[10:11]
	v_mul_f32_e32 v64, 0x3fb8aa3b, v84
	v_mul_f32_e32 v65, 0x3fb8aa3b, v85
	v_mul_f32_e32 v66, 0x3fb8aa3b, v86
	v_mul_f32_e32 v67, 0x3fb8aa3b, v87
	v_exp_f32_e32 v64, v64
	v_exp_f32_e32 v65, v65
	v_exp_f32_e32 v66, v66
	v_exp_f32_e32 v67, v67
	v_lshlrev_b32_e32 v68, 16, v58
	v_and_b32_e32 v69, 0xffff0000, v58
	v_lshlrev_b32_e32 v70, 16, v59
	v_and_b32_e32 v71, 0xffff0000, v59
	v_pk_fma_f32 v[60:61], v[60:61], v[64:65], v[68:69]
	v_pk_fma_f32 v[62:63], v[62:63], v[66:67], v[70:71]
	v_cvt_pk_bf16_f32 v112, v60, v61
	v_cvt_pk_bf16_f32 v113, v62, v63
	s_waitcnt vmcnt(21)
	global_store_dwordx2 v[118:119], v[112:113], off
	v_lshl_add_u64 v[118:119], v[118:119], 0, s[10:11]
	v_mul_f32_e32 v64, 0x3fb8aa3b, v88
	v_mul_f32_e32 v65, 0x3fb8aa3b, v89
	v_mul_f32_e32 v66, 0x3fb8aa3b, v90
	v_mul_f32_e32 v67, 0x3fb8aa3b, v91
	v_exp_f32_e32 v64, v64
	v_exp_f32_e32 v65, v65
	v_exp_f32_e32 v66, v66
	v_exp_f32_e32 v67, v67
	v_lshlrev_b32_e32 v68, 16, v104
	v_and_b32_e32 v69, 0xffff0000, v104
	v_lshlrev_b32_e32 v70, 16, v105
	v_and_b32_e32 v71, 0xffff0000, v105
	v_pk_fma_f32 v[60:61], v[60:61], v[64:65], v[68:69]
	v_pk_fma_f32 v[62:63], v[62:63], v[66:67], v[70:71]
	v_cvt_pk_bf16_f32 v114, v60, v61
	v_cvt_pk_bf16_f32 v115, v62, v63
	s_waitcnt vmcnt(19)
	global_store_dwordx2 v[118:119], v[114:115], off
	v_lshl_add_u64 v[118:119], v[118:119], 0, s[10:11]
	v_mul_f32_e32 v64, 0x3fb8aa3b, v92
	v_mul_f32_e32 v65, 0x3fb8aa3b, v93
	v_mul_f32_e32 v66, 0x3fb8aa3b, v94
	v_mul_f32_e32 v67, 0x3fb8aa3b, v95
	v_exp_f32_e32 v64, v64
	v_exp_f32_e32 v65, v65
	v_exp_f32_e32 v66, v66
	v_exp_f32_e32 v67, v67
	v_lshlrev_b32_e32 v68, 16, v106
	v_and_b32_e32 v69, 0xffff0000, v106
	v_lshlrev_b32_e32 v70, 16, v107
	v_and_b32_e32 v71, 0xffff0000, v107
	v_pk_fma_f32 v[60:61], v[60:61], v[64:65], v[68:69]
	v_pk_fma_f32 v[62:63], v[62:63], v[66:67], v[70:71]
	v_cvt_pk_bf16_f32 v112, v60, v61
	v_cvt_pk_bf16_f32 v113, v62, v63
	s_waitcnt vmcnt(17)
	global_store_dwordx2 v[118:119], v[112:113], off
	v_lshl_add_u64 v[118:119], v[118:119], 0, s[10:11]
	v_mul_f32_e32 v64, 0x3fb8aa3b, v96
	v_mul_f32_e32 v65, 0x3fb8aa3b, v97
	v_mul_f32_e32 v66, 0x3fb8aa3b, v98
	v_mul_f32_e32 v67, 0x3fb8aa3b, v99
	v_exp_f32_e32 v64, v64
	v_exp_f32_e32 v65, v65
	v_exp_f32_e32 v66, v66
	v_exp_f32_e32 v67, v67
	v_lshlrev_b32_e32 v68, 16, v108
	v_and_b32_e32 v69, 0xffff0000, v108
	v_lshlrev_b32_e32 v70, 16, v109
	v_and_b32_e32 v71, 0xffff0000, v109
	v_pk_fma_f32 v[60:61], v[60:61], v[64:65], v[68:69]
	v_pk_fma_f32 v[62:63], v[62:63], v[66:67], v[70:71]
	v_cvt_pk_bf16_f32 v114, v60, v61
	v_cvt_pk_bf16_f32 v115, v62, v63
	s_waitcnt vmcnt(15)
	global_store_dwordx2 v[118:119], v[114:115], off
	v_lshl_add_u64 v[118:119], v[118:119], 0, s[10:11]
	v_mul_f32_e32 v64, 0x3fb8aa3b, v100
	v_mul_f32_e32 v65, 0x3fb8aa3b, v101
	v_mul_f32_e32 v66, 0x3fb8aa3b, v102
	v_mul_f32_e32 v67, 0x3fb8aa3b, v103
	v_exp_f32_e32 v64, v64
	v_exp_f32_e32 v65, v65
	v_exp_f32_e32 v66, v66
	v_exp_f32_e32 v67, v67
	v_lshlrev_b32_e32 v68, 16, v110
	v_and_b32_e32 v69, 0xffff0000, v110
	v_lshlrev_b32_e32 v70, 16, v111
	v_and_b32_e32 v71, 0xffff0000, v111
	v_pk_fma_f32 v[60:61], v[60:61], v[64:65], v[68:69]
	v_pk_fma_f32 v[62:63], v[62:63], v[66:67], v[70:71]
